# baseline (speedup 1.0000x reference)
; #define STA(b, h, half, kt) STAGE(((b) * 2 + (h)) * G_HT * 2, pA, ((size_t)(half) * G_HALF * lda + (size_t)(kt) * G_BK) * 2, lda)
; #define STB(b, h, half, kt) STAGE((4 + (b) * 2 + (h)) * G_HT * 2, pB, ((size_t)(half) * G_HALF * K + (size_t)(kt) * G_BK) * 2, K)
; #define LDA(dst, b, h) for (int m = 0; m < 4; ++m) for (int k = 0; k < 2; ++k) \
;     dst[m][k] = *reinterpret_cast<const bf16x8*>(aRd + (((b) * 2 + (h)) * G_HT * 2 + m * 2048 + k * 1024))
; #define LDB(dst, b, h) for (int n = 0; n < 2; ++n) for (int k = 0; k < 2; ++k) \
;     dst[n][k] = *reinterpret_cast<const bf16x8*>(bRd + (((b) * 2 + (h)) * G_HT * 2 + n * 2048 + k * 1024))
; #define MMA(ai, bj, At, Bx) do { __builtin_amdgcn_s_setprio(1); \
;     for (int m = 0; m < 4; ++m) for (int n = 0; n < 2; ++n) for (int k = 0; k < 2; ++k) \
;       acc[ai][bj][m][n] = __builtin_amdgcn_mfma_f32_16x16x32_bf16(Bx[n][k], At[m][k], acc[ai][bj][m][n], 0, 0, 0);     \
;     __builtin_amdgcn_s_setprio(0); } while (0)
; #define WAIT_V(n) asm volatile("s_waitcnt vmcnt(" #n ")" ::: "memory")
; #define WAIT_L(n) asm volatile("s_waitcnt lgkmcnt(" #n ")" ::: "memory")
; #define BAR __builtin_amdgcn_s_barrier()
; #define SCHED __builtin_amdgcn_sched_barrier(0)
; template <int EPI>
; __device__ __forceinline__ void gemm_tile(const bf16* __restrict__ A, int lda, const bf16* __restrict__ Bt, int K,
;                                           int brow, int bcol, const EpiArgs& ea, char* shmc, bool has_next, int nbrow, int nbcol, bool first_tile) {
;     ...
;   for (int t = 0; t < nt - 2; t += 2) {
;     LDB(B0, 0, 0); SCHED; LDA(At, 0, 0); STA(1, 1, 1, t + 1);
;     WAIT_L(8); BAR; WAIT_L(0); MMA(0, 0, At, B0); BAR; SCHED;
;     LDB(B1, 0, 1); STB(0, 0, 0, t + 2);
;     BAR; WAIT_L(0); MMA(0, 1, At, B1); BAR;
;     LDA(At, 0, 1); STA(0, 0, 0, t + 2);
;     BAR; WAIT_L(0); MMA(1, 0, At, B0); BAR; SCHED;
;     STB(0, 1, 1, t + 2);
;     WAIT_V(6); BAR; MMA(1, 1, At, B1); BAR;
.LBB0_96:
	ds_read_b128 v[162:165], v141
	ds_read_b128 v[166:169], v142
	ds_read_b128 v[170:173], v143
	ds_read_b128 v[174:177], v144
	s_add_u32 s82, s34, 0xffffff00
	s_addc_u32 s83, s35, -1
	s_mov_b32 m0, s77
	ds_read_b128 v[178:181], v160
	ds_read_b128 v[182:185], v160 offset:1024
	ds_read_b128 v[186:189], v160 offset:2048
	ds_read_b128 v[190:193], v160 offset:3072
	ds_read_b128 v[194:197], v160 offset:4096
	ds_read_b128 v[198:201], v160 offset:5120
	ds_read_b128 v[202:205], v160 offset:6144
	ds_read_b128 v[206:209], v160 offset:7168
	v_lshl_add_u64 v[210:211], v[134:135], 0, s[82:83]
	global_load_lds_dwordx4 v[210:211], off
	s_mov_b32 m0, s68
	v_lshl_add_u64 v[210:211], v[210:211], 0, s[0:1]
	global_load_lds_dwordx4 v[210:211], off
	s_waitcnt lgkmcnt(8)
	s_barrier
	s_waitcnt lgkmcnt(0)
	v_mfma_f32_16x16x32_bf16 v[124:127], v[162:165], v[178:181], v[124:127]
	v_mfma_f32_16x16x32_bf16 v[120:123], v[170:173], v[178:181], v[120:123]
	v_mfma_f32_16x16x32_bf16 v[116:119], v[162:165], v[186:189], v[116:119]
	v_mfma_f32_16x16x32_bf16 v[112:115], v[170:173], v[186:189], v[112:115]
	v_mfma_f32_16x16x32_bf16 v[108:111], v[162:165], v[194:197], v[108:111]
	v_mfma_f32_16x16x32_bf16 v[104:107], v[170:173], v[194:197], v[104:107]
	v_mfma_f32_16x16x32_bf16 v[100:103], v[162:165], v[202:205], v[100:103]
	v_mfma_f32_16x16x32_bf16 v[96:99], v[170:173], v[202:205], v[96:99]
	v_mfma_f32_16x16x32_bf16 v[124:127], v[166:169], v[182:185], v[124:127]
	v_mfma_f32_16x16x32_bf16 v[120:123], v[174:177], v[182:185], v[120:123]
	v_mfma_f32_16x16x32_bf16 v[116:119], v[166:169], v[190:193], v[116:119]
	v_mfma_f32_16x16x32_bf16 v[112:115], v[174:177], v[190:193], v[112:115]
	v_mfma_f32_16x16x32_bf16 v[108:111], v[166:169], v[198:201], v[108:111]
	v_mfma_f32_16x16x32_bf16 v[104:107], v[174:177], v[198:201], v[104:107]
	v_mfma_f32_16x16x32_bf16 v[100:103], v[166:169], v[206:209], v[100:103]
	v_mfma_f32_16x16x32_bf16 v[96:99], v[174:177], v[206:209], v[96:99]
	s_barrier
	s_add_u32 s82, s34, 0xffefff80
	s_addc_u32 s83, s35, -1
	s_mov_b64 s[84:85], s[82:83]
	s_mov_b32 m0, s71
	ds_read_b128 v[210:213], v145
	ds_read_b128 v[214:217], v146
	ds_read_b128 v[218:221], v147
	ds_read_b128 v[222:225], v148
	v_lshl_add_u64 v[226:227], v[136:137], 0, s[84:85]
	global_load_lds_dwordx4 v[226:227], off
	s_mov_b32 m0, s72
	v_lshl_add_u64 v[226:227], v[226:227], 0, s[0:1]
	global_load_lds_dwordx4 v[226:227], off
	s_barrier
	s_waitcnt lgkmcnt(0)
	v_mfma_f32_16x16x32_bf16 v[92:95], v[210:213], v[178:181], v[92:95]
	v_mfma_f32_16x16x32_bf16 v[88:91], v[218:221], v[178:181], v[88:91]
	v_mfma_f32_16x16x32_bf16 v[84:87], v[210:213], v[186:189], v[84:87]
	v_mfma_f32_16x16x32_bf16 v[80:83], v[218:221], v[186:189], v[80:83]
	v_mfma_f32_16x16x32_bf16 v[76:79], v[210:213], v[194:197], v[76:79]
	v_mfma_f32_16x16x32_bf16 v[72:75], v[218:221], v[194:197], v[72:75]
	v_mfma_f32_16x16x32_bf16 v[68:71], v[210:213], v[202:205], v[68:71]
	v_mfma_f32_16x16x32_bf16 v[64:67], v[218:221], v[202:205], v[64:67]
	v_mfma_f32_16x16x32_bf16 v[92:95], v[214:217], v[182:185], v[92:95]
	v_mfma_f32_16x16x32_bf16 v[88:91], v[222:225], v[182:185], v[88:91]
	v_mfma_f32_16x16x32_bf16 v[84:87], v[214:217], v[190:193], v[84:87]
	v_mfma_f32_16x16x32_bf16 v[80:83], v[222:225], v[190:193], v[80:83]
	v_mfma_f32_16x16x32_bf16 v[76:79], v[214:217], v[198:201], v[76:79]
	v_mfma_f32_16x16x32_bf16 v[72:75], v[222:225], v[198:201], v[72:75]
	v_mfma_f32_16x16x32_bf16 v[68:71], v[214:217], v[206:209], v[68:71]
	v_mfma_f32_16x16x32_bf16 v[64:67], v[222:225], v[206:209], v[64:67]
	s_mov_b32 m0, s7
	s_barrier
	ds_read_b128 v[178:181], v160 offset:16384
	ds_read_b128 v[182:185], v160 offset:17408
	ds_read_b128 v[186:189], v160 offset:18432
	ds_read_b128 v[190:193], v160 offset:19456
	ds_read_b128 v[194:197], v160 offset:20480
	ds_read_b128 v[198:201], v160 offset:21504
	ds_read_b128 v[202:205], v160 offset:22528
	ds_read_b128 v[206:209], v160 offset:23552
	v_lshl_add_u64 v[226:227], v[134:135], 0, s[82:83]
	global_load_lds_dwordx4 v[226:227], off
	s_mov_b32 m0, s79
	v_lshl_add_u64 v[226:227], v[226:227], 0, s[0:1]
	global_load_lds_dwordx4 v[226:227], off
	s_barrier
	s_waitcnt lgkmcnt(0)
	v_mfma_f32_16x16x32_bf16 v[60:63], v[162:165], v[178:181], v[60:63]
	v_mfma_f32_16x16x32_bf16 v[56:59], v[170:173], v[178:181], v[56:59]
	v_mfma_f32_16x16x32_bf16 v[52:55], v[162:165], v[186:189], v[52:55]
	v_mfma_f32_16x16x32_bf16 v[48:51], v[170:173], v[186:189], v[48:51]
	v_mfma_f32_16x16x32_bf16 v[44:47], v[162:165], v[194:197], v[44:47]
	v_mfma_f32_16x16x32_bf16 v[40:43], v[170:173], v[194:197], v[40:43]
	v_mfma_f32_16x16x32_bf16 v[36:39], v[162:165], v[202:205], v[36:39]
	v_mfma_f32_16x16x32_bf16 v[32:35], v[170:173], v[202:205], v[32:35]
	v_mfma_f32_16x16x32_bf16 v[60:63], v[166:169], v[182:185], v[60:63]
	v_mfma_f32_16x16x32_bf16 v[56:59], v[174:177], v[182:185], v[56:59]
	v_mfma_f32_16x16x32_bf16 v[52:55], v[166:169], v[190:193], v[52:55]
	v_mfma_f32_16x16x32_bf16 v[48:51], v[174:177], v[190:193], v[48:51]
	v_mfma_f32_16x16x32_bf16 v[44:47], v[166:169], v[198:201], v[44:47]
	v_mfma_f32_16x16x32_bf16 v[40:43], v[174:177], v[198:201], v[40:43]
	v_mfma_f32_16x16x32_bf16 v[36:39], v[166:169], v[206:209], v[36:39]
	v_mfma_f32_16x16x32_bf16 v[32:35], v[174:177], v[206:209], v[32:35]
	s_barrier
	s_add_u32 s82, s34, 0xffffff80
	s_addc_u32 s83, s35, -1
	s_mov_b64 s[84:85], s[82:83]
	s_mov_b32 m0, s73
	v_lshl_add_u64 v[162:163], v[136:137], 0, s[84:85]
	global_load_lds_dwordx4 v[162:163], off
	s_mov_b32 m0, s74
	v_lshl_add_u64 v[162:163], v[162:163], 0, s[0:1]
	global_load_lds_dwordx4 v[162:163], off
	s_waitcnt vmcnt(6)
	s_barrier
; #define STA(b, h, half, kt) STAGE(((b) * 2 + (h)) * G_HT * 2, pA, ((size_t)(half) * G_HALF * lda + (size_t)(kt) * G_BK) * 2, lda)
; #define STB(b, h, half, kt) STAGE((4 + (b) * 2 + (h)) * G_HT * 2, pB, ((size_t)(half) * G_HALF * K + (size_t)(kt) * G_BK) * 2, K)
; #define LDA(dst, b, h) for (int m = 0; m < 4; ++m) for (int k = 0; k < 2; ++k) \
;     dst[m][k] = *reinterpret_cast<const bf16x8*>(aRd + (((b) * 2 + (h)) * G_HT * 2 + m * 2048 + k * 1024))
; #define LDB(dst, b, h) for (int n = 0; n < 2; ++n) for (int k = 0; k < 2; ++k) \
;     dst[n][k] = *reinterpret_cast<const bf16x8*>(bRd + (((b) * 2 + (h)) * G_HT * 2 + n * 2048 + k * 1024))
; #define MMA(ai, bj, At, Bx) do { __builtin_amdgcn_s_setprio(1); \
;     for (int m = 0; m < 4; ++m) for (int n = 0; n < 2; ++n) for (int k = 0; k < 2; ++k) \
;       acc[ai][bj][m][n] = __builtin_amdgcn_mfma_f32_16x16x32_bf16(Bx[n][k], At[m][k], acc[ai][bj][m][n], 0, 0, 0);     \
;     __builtin_amdgcn_s_setprio(0); } while (0)
; #define WAIT_V(n) asm volatile("s_waitcnt vmcnt(" #n ")" ::: "memory")
; #define WAIT_L(n) asm volatile("s_waitcnt lgkmcnt(" #n ")" ::: "memory")
; #define BAR __builtin_amdgcn_s_barrier()
; #define SCHED __builtin_amdgcn_sched_barrier(0)
; template <int EPI>
; __device__ __forceinline__ void gemm_tile(const bf16* __restrict__ A, int lda, const bf16* __restrict__ Bt, int K,
;                                           int brow, int bcol, const EpiArgs& ea, char* shmc, bool has_next, int nbrow, int nbcol, bool first_tile) {
;     ...
;     WAIT_V(6); BAR; MMA(1, 1, At, B1); BAR;
;     LDB(B0, 1, 0); SCHED; LDA(At, 1, 0); STA(0, 1, 1, t + 2);
;     WAIT_L(8); BAR; WAIT_L(0); MMA(0, 0, At, B0); BAR; SCHED;
;     LDB(B1, 1, 1); STB(1, 0, 0, t + 3);
;     BAR; WAIT_L(0); MMA(0, 1, At, B1); BAR;
;     LDA(At, 1, 1); STA(1, 0, 0, t + 3);
	v_mfma_f32_16x16x32_bf16 v[28:31], v[210:213], v[178:181], v[28:31]
	v_mfma_f32_16x16x32_bf16 v[24:27], v[218:221], v[178:181], v[24:27]
	v_mfma_f32_16x16x32_bf16 v[20:23], v[210:213], v[186:189], v[20:23]
	v_mfma_f32_16x16x32_bf16 v[16:19], v[218:221], v[186:189], v[16:19]
	v_mfma_f32_16x16x32_bf16 v[12:15], v[210:213], v[194:197], v[12:15]
	v_mfma_f32_16x16x32_bf16 v[8:11], v[218:221], v[194:197], v[8:11]
	v_mfma_f32_16x16x32_bf16 v[4:7], v[210:213], v[202:205], v[4:7]
	v_mfma_f32_16x16x32_bf16 v[0:3], v[218:221], v[202:205], v[0:3]
	v_mfma_f32_16x16x32_bf16 v[28:31], v[214:217], v[182:185], v[28:31]
	v_mfma_f32_16x16x32_bf16 v[24:27], v[222:225], v[182:185], v[24:27]
	v_mfma_f32_16x16x32_bf16 v[20:23], v[214:217], v[190:193], v[20:23]
	v_mfma_f32_16x16x32_bf16 v[16:19], v[222:225], v[190:193], v[16:19]
	v_mfma_f32_16x16x32_bf16 v[12:15], v[214:217], v[198:201], v[12:15]
	v_mfma_f32_16x16x32_bf16 v[8:11], v[222:225], v[198:201], v[8:11]
	v_mfma_f32_16x16x32_bf16 v[4:7], v[214:217], v[206:209], v[4:7]
	v_mfma_f32_16x16x32_bf16 v[0:3], v[222:225], v[206:209], v[0:3]
	s_barrier
	ds_read_b128 v[162:165], v149
	ds_read_b128 v[166:169], v150
	ds_read_b128 v[170:173], v151
	ds_read_b128 v[174:177], v152
	s_mov_b32 m0, s80
	ds_read_b128 v[178:181], v160 offset:32768
	ds_read_b128 v[182:185], v160 offset:33792
	ds_read_b128 v[186:189], v160 offset:34816
	ds_read_b128 v[190:193], v160 offset:35840
	ds_read_b128 v[194:197], v160 offset:36864
	ds_read_b128 v[198:201], v160 offset:37888
	ds_read_b128 v[202:205], v160 offset:38912
	ds_read_b128 v[206:209], v160 offset:39936
	v_lshl_add_u64 v[210:211], v[134:135], 0, s[82:83]
	global_load_lds_dwordx4 v[210:211], off
	s_mov_b32 m0, s81
	v_lshl_add_u64 v[210:211], v[210:211], 0, s[0:1]
	global_load_lds_dwordx4 v[210:211], off
	s_waitcnt lgkmcnt(8)
	s_barrier
	s_waitcnt lgkmcnt(0)
	v_mfma_f32_16x16x32_bf16 v[124:127], v[162:165], v[178:181], v[124:127]
	v_mfma_f32_16x16x32_bf16 v[120:123], v[170:173], v[178:181], v[120:123]
	v_mfma_f32_16x16x32_bf16 v[116:119], v[162:165], v[186:189], v[116:119]
	v_mfma_f32_16x16x32_bf16 v[112:115], v[170:173], v[186:189], v[112:115]
	v_mfma_f32_16x16x32_bf16 v[108:111], v[162:165], v[194:197], v[108:111]
	v_mfma_f32_16x16x32_bf16 v[104:107], v[170:173], v[194:197], v[104:107]
	v_mfma_f32_16x16x32_bf16 v[100:103], v[162:165], v[202:205], v[100:103]
	v_mfma_f32_16x16x32_bf16 v[96:99], v[170:173], v[202:205], v[96:99]
	v_mfma_f32_16x16x32_bf16 v[124:127], v[166:169], v[182:185], v[124:127]
	v_mfma_f32_16x16x32_bf16 v[120:123], v[174:177], v[182:185], v[120:123]
	v_mfma_f32_16x16x32_bf16 v[116:119], v[166:169], v[190:193], v[116:119]
	v_mfma_f32_16x16x32_bf16 v[112:115], v[174:177], v[190:193], v[112:115]
	v_mfma_f32_16x16x32_bf16 v[108:111], v[166:169], v[198:201], v[108:111]
	v_mfma_f32_16x16x32_bf16 v[104:107], v[174:177], v[198:201], v[104:107]
	v_mfma_f32_16x16x32_bf16 v[100:103], v[166:169], v[206:209], v[100:103]
	v_mfma_f32_16x16x32_bf16 v[96:99], v[174:177], v[206:209], v[96:99]
	s_barrier
	s_add_u32 s82, s34, 0xfff00000
	s_addc_u32 s83, s35, -1
	s_mov_b64 s[84:85], s[82:83]
	s_mov_b32 m0, s11
	ds_read_b128 v[210:213], v153
	ds_read_b128 v[214:217], v154
	ds_read_b128 v[218:221], v155
	ds_read_b128 v[222:225], v156
	v_lshl_add_u64 v[226:227], v[136:137], 0, s[84:85]
	global_load_lds_dwordx4 v[226:227], off
	s_mov_b32 m0, s63
	v_lshl_add_u64 v[226:227], v[226:227], 0, s[0:1]
	global_load_lds_dwordx4 v[226:227], off
	s_barrier
	s_waitcnt lgkmcnt(0)
	v_mfma_f32_16x16x32_bf16 v[92:95], v[210:213], v[178:181], v[92:95]
	v_mfma_f32_16x16x32_bf16 v[88:91], v[218:221], v[178:181], v[88:91]
	v_mfma_f32_16x16x32_bf16 v[84:87], v[210:213], v[186:189], v[84:87]
	v_mfma_f32_16x16x32_bf16 v[80:83], v[218:221], v[186:189], v[80:83]
	v_mfma_f32_16x16x32_bf16 v[76:79], v[210:213], v[194:197], v[76:79]
	v_mfma_f32_16x16x32_bf16 v[72:75], v[218:221], v[194:197], v[72:75]
	v_mfma_f32_16x16x32_bf16 v[68:71], v[210:213], v[202:205], v[68:71]
	v_mfma_f32_16x16x32_bf16 v[64:67], v[218:221], v[202:205], v[64:67]
	v_mfma_f32_16x16x32_bf16 v[92:95], v[214:217], v[182:185], v[92:95]
	v_mfma_f32_16x16x32_bf16 v[88:91], v[222:225], v[182:185], v[88:91]
	v_mfma_f32_16x16x32_bf16 v[84:87], v[214:217], v[190:193], v[84:87]
	v_mfma_f32_16x16x32_bf16 v[80:83], v[222:225], v[190:193], v[80:83]
	v_mfma_f32_16x16x32_bf16 v[76:79], v[214:217], v[198:201], v[76:79]
	v_mfma_f32_16x16x32_bf16 v[72:75], v[222:225], v[198:201], v[72:75]
	v_mfma_f32_16x16x32_bf16 v[68:71], v[214:217], v[206:209], v[68:71]
	v_mfma_f32_16x16x32_bf16 v[64:67], v[222:225], v[206:209], v[64:67]
	s_mov_b32 m0, s66
	s_barrier
	ds_read_b128 v[178:181], v160 offset:49152
	ds_read_b128 v[182:185], v160 offset:50176
	ds_read_b128 v[186:189], v160 offset:51200
	ds_read_b128 v[190:193], v160 offset:52224
	ds_read_b128 v[194:197], v160 offset:53248
	ds_read_b128 v[198:201], v160 offset:54272
	ds_read_b128 v[202:205], v160 offset:55296
	ds_read_b128 v[206:209], v160 offset:56320
	v_lshl_add_u64 v[226:227], v[134:135], 0, s[82:83]
	global_load_lds_dwordx4 v[226:227], off
	s_mov_b32 m0, s67
	v_lshl_add_u64 v[226:227], v[226:227], 0, s[0:1]
	global_load_lds_dwordx4 v[226:227], off
	s_barrier
; #define STA(b, h, half, kt) STAGE(((b) * 2 + (h)) * G_HT * 2, pA, ((size_t)(half) * G_HALF * lda + (size_t)(kt) * G_BK) * 2, lda)
; #define STB(b, h, half, kt) STAGE((4 + (b) * 2 + (h)) * G_HT * 2, pB, ((size_t)(half) * G_HALF * K + (size_t)(kt) * G_BK) * 2, K)
; #define LDA(dst, b, h) for (int m = 0; m < 4; ++m) for (int k = 0; k < 2; ++k) \
;     dst[m][k] = *reinterpret_cast<const bf16x8*>(aRd + (((b) * 2 + (h)) * G_HT * 2 + m * 2048 + k * 1024))
; #define LDB(dst, b, h) for (int n = 0; n < 2; ++n) for (int k = 0; k < 2; ++k) \
;     dst[n][k] = *reinterpret_cast<const bf16x8*>(bRd + (((b) * 2 + (h)) * G_HT * 2 + n * 2048 + k * 1024))
; #define MMA(ai, bj, At, Bx) do { __builtin_amdgcn_s_setprio(1); \
;     for (int m = 0; m < 4; ++m) for (int n = 0; n < 2; ++n) for (int k = 0; k < 2; ++k) \
;       acc[ai][bj][m][n] = __builtin_amdgcn_mfma_f32_16x16x32_bf16(Bx[n][k], At[m][k], acc[ai][bj][m][n], 0, 0, 0);     \
;     __builtin_amdgcn_s_setprio(0); } while (0)
; #define WAIT_V(n) asm volatile("s_waitcnt vmcnt(" #n ")" ::: "memory")
; #define WAIT_L(n) asm volatile("s_waitcnt lgkmcnt(" #n ")" ::: "memory")
; #define BAR __builtin_amdgcn_s_barrier()
; #define SCHED __builtin_amdgcn_sched_barrier(0)
; template <int EPI>
; __device__ __forceinline__ void gemm_tile(const bf16* __restrict__ A, int lda, const bf16* __restrict__ Bt, int K,
;                                           int brow, int bcol, const EpiArgs& ea, char* shmc, bool has_next, int nbrow, int nbcol, bool first_tile) {
;     ...
;     BAR; WAIT_L(0); MMA(1, 0, At, B0); BAR; SCHED;
;     STB(1, 1, 1, t + 3);
;     WAIT_V(6); BAR; MMA(1, 1, At, B1); BAR;
;   }
;   { LDB(B0, 0, 0); LDA(At, 0, 0); STA(1, 1, 1, nt - 1);
;     BAR; WAIT_L(0); MMA(0, 0, At, B0); BAR;
;     LDB(B1, 0, 1); BAR; WAIT_L(0); MMA(0, 1, At, B1); BAR;
	s_waitcnt lgkmcnt(0)
	v_mfma_f32_16x16x32_bf16 v[60:63], v[162:165], v[178:181], v[60:63]
	v_mfma_f32_16x16x32_bf16 v[56:59], v[170:173], v[178:181], v[56:59]
	v_mfma_f32_16x16x32_bf16 v[52:55], v[162:165], v[186:189], v[52:55]
	v_mfma_f32_16x16x32_bf16 v[48:51], v[170:173], v[186:189], v[48:51]
	v_mfma_f32_16x16x32_bf16 v[44:47], v[162:165], v[194:197], v[44:47]
	v_mfma_f32_16x16x32_bf16 v[40:43], v[170:173], v[194:197], v[40:43]
	v_mfma_f32_16x16x32_bf16 v[36:39], v[162:165], v[202:205], v[36:39]
	v_mfma_f32_16x16x32_bf16 v[32:35], v[170:173], v[202:205], v[32:35]
	v_mfma_f32_16x16x32_bf16 v[60:63], v[166:169], v[182:185], v[60:63]
	v_mfma_f32_16x16x32_bf16 v[56:59], v[174:177], v[182:185], v[56:59]
	v_mfma_f32_16x16x32_bf16 v[52:55], v[166:169], v[190:193], v[52:55]
	v_mfma_f32_16x16x32_bf16 v[48:51], v[174:177], v[190:193], v[48:51]
	v_mfma_f32_16x16x32_bf16 v[44:47], v[166:169], v[198:201], v[44:47]
	v_mfma_f32_16x16x32_bf16 v[40:43], v[174:177], v[198:201], v[40:43]
	v_mfma_f32_16x16x32_bf16 v[36:39], v[166:169], v[206:209], v[36:39]
	v_mfma_f32_16x16x32_bf16 v[32:35], v[174:177], v[206:209], v[32:35]
	s_barrier
	s_mov_b64 s[82:83], s[34:35]
	s_mov_b32 m0, s69
	v_lshl_add_u64 v[162:163], v[136:137], 0, s[82:83]
	global_load_lds_dwordx4 v[162:163], off
	s_mov_b32 m0, s70
	v_lshl_add_u64 v[162:163], v[162:163], 0, s[0:1]
	global_load_lds_dwordx4 v[162:163], off
	s_waitcnt vmcnt(6)
	s_barrier
	v_mfma_f32_16x16x32_bf16 v[28:31], v[210:213], v[178:181], v[28:31]
	v_mfma_f32_16x16x32_bf16 v[24:27], v[218:221], v[178:181], v[24:27]
	v_mfma_f32_16x16x32_bf16 v[20:23], v[210:213], v[186:189], v[20:23]
	v_mfma_f32_16x16x32_bf16 v[16:19], v[218:221], v[186:189], v[16:19]
	v_mfma_f32_16x16x32_bf16 v[12:15], v[210:213], v[194:197], v[12:15]
	v_mfma_f32_16x16x32_bf16 v[8:11], v[218:221], v[194:197], v[8:11]
	v_mfma_f32_16x16x32_bf16 v[4:7], v[210:213], v[202:205], v[4:7]
	v_mfma_f32_16x16x32_bf16 v[0:3], v[218:221], v[202:205], v[0:3]
	v_mfma_f32_16x16x32_bf16 v[28:31], v[214:217], v[182:185], v[28:31]
	v_mfma_f32_16x16x32_bf16 v[24:27], v[222:225], v[182:185], v[24:27]
	v_mfma_f32_16x16x32_bf16 v[20:23], v[214:217], v[190:193], v[20:23]
	v_mfma_f32_16x16x32_bf16 v[16:19], v[222:225], v[190:193], v[16:19]
	v_mfma_f32_16x16x32_bf16 v[12:15], v[214:217], v[198:201], v[12:15]
	v_mfma_f32_16x16x32_bf16 v[8:11], v[222:225], v[198:201], v[8:11]
	v_mfma_f32_16x16x32_bf16 v[4:7], v[214:217], v[206:209], v[4:7]
	v_mfma_f32_16x16x32_bf16 v[0:3], v[222:225], v[206:209], v[0:3]
	s_add_i32 s75, s75, 2
	s_add_u32 s34, s34, 0x100
	s_addc_u32 s35, s35, 0
	s_cmp_lt_u32 s75, 60
	s_barrier
	s_cbranch_scc1 .LBB0_96
	s_mov_b64 s[34:35], 0x101f80
	s_mov_b32 m0, s77
	ds_read_b128 v[162:165], v141
	ds_read_b128 v[166:169], v142
	ds_read_b128 v[170:173], v143
	ds_read_b128 v[174:177], v144
	ds_read_b128 v[178:181], v160
	ds_read_b128 v[182:185], v160 offset:1024
	ds_read_b128 v[186:189], v160 offset:2048
	ds_read_b128 v[190:193], v160 offset:3072
	ds_read_b128 v[194:197], v160 offset:4096
	ds_read_b128 v[198:201], v160 offset:5120
	ds_read_b128 v[202:205], v160 offset:6144
	ds_read_b128 v[206:209], v160 offset:7168
	s_nop 0
	v_lshl_add_u64 v[134:135], v[134:135], 0, s[34:35]
	global_load_lds_dwordx4 v[134:135], off
	v_lshl_add_u64 v[134:135], v[134:135], 0, s[0:1]
	s_mov_b32 m0, s68
	s_nop 0
	global_load_lds_dwordx4 v[134:135], off
	s_barrier
	s_waitcnt lgkmcnt(0)
	s_waitcnt lgkmcnt(0)
	v_mfma_f32_16x16x32_bf16 v[124:127], v[162:165], v[178:181], v[124:127]
	v_mfma_f32_16x16x32_bf16 v[116:119], v[162:165], v[186:189], v[116:119]
	v_mfma_f32_16x16x32_bf16 v[112:115], v[170:173], v[186:189], v[112:115]
	v_mfma_f32_16x16x32_bf16 v[100:103], v[162:165], v[202:205], v[100:103]
	v_mfma_f32_16x16x32_bf16 v[96:99], v[170:173], v[202:205], v[96:99]
	v_mfma_f32_16x16x32_bf16 v[124:127], v[166:169], v[182:185], v[124:127]
	v_mfma_f32_16x16x32_bf16 v[120:123], v[170:173], v[178:181], v[120:123]
	v_mfma_f32_16x16x32_bf16 v[116:119], v[166:169], v[190:193], v[116:119]
	v_mfma_f32_16x16x32_bf16 v[112:115], v[174:177], v[190:193], v[112:115]
	v_mfma_f32_16x16x32_bf16 v[108:111], v[162:165], v[194:197], v[108:111]
	v_mfma_f32_16x16x32_bf16 v[104:107], v[170:173], v[194:197], v[104:107]
	v_mfma_f32_16x16x32_bf16 v[100:103], v[166:169], v[206:209], v[100:103]
	v_mfma_f32_16x16x32_bf16 v[96:99], v[174:177], v[206:209], v[96:99]
	v_mfma_f32_16x16x32_bf16 v[134:137], v[174:177], v[182:185], v[120:123]
	v_mfma_f32_16x16x32_bf16 v[210:213], v[166:169], v[198:201], v[108:111]
	v_mfma_f32_16x16x32_bf16 v[214:217], v[174:177], v[198:201], v[104:107]
	s_barrier
	s_nop 0
	ds_read_b128 v[104:107], v145
	ds_read_b128 v[108:111], v146
	ds_read_b128 v[120:123], v147
	ds_read_b128 v[218:221], v148
	s_barrier
	s_waitcnt lgkmcnt(0)
	s_waitcnt lgkmcnt(0)
	v_mfma_f32_16x16x32_bf16 v[84:87], v[104:107], v[186:189], v[84:87]
	v_mfma_f32_16x16x32_bf16 v[80:83], v[120:123], v[186:189], v[80:83]
	v_mfma_f32_16x16x32_bf16 v[68:71], v[104:107], v[202:205], v[68:71]
	v_mfma_f32_16x16x32_bf16 v[92:95], v[104:107], v[178:181], v[92:95]
	v_mfma_f32_16x16x32_bf16 v[88:91], v[120:123], v[178:181], v[88:91]
	v_mfma_f32_16x16x32_bf16 v[84:87], v[108:111], v[190:193], v[84:87]
	v_mfma_f32_16x16x32_bf16 v[80:83], v[218:221], v[190:193], v[80:83]
	v_mfma_f32_16x16x32_bf16 v[76:79], v[104:107], v[194:197], v[76:79]
	v_mfma_f32_16x16x32_bf16 v[72:75], v[120:123], v[194:197], v[72:75]
	v_mfma_f32_16x16x32_bf16 v[68:71], v[108:111], v[206:209], v[68:71]
	v_mfma_f32_16x16x32_bf16 v[64:67], v[120:123], v[202:205], v[64:67]
	v_mfma_f32_16x16x32_bf16 v[222:225], v[108:111], v[182:185], v[92:95]
	v_mfma_f32_16x16x32_bf16 v[178:181], v[218:221], v[182:185], v[88:91]
	v_mfma_f32_16x16x32_bf16 v[182:185], v[108:111], v[198:201], v[76:79]
	v_mfma_f32_16x16x32_bf16 v[186:189], v[218:221], v[198:201], v[72:75]
	v_mfma_f32_16x16x32_bf16 v[190:193], v[218:221], v[206:209], v[64:67]
	s_barrier
; #define LDA(dst, b, h) for (int m = 0; m < 4; ++m) for (int k = 0; k < 2; ++k) \
;     dst[m][k] = *reinterpret_cast<const bf16x8*>(aRd + (((b) * 2 + (h)) * G_HT * 2 + m * 2048 + k * 1024))
; #define LDB(dst, b, h) for (int n = 0; n < 2; ++n) for (int k = 0; k < 2; ++k) \
;     dst[n][k] = *reinterpret_cast<const bf16x8*>(bRd + (((b) * 2 + (h)) * G_HT * 2 + n * 2048 + k * 1024))
; #define MMA(ai, bj, At, Bx) do { __builtin_amdgcn_s_setprio(1); \
;     for (int m = 0; m < 4; ++m) for (int n = 0; n < 2; ++n) for (int k = 0; k < 2; ++k) \
;       acc[ai][bj][m][n] = __builtin_amdgcn_mfma_f32_16x16x32_bf16(Bx[n][k], At[m][k], acc[ai][bj][m][n], 0, 0, 0);     \
;     __builtin_amdgcn_s_setprio(0); } while (0)
; #define WAIT_V(n) asm volatile("s_waitcnt vmcnt(" #n ")" ::: "memory")
; #define WAIT_L(n) asm volatile("s_waitcnt lgkmcnt(" #n ")" ::: "memory")
; #define BAR __builtin_amdgcn_s_barrier()
; template <int EPI>
; __device__ __forceinline__ void gemm_tile(const bf16* __restrict__ A, int lda, const bf16* __restrict__ Bt, int K,
;                                           int brow, int bcol, const EpiArgs& ea, char* shmc, bool has_next, int nbrow, int nbcol, bool first_tile) {
;     ...
;     LDA(At, 0, 1); WAIT_V(4); BAR; WAIT_L(0); MMA(1, 0, At, B0); MMA(1, 1, At, B1); BAR; }
;   { LDB(B0, 1, 0); LDA(At, 1, 0); WAIT_V(2); BAR; WAIT_L(0); MMA(0, 0, At, B0); BAR;
	s_nop 0
	ds_read_b128 v[64:67], v160 offset:16384
	ds_read_b128 v[72:75], v160 offset:17408
	ds_read_b128 v[76:79], v160 offset:18432
	ds_read_b128 v[88:91], v160 offset:19456
	ds_read_b128 v[92:95], v160 offset:20480
	ds_read_b128 v[194:197], v160 offset:21504
	ds_read_b128 v[198:201], v160 offset:22528
	ds_read_b128 v[202:205], v160 offset:23552
	s_waitcnt vmcnt(4)
	s_barrier
	s_waitcnt lgkmcnt(0)
	s_waitcnt lgkmcnt(0)
	v_mfma_f32_16x16x32_bf16 v[60:63], v[162:165], v[64:67], v[60:63]
	v_mfma_f32_16x16x32_bf16 v[52:55], v[162:165], v[76:79], v[52:55]
	v_mfma_f32_16x16x32_bf16 v[48:51], v[170:173], v[76:79], v[48:51]
	v_mfma_f32_16x16x32_bf16 v[36:39], v[162:165], v[198:201], v[36:39]
	v_mfma_f32_16x16x32_bf16 v[32:35], v[170:173], v[198:201], v[32:35]
	v_mfma_f32_16x16x32_bf16 v[60:63], v[166:169], v[72:75], v[60:63]
	v_mfma_f32_16x16x32_bf16 v[56:59], v[170:173], v[64:67], v[56:59]
	v_mfma_f32_16x16x32_bf16 v[52:55], v[166:169], v[88:91], v[52:55]
	v_mfma_f32_16x16x32_bf16 v[48:51], v[174:177], v[88:91], v[48:51]
	v_mfma_f32_16x16x32_bf16 v[44:47], v[162:165], v[92:95], v[44:47]
	v_mfma_f32_16x16x32_bf16 v[40:43], v[170:173], v[92:95], v[40:43]
	v_mfma_f32_16x16x32_bf16 v[36:39], v[166:169], v[202:205], v[36:39]
	v_mfma_f32_16x16x32_bf16 v[32:35], v[174:177], v[202:205], v[32:35]
	v_mfma_f32_16x16x32_bf16 v[206:209], v[174:177], v[72:75], v[56:59]
	v_mfma_f32_16x16x32_bf16 v[226:229], v[166:169], v[194:197], v[44:47]
	v_mfma_f32_16x16x32_bf16 v[230:233], v[174:177], v[194:197], v[40:43]
	v_mfma_f32_16x16x32_bf16 v[20:23], v[104:107], v[76:79], v[20:23]
	v_mfma_f32_16x16x32_bf16 v[16:19], v[120:123], v[76:79], v[16:19]
	v_mfma_f32_16x16x32_bf16 v[4:7], v[104:107], v[198:201], v[4:7]
	v_mfma_f32_16x16x32_bf16 v[28:31], v[104:107], v[64:67], v[28:31]
	v_mfma_f32_16x16x32_bf16 v[24:27], v[120:123], v[64:67], v[24:27]
	v_mfma_f32_16x16x32_bf16 v[20:23], v[108:111], v[88:91], v[20:23]
	v_mfma_f32_16x16x32_bf16 v[16:19], v[218:221], v[88:91], v[16:19]
	v_mfma_f32_16x16x32_bf16 v[12:15], v[104:107], v[92:95], v[12:15]
	v_mfma_f32_16x16x32_bf16 v[8:11], v[120:123], v[92:95], v[8:11]
	v_mfma_f32_16x16x32_bf16 v[4:7], v[108:111], v[202:205], v[4:7]
	v_mfma_f32_16x16x32_bf16 v[0:3], v[120:123], v[198:201], v[0:3]
	v_mfma_f32_16x16x32_bf16 v[162:165], v[108:111], v[72:75], v[28:31]
	v_mfma_f32_16x16x32_bf16 v[166:169], v[218:221], v[72:75], v[24:27]
	v_mfma_f32_16x16x32_bf16 v[170:173], v[108:111], v[194:197], v[12:15]
	v_mfma_f32_16x16x32_bf16 v[174:177], v[218:221], v[194:197], v[8:11]
	v_mfma_f32_16x16x32_bf16 v[194:197], v[218:221], v[202:205], v[0:3]
	s_barrier
	s_nop 0
	ds_read_b128 v[0:3], v149
	ds_read_b128 v[8:11], v150
	ds_read_b128 v[12:15], v151
	ds_read_b128 v[198:201], v152
	ds_read_b128 v[24:27], v160 offset:32768
	ds_read_b128 v[28:31], v160 offset:33792
	ds_read_b128 v[40:43], v160 offset:34816
	ds_read_b128 v[44:47], v160 offset:35840
	ds_read_b128 v[56:59], v160 offset:36864
	ds_read_b128 v[64:67], v160 offset:37888
	ds_read_b128 v[202:205], v160 offset:38912
	ds_read_b128 v[218:221], v160 offset:39936
	s_waitcnt vmcnt(2)
	s_barrier
	s_waitcnt lgkmcnt(0)
	s_waitcnt lgkmcnt(0)
	v_mfma_f32_16x16x32_bf16 v[72:75], v[0:3], v[24:27], v[124:127]
	v_mfma_f32_16x16x32_bf16 v[120:123], v[8:11], v[28:31], v[72:75]
	v_mfma_f32_16x16x32_bf16 v[72:75], v[12:15], v[24:27], v[134:137]
	v_mfma_f32_16x16x32_bf16 v[124:127], v[198:201], v[28:31], v[72:75]
	v_mfma_f32_16x16x32_bf16 v[72:75], v[0:3], v[40:43], v[116:119]
	v_mfma_f32_16x16x32_bf16 v[104:107], v[8:11], v[44:47], v[72:75]
	v_mfma_f32_16x16x32_bf16 v[72:75], v[12:15], v[40:43], v[112:115]
	v_mfma_f32_16x16x32_bf16 v[108:111], v[198:201], v[44:47], v[72:75]
	v_mfma_f32_16x16x32_bf16 v[72:75], v[0:3], v[56:59], v[210:213]
	v_mfma_f32_16x16x32_bf16 v[88:91], v[8:11], v[64:67], v[72:75]
	v_mfma_f32_16x16x32_bf16 v[72:75], v[12:15], v[56:59], v[214:217]
	v_mfma_f32_16x16x32_bf16 v[92:95], v[198:201], v[64:67], v[72:75]
	v_mfma_f32_16x16x32_bf16 v[72:75], v[0:3], v[202:205], v[100:103]
	v_mfma_f32_16x16x32_bf16 v[76:79], v[12:15], v[202:205], v[96:99]
	v_mfma_f32_16x16x32_bf16 v[72:75], v[8:11], v[218:221], v[72:75]
	v_mfma_f32_16x16x32_bf16 v[76:79], v[198:201], v[218:221], v[76:79]
	s_barrier
; #define LDA(dst, b, h) for (int m = 0; m < 4; ++m) for (int k = 0; k < 2; ++k) \
;     dst[m][k] = *reinterpret_cast<const bf16x8*>(aRd + (((b) * 2 + (h)) * G_HT * 2 + m * 2048 + k * 1024))
; #define LDB(dst, b, h) for (int n = 0; n < 2; ++n) for (int k = 0; k < 2; ++k) \
;     dst[n][k] = *reinterpret_cast<const bf16x8*>(bRd + (((b) * 2 + (h)) * G_HT * 2 + n * 2048 + k * 1024))
; #define MMA(ai, bj, At, Bx) do { __builtin_amdgcn_s_setprio(1); \
;     for (int m = 0; m < 4; ++m) for (int n = 0; n < 2; ++n) for (int k = 0; k < 2; ++k) \
;       acc[ai][bj][m][n] = __builtin_amdgcn_mfma_f32_16x16x32_bf16(Bx[n][k], At[m][k], acc[ai][bj][m][n], 0, 0, 0);     \
;     __builtin_amdgcn_s_setprio(0); } while (0)
; #define WAIT_V(n) asm volatile("s_waitcnt vmcnt(" #n ")" ::: "memory")
; #define WAIT_L(n) asm volatile("s_waitcnt lgkmcnt(" #n ")" ::: "memory")
; #define BAR __builtin_amdgcn_s_barrier()
; template <int EPI>
; __device__ __forceinline__ void gemm_tile(const bf16* __restrict__ A, int lda, const bf16* __restrict__ Bt, int K,
;                                           int brow, int bcol, const EpiArgs& ea, char* shmc, bool has_next, int nbrow, int nbcol, bool first_tile) {
;     ...
;     LDB(B1, 1, 1); WAIT_V(0); BAR; WAIT_L(0); MMA(0, 1, At, B1); BAR;
;     LDA(At, 1, 1); BAR; WAIT_L(0); MMA(1, 0, At, B0); MMA(1, 1, At, B1); BAR; }
;   if (wr == 0) BAR;
	ds_read_b128 v[134:137], v153
	ds_read_b128 v[210:213], v154
	ds_read_b128 v[214:217], v155
	ds_read_b128 v[234:237], v156
	s_waitcnt vmcnt(0)
	s_barrier
	s_waitcnt lgkmcnt(0)
	s_waitcnt lgkmcnt(0)
	v_mfma_f32_16x16x32_bf16 v[96:99], v[134:137], v[24:27], v[222:225]
	v_mfma_f32_16x16x32_bf16 v[24:27], v[214:217], v[24:27], v[178:181]
	v_mfma_f32_16x16x32_bf16 v[116:119], v[234:237], v[28:31], v[24:27]
	v_mfma_f32_16x16x32_bf16 v[24:27], v[134:137], v[40:43], v[84:87]
	v_mfma_f32_16x16x32_bf16 v[112:115], v[210:213], v[28:31], v[96:99]
	v_mfma_f32_16x16x32_bf16 v[96:99], v[210:213], v[44:47], v[24:27]
	v_mfma_f32_16x16x32_bf16 v[24:27], v[214:217], v[40:43], v[80:83]
	v_mfma_f32_16x16x32_bf16 v[100:103], v[234:237], v[44:47], v[24:27]
	v_mfma_f32_16x16x32_bf16 v[24:27], v[134:137], v[56:59], v[182:185]
	v_mfma_f32_16x16x32_bf16 v[80:83], v[210:213], v[64:67], v[24:27]
	v_mfma_f32_16x16x32_bf16 v[24:27], v[214:217], v[56:59], v[186:189]
	v_mfma_f32_16x16x32_bf16 v[84:87], v[234:237], v[64:67], v[24:27]
	v_mfma_f32_16x16x32_bf16 v[24:27], v[134:137], v[202:205], v[68:71]
	v_mfma_f32_16x16x32_bf16 v[64:67], v[210:213], v[218:221], v[24:27]
	v_mfma_f32_16x16x32_bf16 v[24:27], v[214:217], v[202:205], v[190:193]
	v_mfma_f32_16x16x32_bf16 v[68:71], v[234:237], v[218:221], v[24:27]
	s_barrier
	ds_read_b128 v[178:181], v160 offset:49152
	ds_read_b128 v[182:185], v160 offset:50176
	ds_read_b128 v[186:189], v160 offset:51200
	ds_read_b128 v[190:193], v160 offset:52224
	ds_read_b128 v[202:205], v160 offset:53248
	ds_read_b128 v[218:221], v160 offset:54272
	ds_read_b128 v[222:225], v160 offset:55296
	ds_read_b128 v[238:241], v160 offset:56320
	s_barrier
	s_waitcnt lgkmcnt(0)
	s_waitcnt lgkmcnt(0)
	v_mfma_f32_16x16x32_bf16 v[24:27], v[0:3], v[178:181], v[60:63]
	v_mfma_f32_16x16x32_bf16 v[56:59], v[8:11], v[182:185], v[24:27]
	v_mfma_f32_16x16x32_bf16 v[24:27], v[12:15], v[178:181], v[206:209]
	v_mfma_f32_16x16x32_bf16 v[60:63], v[198:201], v[182:185], v[24:27]
	v_mfma_f32_16x16x32_bf16 v[24:27], v[0:3], v[186:189], v[52:55]
	v_mfma_f32_16x16x32_bf16 v[40:43], v[8:11], v[190:193], v[24:27]
	v_mfma_f32_16x16x32_bf16 v[24:27], v[12:15], v[186:189], v[48:51]
	v_mfma_f32_16x16x32_bf16 v[44:47], v[198:201], v[190:193], v[24:27]
	v_mfma_f32_16x16x32_bf16 v[24:27], v[0:3], v[202:205], v[226:229]
	v_mfma_f32_16x16x32_bf16 v[0:3], v[0:3], v[222:225], v[36:39]
	v_mfma_f32_16x16x32_bf16 v[24:27], v[8:11], v[218:221], v[24:27]
	v_mfma_f32_16x16x32_bf16 v[28:31], v[12:15], v[202:205], v[230:233]
	v_mfma_f32_16x16x32_bf16 v[8:11], v[8:11], v[238:241], v[0:3]
	v_mfma_f32_16x16x32_bf16 v[0:3], v[12:15], v[222:225], v[32:35]
	v_mfma_f32_16x16x32_bf16 v[28:31], v[198:201], v[218:221], v[28:31]
	v_mfma_f32_16x16x32_bf16 v[12:15], v[198:201], v[238:241], v[0:3]
	v_mfma_f32_16x16x32_bf16 v[0:3], v[134:137], v[178:181], v[162:165]
	v_mfma_f32_16x16x32_bf16 v[48:51], v[210:213], v[182:185], v[0:3]
	v_mfma_f32_16x16x32_bf16 v[0:3], v[214:217], v[178:181], v[166:169]
	v_mfma_f32_16x16x32_bf16 v[52:55], v[234:237], v[182:185], v[0:3]
	v_mfma_f32_16x16x32_bf16 v[0:3], v[134:137], v[186:189], v[20:23]
	v_mfma_f32_16x16x32_bf16 v[32:35], v[210:213], v[190:193], v[0:3]
	v_mfma_f32_16x16x32_bf16 v[0:3], v[214:217], v[186:189], v[16:19]
	v_mfma_f32_16x16x32_bf16 v[36:39], v[234:237], v[190:193], v[0:3]
	v_mfma_f32_16x16x32_bf16 v[0:3], v[134:137], v[202:205], v[170:173]
	v_mfma_f32_16x16x32_bf16 v[16:19], v[210:213], v[218:221], v[0:3]
	v_mfma_f32_16x16x32_bf16 v[0:3], v[214:217], v[202:205], v[174:177]
	v_mfma_f32_16x16x32_bf16 v[20:23], v[234:237], v[218:221], v[0:3]
	v_mfma_f32_16x16x32_bf16 v[0:3], v[134:137], v[222:225], v[4:7]
	v_mfma_f32_16x16x32_bf16 v[4:7], v[214:217], v[222:225], v[194:197]
	v_mfma_f32_16x16x32_bf16 v[0:3], v[210:213], v[238:241], v[0:3]
	v_mfma_f32_16x16x32_bf16 v[4:7], v[234:237], v[238:241], v[4:7]
	s_barrier
	s_and_saveexec_b64 s[34:35], s[4:5]
	s_cbranch_execz .LBB0_99
	s_barrier

; #define STA(b, h, half, kt) STAGE(((b) * 2 + (h)) * G_HT * 2, pA, ((size_t)(half) * G_HALF * lda + (size_t)(kt) * G_BK) * 2, lda)
; #define STB(b, h, half, kt) STAGE((4 + (b) * 2 + (h)) * G_HT * 2, pB, ((size_t)(half) * G_HALF * K + (size_t)(kt) * G_BK) * 2, K)
; #define LDA(dst, b, h) for (int m = 0; m < 4; ++m) for (int k = 0; k < 2; ++k) \
;     dst[m][k] = *reinterpret_cast<const bf16x8*>(aRd + (((b) * 2 + (h)) * G_HT * 2 + m * 2048 + k * 1024))
; #define LDB(dst, b, h) for (int n = 0; n < 2; ++n) for (int k = 0; k < 2; ++k) \
;     dst[n][k] = *reinterpret_cast<const bf16x8*>(bRd + (((b) * 2 + (h)) * G_HT * 2 + n * 2048 + k * 1024))
; #define MMA(ai, bj, At, Bx) do { __builtin_amdgcn_s_setprio(1); \
;     for (int m = 0; m < 4; ++m) for (int n = 0; n < 2; ++n) for (int k = 0; k < 2; ++k) \
;       acc[ai][bj][m][n] = __builtin_amdgcn_mfma_f32_16x16x32_bf16(Bx[n][k], At[m][k], acc[ai][bj][m][n], 0, 0, 0);     \
;     __builtin_amdgcn_s_setprio(0); } while (0)
; #define WAIT_V(n) asm volatile("s_waitcnt vmcnt(" #n ")" ::: "memory")
; #define WAIT_L(n) asm volatile("s_waitcnt lgkmcnt(" #n ")" ::: "memory")
; #define BAR __builtin_amdgcn_s_barrier()
; #define SCHED __builtin_amdgcn_sched_barrier(0)
; template <int EPI>
; __device__ __forceinline__ void gemm_tile(const bf16* __restrict__ A, int lda, const bf16* __restrict__ Bt, int K,
;                                           int brow, int bcol, const EpiArgs& ea, char* shmc, bool has_next, int nbrow, int nbcol, bool first_tile) {
;     ...
;   for (int t = 0; t < nt - 2; t += 2) {
;     LDB(B0, 0, 0); SCHED; LDA(At, 0, 0); STA(1, 1, 1, t + 1);
;     WAIT_L(8); BAR; WAIT_L(0); MMA(0, 0, At, B0); BAR; SCHED;
;     LDB(B1, 0, 1); STB(0, 0, 0, t + 2);
;     BAR; WAIT_L(0); MMA(0, 1, At, B1); BAR;
;     LDA(At, 0, 1); STA(0, 0, 0, t + 2);
;     BAR; WAIT_L(0); MMA(1, 0, At, B0); BAR; SCHED;
;     STB(0, 1, 1, t + 2);
;     WAIT_V(6); BAR; MMA(1, 1, At, B1); BAR;
.LBB0_291:
	ds_read_b128 v[160:163], v137
	ds_read_b128 v[164:167], v138
	ds_read_b128 v[168:171], v139
	ds_read_b128 v[172:175], v140
	s_add_u32 s80, s18, 0xffffff80
	s_addc_u32 s81, s19, -1
	s_mov_b32 m0, s72
	ds_read_b128 v[176:179], v158
	ds_read_b128 v[180:183], v158 offset:1024
	ds_read_b128 v[184:187], v158 offset:2048
	ds_read_b128 v[188:191], v158 offset:3072
	ds_read_b128 v[192:195], v158 offset:4096
	ds_read_b128 v[196:199], v158 offset:5120
	ds_read_b128 v[200:203], v158 offset:6144
	ds_read_b128 v[204:207], v158 offset:7168
	s_nop 0
	v_lshl_add_u64 v[208:209], v[132:133], 0, s[80:81]
	global_load_lds_dwordx4 v[208:209], off
	s_mov_b32 m0, s62
	v_lshl_add_u64 v[208:209], v[208:209], 0, s[10:11]
	global_load_lds_dwordx4 v[208:209], off
	s_waitcnt lgkmcnt(8)
	s_barrier
	s_waitcnt lgkmcnt(0)
	s_waitcnt lgkmcnt(0)
	v_mfma_f32_16x16x32_bf16 v[124:127], v[160:163], v[176:179], v[124:127]
	v_mfma_f32_16x16x32_bf16 v[120:123], v[168:171], v[176:179], v[120:123]
	v_mfma_f32_16x16x32_bf16 v[116:119], v[160:163], v[184:187], v[116:119]
	v_mfma_f32_16x16x32_bf16 v[112:115], v[168:171], v[184:187], v[112:115]
	v_mfma_f32_16x16x32_bf16 v[108:111], v[160:163], v[192:195], v[108:111]
	v_mfma_f32_16x16x32_bf16 v[104:107], v[168:171], v[192:195], v[104:107]
	v_mfma_f32_16x16x32_bf16 v[100:103], v[160:163], v[200:203], v[100:103]
	v_mfma_f32_16x16x32_bf16 v[96:99], v[168:171], v[200:203], v[96:99]
	v_mfma_f32_16x16x32_bf16 v[124:127], v[164:167], v[180:183], v[124:127]
	v_mfma_f32_16x16x32_bf16 v[120:123], v[172:175], v[180:183], v[120:123]
	v_mfma_f32_16x16x32_bf16 v[116:119], v[164:167], v[188:191], v[116:119]
	v_mfma_f32_16x16x32_bf16 v[112:115], v[172:175], v[188:191], v[112:115]
	v_mfma_f32_16x16x32_bf16 v[108:111], v[164:167], v[196:199], v[108:111]
	v_mfma_f32_16x16x32_bf16 v[104:107], v[172:175], v[196:199], v[104:107]
	v_mfma_f32_16x16x32_bf16 v[100:103], v[164:167], v[204:207], v[100:103]
	v_mfma_f32_16x16x32_bf16 v[96:99], v[172:175], v[204:207], v[96:99]
	s_barrier
	s_add_u32 s80, s18, 0xfffa0000
	s_addc_u32 s81, s19, -1
	s_mov_b64 s[82:83], s[80:81]
	s_mov_b32 m0, s67
	ds_read_b128 v[208:211], v141
	ds_read_b128 v[212:215], v142
	ds_read_b128 v[216:219], v143
	ds_read_b128 v[220:223], v144
	s_nop 0
	v_lshl_add_u64 v[224:225], v[134:135], 0, s[82:83]
	global_load_lds_dwordx4 v[224:225], off
	s_mov_b32 m0, s68
	v_lshl_add_u64 v[224:225], v[224:225], 0, s[8:9]
	global_load_lds_dwordx4 v[224:225], off
	s_barrier
	s_waitcnt lgkmcnt(0)
	s_waitcnt lgkmcnt(0)
	v_mfma_f32_16x16x32_bf16 v[92:95], v[208:211], v[176:179], v[92:95]
	v_mfma_f32_16x16x32_bf16 v[88:91], v[216:219], v[176:179], v[88:91]
	v_mfma_f32_16x16x32_bf16 v[84:87], v[208:211], v[184:187], v[84:87]
	v_mfma_f32_16x16x32_bf16 v[80:83], v[216:219], v[184:187], v[80:83]
	v_mfma_f32_16x16x32_bf16 v[76:79], v[208:211], v[192:195], v[76:79]
	v_mfma_f32_16x16x32_bf16 v[72:75], v[216:219], v[192:195], v[72:75]
	v_mfma_f32_16x16x32_bf16 v[68:71], v[208:211], v[200:203], v[68:71]
	v_mfma_f32_16x16x32_bf16 v[64:67], v[216:219], v[200:203], v[64:67]
	v_mfma_f32_16x16x32_bf16 v[92:95], v[212:215], v[180:183], v[92:95]
	v_mfma_f32_16x16x32_bf16 v[88:91], v[220:223], v[180:183], v[88:91]
	v_mfma_f32_16x16x32_bf16 v[84:87], v[212:215], v[188:191], v[84:87]
	v_mfma_f32_16x16x32_bf16 v[80:83], v[220:223], v[188:191], v[80:83]
	v_mfma_f32_16x16x32_bf16 v[76:79], v[212:215], v[196:199], v[76:79]
	v_mfma_f32_16x16x32_bf16 v[72:75], v[220:223], v[196:199], v[72:75]
	v_mfma_f32_16x16x32_bf16 v[68:71], v[212:215], v[204:207], v[68:71]
	v_mfma_f32_16x16x32_bf16 v[64:67], v[220:223], v[204:207], v[64:67]
	s_mov_b32 m0, s31
	s_barrier
	ds_read_b128 v[176:179], v158 offset:16384
	ds_read_b128 v[180:183], v158 offset:17408
	ds_read_b128 v[184:187], v158 offset:18432
	ds_read_b128 v[188:191], v158 offset:19456
	ds_read_b128 v[192:195], v158 offset:20480
	ds_read_b128 v[196:199], v158 offset:21504
	ds_read_b128 v[200:203], v158 offset:22528
	ds_read_b128 v[204:207], v158 offset:23552
	s_nop 0
	v_lshl_add_u64 v[224:225], v[132:133], 0, s[80:81]
	global_load_lds_dwordx4 v[224:225], off
	s_mov_b32 m0, s73
	v_lshl_add_u64 v[224:225], v[224:225], 0, s[10:11]
	global_load_lds_dwordx4 v[224:225], off
	s_barrier
	s_waitcnt lgkmcnt(0)
	s_waitcnt lgkmcnt(0)
	v_mfma_f32_16x16x32_bf16 v[60:63], v[160:163], v[176:179], v[60:63]
	v_mfma_f32_16x16x32_bf16 v[56:59], v[168:171], v[176:179], v[56:59]
	v_mfma_f32_16x16x32_bf16 v[52:55], v[160:163], v[184:187], v[52:55]
	v_mfma_f32_16x16x32_bf16 v[48:51], v[168:171], v[184:187], v[48:51]
	v_mfma_f32_16x16x32_bf16 v[44:47], v[160:163], v[192:195], v[44:47]
	v_mfma_f32_16x16x32_bf16 v[40:43], v[168:171], v[192:195], v[40:43]
	v_mfma_f32_16x16x32_bf16 v[36:39], v[160:163], v[200:203], v[36:39]
	v_mfma_f32_16x16x32_bf16 v[32:35], v[168:171], v[200:203], v[32:35]
	v_mfma_f32_16x16x32_bf16 v[60:63], v[164:167], v[180:183], v[60:63]
	v_mfma_f32_16x16x32_bf16 v[56:59], v[172:175], v[180:183], v[56:59]
	v_mfma_f32_16x16x32_bf16 v[52:55], v[164:167], v[188:191], v[52:55]
	v_mfma_f32_16x16x32_bf16 v[48:51], v[172:175], v[188:191], v[48:51]
	v_mfma_f32_16x16x32_bf16 v[44:47], v[164:167], v[196:199], v[44:47]
	v_mfma_f32_16x16x32_bf16 v[40:43], v[172:175], v[196:199], v[40:43]
	v_mfma_f32_16x16x32_bf16 v[36:39], v[164:167], v[204:207], v[36:39]
	v_mfma_f32_16x16x32_bf16 v[32:35], v[172:175], v[204:207], v[32:35]
	s_barrier
	s_add_u32 s80, s18, 0xfffd0000
	s_addc_u32 s81, s19, -1
	s_mov_b32 m0, s69
	s_nop 0
	v_lshl_add_u64 v[160:161], v[134:135], 0, s[80:81]
	global_load_lds_dwordx4 v[160:161], off
	s_mov_b32 m0, s70
	v_lshl_add_u64 v[160:161], v[160:161], 0, s[8:9]
	global_load_lds_dwordx4 v[160:161], off
	s_waitcnt vmcnt(6)
	s_barrier
; #define STA(b, h, half, kt) STAGE(((b) * 2 + (h)) * G_HT * 2, pA, ((size_t)(half) * G_HALF * lda + (size_t)(kt) * G_BK) * 2, lda)
; #define STB(b, h, half, kt) STAGE((4 + (b) * 2 + (h)) * G_HT * 2, pB, ((size_t)(half) * G_HALF * K + (size_t)(kt) * G_BK) * 2, K)
; #define LDA(dst, b, h) for (int m = 0; m < 4; ++m) for (int k = 0; k < 2; ++k) \
;     dst[m][k] = *reinterpret_cast<const bf16x8*>(aRd + (((b) * 2 + (h)) * G_HT * 2 + m * 2048 + k * 1024))
; #define LDB(dst, b, h) for (int n = 0; n < 2; ++n) for (int k = 0; k < 2; ++k) \
;     dst[n][k] = *reinterpret_cast<const bf16x8*>(bRd + (((b) * 2 + (h)) * G_HT * 2 + n * 2048 + k * 1024))
; #define MMA(ai, bj, At, Bx) do { __builtin_amdgcn_s_setprio(1); \
;     for (int m = 0; m < 4; ++m) for (int n = 0; n < 2; ++n) for (int k = 0; k < 2; ++k) \
;       acc[ai][bj][m][n] = __builtin_amdgcn_mfma_f32_16x16x32_bf16(Bx[n][k], At[m][k], acc[ai][bj][m][n], 0, 0, 0);     \
;     __builtin_amdgcn_s_setprio(0); } while (0)
; #define WAIT_V(n) asm volatile("s_waitcnt vmcnt(" #n ")" ::: "memory")
; #define WAIT_L(n) asm volatile("s_waitcnt lgkmcnt(" #n ")" ::: "memory")
; #define BAR __builtin_amdgcn_s_barrier()
; #define SCHED __builtin_amdgcn_sched_barrier(0)
; template <int EPI>
; __device__ __forceinline__ void gemm_tile(const bf16* __restrict__ A, int lda, const bf16* __restrict__ Bt, int K,
;                                           int brow, int bcol, const EpiArgs& ea, char* shmc, bool has_next, int nbrow, int nbcol, bool first_tile) {
;     ...
;     LDB(B0, 0, 0); SCHED; LDA(At, 0, 0); STA(1, 1, 1, t + 1);
;     WAIT_L(8); BAR; WAIT_L(0); MMA(0, 0, At, B0); BAR; SCHED;
;     LDB(B1, 0, 1); STB(0, 0, 0, t + 2);
;     BAR; WAIT_L(0); MMA(0, 1, At, B1); BAR;
;     LDA(At, 0, 1); STA(0, 0, 0, t + 2);
;     BAR; WAIT_L(0); MMA(1, 0, At, B0); BAR; SCHED;
;     STB(0, 1, 1, t + 2);
;     WAIT_V(6); BAR; MMA(1, 1, At, B1); BAR;
;     LDB(B0, 1, 0); SCHED; LDA(At, 1, 0); STA(0, 1, 1, t + 2);
;     WAIT_L(8); BAR; WAIT_L(0); MMA(0, 0, At, B0); BAR; SCHED;
;     LDB(B1, 1, 1); STB(1, 0, 0, t + 3);
;     BAR; WAIT_L(0); MMA(0, 1, At, B1); BAR;
;     LDA(At, 1, 1); STA(1, 0, 0, t + 3);
;     BAR; WAIT_L(0); MMA(1, 0, At, B0); BAR; SCHED;
;     STB(1, 1, 1, t + 3);
;     WAIT_V(6); BAR; MMA(1, 1, At, B1); BAR;
	v_mfma_f32_16x16x32_bf16 v[28:31], v[208:211], v[176:179], v[28:31]
	v_mfma_f32_16x16x32_bf16 v[24:27], v[216:219], v[176:179], v[24:27]
	v_mfma_f32_16x16x32_bf16 v[20:23], v[208:211], v[184:187], v[20:23]
	v_mfma_f32_16x16x32_bf16 v[16:19], v[216:219], v[184:187], v[16:19]
	v_mfma_f32_16x16x32_bf16 v[12:15], v[208:211], v[192:195], v[12:15]
	v_mfma_f32_16x16x32_bf16 v[8:11], v[216:219], v[192:195], v[8:11]
	v_mfma_f32_16x16x32_bf16 v[4:7], v[208:211], v[200:203], v[4:7]
	v_mfma_f32_16x16x32_bf16 v[0:3], v[216:219], v[200:203], v[0:3]
	v_mfma_f32_16x16x32_bf16 v[28:31], v[212:215], v[180:183], v[28:31]
	v_mfma_f32_16x16x32_bf16 v[24:27], v[220:223], v[180:183], v[24:27]
	v_mfma_f32_16x16x32_bf16 v[20:23], v[212:215], v[188:191], v[20:23]
	v_mfma_f32_16x16x32_bf16 v[16:19], v[220:223], v[188:191], v[16:19]
	v_mfma_f32_16x16x32_bf16 v[12:15], v[212:215], v[196:199], v[12:15]
	v_mfma_f32_16x16x32_bf16 v[8:11], v[220:223], v[196:199], v[8:11]
	v_mfma_f32_16x16x32_bf16 v[4:7], v[212:215], v[204:207], v[4:7]
	v_mfma_f32_16x16x32_bf16 v[0:3], v[220:223], v[204:207], v[0:3]
	s_barrier
	ds_read_b128 v[160:163], v145
	ds_read_b128 v[164:167], v146
	ds_read_b128 v[168:171], v147
	ds_read_b128 v[172:175], v148
	s_mov_b64 s[80:81], s[18:19]
	s_mov_b32 m0, s74
	ds_read_b128 v[176:179], v158 offset:32768
	ds_read_b128 v[180:183], v158 offset:33792
	ds_read_b128 v[184:187], v158 offset:34816
	ds_read_b128 v[188:191], v158 offset:35840
	ds_read_b128 v[192:195], v158 offset:36864
	ds_read_b128 v[196:199], v158 offset:37888
	ds_read_b128 v[200:203], v158 offset:38912
	ds_read_b128 v[204:207], v158 offset:39936
	s_nop 0
	v_lshl_add_u64 v[208:209], v[132:133], 0, s[80:81]
	global_load_lds_dwordx4 v[208:209], off
	s_mov_b32 m0, s75
	v_lshl_add_u64 v[208:209], v[208:209], 0, s[10:11]
	global_load_lds_dwordx4 v[208:209], off
	s_waitcnt lgkmcnt(8)
	s_barrier
	s_waitcnt lgkmcnt(0)
	s_waitcnt lgkmcnt(0)
	v_mfma_f32_16x16x32_bf16 v[124:127], v[160:163], v[176:179], v[124:127]
	v_mfma_f32_16x16x32_bf16 v[120:123], v[168:171], v[176:179], v[120:123]
	v_mfma_f32_16x16x32_bf16 v[116:119], v[160:163], v[184:187], v[116:119]
	v_mfma_f32_16x16x32_bf16 v[112:115], v[168:171], v[184:187], v[112:115]
	v_mfma_f32_16x16x32_bf16 v[108:111], v[160:163], v[192:195], v[108:111]
	v_mfma_f32_16x16x32_bf16 v[104:107], v[168:171], v[192:195], v[104:107]
	v_mfma_f32_16x16x32_bf16 v[100:103], v[160:163], v[200:203], v[100:103]
	v_mfma_f32_16x16x32_bf16 v[96:99], v[168:171], v[200:203], v[96:99]
	v_mfma_f32_16x16x32_bf16 v[124:127], v[164:167], v[180:183], v[124:127]
	v_mfma_f32_16x16x32_bf16 v[120:123], v[172:175], v[180:183], v[120:123]
	v_mfma_f32_16x16x32_bf16 v[116:119], v[164:167], v[188:191], v[116:119]
	v_mfma_f32_16x16x32_bf16 v[112:115], v[172:175], v[188:191], v[112:115]
	v_mfma_f32_16x16x32_bf16 v[108:111], v[164:167], v[196:199], v[108:111]
	v_mfma_f32_16x16x32_bf16 v[104:107], v[172:175], v[196:199], v[104:107]
	v_mfma_f32_16x16x32_bf16 v[100:103], v[164:167], v[204:207], v[100:103]
	v_mfma_f32_16x16x32_bf16 v[96:99], v[172:175], v[204:207], v[96:99]
	s_barrier
	s_add_u32 s80, s18, 0xfffa0080
	s_addc_u32 s81, s19, -1
	s_mov_b64 s[82:83], s[80:81]
	s_mov_b32 m0, s34
	ds_read_b128 v[208:211], v149
	ds_read_b128 v[212:215], v150
	ds_read_b128 v[216:219], v151
	ds_read_b128 v[220:223], v152
	s_nop 0
	v_lshl_add_u64 v[224:225], v[134:135], 0, s[82:83]
	global_load_lds_dwordx4 v[224:225], off
	s_mov_b32 m0, s35
	v_lshl_add_u64 v[224:225], v[224:225], 0, s[8:9]
	global_load_lds_dwordx4 v[224:225], off
	s_barrier
	s_waitcnt lgkmcnt(0)
	s_waitcnt lgkmcnt(0)
	v_mfma_f32_16x16x32_bf16 v[92:95], v[208:211], v[176:179], v[92:95]
	v_mfma_f32_16x16x32_bf16 v[88:91], v[216:219], v[176:179], v[88:91]
	v_mfma_f32_16x16x32_bf16 v[84:87], v[208:211], v[184:187], v[84:87]
	v_mfma_f32_16x16x32_bf16 v[80:83], v[216:219], v[184:187], v[80:83]
	v_mfma_f32_16x16x32_bf16 v[76:79], v[208:211], v[192:195], v[76:79]
	v_mfma_f32_16x16x32_bf16 v[72:75], v[216:219], v[192:195], v[72:75]
	v_mfma_f32_16x16x32_bf16 v[68:71], v[208:211], v[200:203], v[68:71]
	v_mfma_f32_16x16x32_bf16 v[64:67], v[216:219], v[200:203], v[64:67]
	v_mfma_f32_16x16x32_bf16 v[92:95], v[212:215], v[180:183], v[92:95]
	v_mfma_f32_16x16x32_bf16 v[88:91], v[220:223], v[180:183], v[88:91]
	v_mfma_f32_16x16x32_bf16 v[84:87], v[212:215], v[188:191], v[84:87]
	v_mfma_f32_16x16x32_bf16 v[80:83], v[220:223], v[188:191], v[80:83]
	v_mfma_f32_16x16x32_bf16 v[76:79], v[212:215], v[196:199], v[76:79]
	v_mfma_f32_16x16x32_bf16 v[72:75], v[220:223], v[196:199], v[72:75]
	v_mfma_f32_16x16x32_bf16 v[68:71], v[212:215], v[204:207], v[68:71]
	v_mfma_f32_16x16x32_bf16 v[64:67], v[220:223], v[204:207], v[64:67]
	s_mov_b32 m0, s54
	s_barrier
	ds_read_b128 v[176:179], v158 offset:49152
	ds_read_b128 v[180:183], v158 offset:50176
	ds_read_b128 v[184:187], v158 offset:51200
	ds_read_b128 v[188:191], v158 offset:52224
	ds_read_b128 v[192:195], v158 offset:53248
	ds_read_b128 v[196:199], v158 offset:54272
	ds_read_b128 v[200:203], v158 offset:55296
	ds_read_b128 v[204:207], v158 offset:56320
	s_nop 0
	v_lshl_add_u64 v[224:225], v[132:133], 0, s[80:81]
	global_load_lds_dwordx4 v[224:225], off
	s_mov_b32 m0, s55
	v_lshl_add_u64 v[224:225], v[224:225], 0, s[10:11]
	global_load_lds_dwordx4 v[224:225], off
	s_barrier
; #define STA(b, h, half, kt) STAGE(((b) * 2 + (h)) * G_HT * 2, pA, ((size_t)(half) * G_HALF * lda + (size_t)(kt) * G_BK) * 2, lda)
; #define STB(b, h, half, kt) STAGE((4 + (b) * 2 + (h)) * G_HT * 2, pB, ((size_t)(half) * G_HALF * K + (size_t)(kt) * G_BK) * 2, K)
; #define LDA(dst, b, h) for (int m = 0; m < 4; ++m) for (int k = 0; k < 2; ++k) \
;     dst[m][k] = *reinterpret_cast<const bf16x8*>(aRd + (((b) * 2 + (h)) * G_HT * 2 + m * 2048 + k * 1024))
; #define LDB(dst, b, h) for (int n = 0; n < 2; ++n) for (int k = 0; k < 2; ++k) \
;     dst[n][k] = *reinterpret_cast<const bf16x8*>(bRd + (((b) * 2 + (h)) * G_HT * 2 + n * 2048 + k * 1024))
; #define MMA(ai, bj, At, Bx) do { __builtin_amdgcn_s_setprio(1); \
;     for (int m = 0; m < 4; ++m) for (int n = 0; n < 2; ++n) for (int k = 0; k < 2; ++k) \
;       acc[ai][bj][m][n] = __builtin_amdgcn_mfma_f32_16x16x32_bf16(Bx[n][k], At[m][k], acc[ai][bj][m][n], 0, 0, 0);     \
;     __builtin_amdgcn_s_setprio(0); } while (0)
; #define WAIT_V(n) asm volatile("s_waitcnt vmcnt(" #n ")" ::: "memory")
; #define WAIT_L(n) asm volatile("s_waitcnt lgkmcnt(" #n ")" ::: "memory")
; #define BAR __builtin_amdgcn_s_barrier()
; #define SCHED __builtin_amdgcn_sched_barrier(0)
; template <int EPI>
; __device__ __forceinline__ void gemm_tile(const bf16* __restrict__ A, int lda, const bf16* __restrict__ Bt, int K,
;                                           int brow, int bcol, const EpiArgs& ea, char* shmc, bool has_next, int nbrow, int nbcol, bool first_tile) {
;     ...
;     STB(0, 1, 1, t + 2);
;     WAIT_V(6); BAR; MMA(1, 1, At, B1); BAR;
;     LDB(B0, 1, 0); SCHED; LDA(At, 1, 0); STA(0, 1, 1, t + 2);
;     WAIT_L(8); BAR; WAIT_L(0); MMA(0, 0, At, B0); BAR; SCHED;
;     LDB(B1, 1, 1); STB(1, 0, 0, t + 3);
;     BAR; WAIT_L(0); MMA(0, 1, At, B1); BAR;
;     LDA(At, 1, 1); STA(1, 0, 0, t + 3);
;     BAR; WAIT_L(0); MMA(1, 0, At, B0); BAR; SCHED;
;     STB(1, 1, 1, t + 3);
;     WAIT_V(6); BAR; MMA(1, 1, At, B1); BAR;
;   }
;   { LDB(B0, 0, 0); LDA(At, 0, 0); STA(1, 1, 1, nt - 1);
;     BAR; WAIT_L(0); MMA(0, 0, At, B0); BAR;
;     LDB(B1, 0, 1); BAR; WAIT_L(0); MMA(0, 1, At, B1); BAR;
;     LDA(At, 0, 1); WAIT_V(4); BAR; WAIT_L(0); MMA(1, 0, At, B0); MMA(1, 1, At, B1); BAR; }
	s_waitcnt lgkmcnt(0)
	s_waitcnt lgkmcnt(0)
	v_mfma_f32_16x16x32_bf16 v[60:63], v[160:163], v[176:179], v[60:63]
	v_mfma_f32_16x16x32_bf16 v[56:59], v[168:171], v[176:179], v[56:59]
	v_mfma_f32_16x16x32_bf16 v[52:55], v[160:163], v[184:187], v[52:55]
	v_mfma_f32_16x16x32_bf16 v[48:51], v[168:171], v[184:187], v[48:51]
	v_mfma_f32_16x16x32_bf16 v[44:47], v[160:163], v[192:195], v[44:47]
	v_mfma_f32_16x16x32_bf16 v[40:43], v[168:171], v[192:195], v[40:43]
	v_mfma_f32_16x16x32_bf16 v[36:39], v[160:163], v[200:203], v[36:39]
	v_mfma_f32_16x16x32_bf16 v[32:35], v[168:171], v[200:203], v[32:35]
	v_mfma_f32_16x16x32_bf16 v[60:63], v[164:167], v[180:183], v[60:63]
	v_mfma_f32_16x16x32_bf16 v[56:59], v[172:175], v[180:183], v[56:59]
	v_mfma_f32_16x16x32_bf16 v[52:55], v[164:167], v[188:191], v[52:55]
	v_mfma_f32_16x16x32_bf16 v[48:51], v[172:175], v[188:191], v[48:51]
	v_mfma_f32_16x16x32_bf16 v[44:47], v[164:167], v[196:199], v[44:47]
	v_mfma_f32_16x16x32_bf16 v[40:43], v[172:175], v[196:199], v[40:43]
	v_mfma_f32_16x16x32_bf16 v[36:39], v[164:167], v[204:207], v[36:39]
	v_mfma_f32_16x16x32_bf16 v[32:35], v[172:175], v[204:207], v[32:35]
	s_barrier
	s_add_u32 s80, s18, 0xfffd0080
	s_addc_u32 s81, s19, -1
	s_mov_b32 m0, s63
	s_nop 0
	v_lshl_add_u64 v[160:161], v[134:135], 0, s[80:81]
	global_load_lds_dwordx4 v[160:161], off
	s_mov_b32 m0, s66
	v_lshl_add_u64 v[160:161], v[160:161], 0, s[8:9]
	global_load_lds_dwordx4 v[160:161], off
	s_waitcnt vmcnt(6)
	s_barrier
	v_mfma_f32_16x16x32_bf16 v[28:31], v[208:211], v[176:179], v[28:31]
	v_mfma_f32_16x16x32_bf16 v[24:27], v[216:219], v[176:179], v[24:27]
	v_mfma_f32_16x16x32_bf16 v[20:23], v[208:211], v[184:187], v[20:23]
	v_mfma_f32_16x16x32_bf16 v[16:19], v[216:219], v[184:187], v[16:19]
	v_mfma_f32_16x16x32_bf16 v[12:15], v[208:211], v[192:195], v[12:15]
	v_mfma_f32_16x16x32_bf16 v[8:11], v[216:219], v[192:195], v[8:11]
	v_mfma_f32_16x16x32_bf16 v[4:7], v[208:211], v[200:203], v[4:7]
	v_mfma_f32_16x16x32_bf16 v[0:3], v[216:219], v[200:203], v[0:3]
	v_mfma_f32_16x16x32_bf16 v[28:31], v[212:215], v[180:183], v[28:31]
	v_mfma_f32_16x16x32_bf16 v[24:27], v[220:223], v[180:183], v[24:27]
	v_mfma_f32_16x16x32_bf16 v[20:23], v[212:215], v[188:191], v[20:23]
	v_mfma_f32_16x16x32_bf16 v[16:19], v[220:223], v[188:191], v[16:19]
	v_mfma_f32_16x16x32_bf16 v[12:15], v[212:215], v[196:199], v[12:15]
	v_mfma_f32_16x16x32_bf16 v[8:11], v[220:223], v[196:199], v[8:11]
	v_mfma_f32_16x16x32_bf16 v[4:7], v[212:215], v[204:207], v[4:7]
	v_mfma_f32_16x16x32_bf16 v[0:3], v[220:223], v[204:207], v[0:3]
	s_add_i32 s71, s71, 2
	s_add_u32 s18, s18, 0x100
	s_addc_u32 s19, s19, 0
	s_cmp_lt_u32 s71, 8
	s_barrier
	s_cbranch_scc1 .LBB0_291
	s_mov_b64 s[18:19], 0x60580
	s_mov_b32 m0, s72
	ds_read_b128 v[160:163], v137
	ds_read_b128 v[164:167], v138
	ds_read_b128 v[168:171], v139
	ds_read_b128 v[172:175], v140
	ds_read_b128 v[176:179], v158
	ds_read_b128 v[180:183], v158 offset:1024
	ds_read_b128 v[184:187], v158 offset:2048
	ds_read_b128 v[188:191], v158 offset:3072
	ds_read_b128 v[192:195], v158 offset:4096
	ds_read_b128 v[196:199], v158 offset:5120
	ds_read_b128 v[200:203], v158 offset:6144
	ds_read_b128 v[204:207], v158 offset:7168
	s_nop 0
	v_lshl_add_u64 v[132:133], v[132:133], 0, s[18:19]
	global_load_lds_dwordx4 v[132:133], off
	v_lshl_add_u64 v[132:133], v[132:133], 0, s[10:11]
	s_mov_b32 m0, s62
	s_nop 0
	global_load_lds_dwordx4 v[132:133], off
	s_barrier
	s_waitcnt lgkmcnt(0)
	s_waitcnt lgkmcnt(0)
	v_mfma_f32_16x16x32_bf16 v[124:127], v[160:163], v[176:179], v[124:127]
	v_mfma_f32_16x16x32_bf16 v[120:123], v[168:171], v[176:179], v[120:123]
	v_mfma_f32_16x16x32_bf16 v[108:111], v[160:163], v[192:195], v[108:111]
	v_mfma_f32_16x16x32_bf16 v[104:107], v[168:171], v[192:195], v[104:107]
	v_mfma_f32_16x16x32_bf16 v[124:127], v[164:167], v[180:183], v[124:127]
	v_mfma_f32_16x16x32_bf16 v[120:123], v[172:175], v[180:183], v[120:123]
	v_mfma_f32_16x16x32_bf16 v[116:119], v[160:163], v[184:187], v[116:119]
	v_mfma_f32_16x16x32_bf16 v[112:115], v[168:171], v[184:187], v[112:115]
	v_mfma_f32_16x16x32_bf16 v[108:111], v[164:167], v[196:199], v[108:111]
	v_mfma_f32_16x16x32_bf16 v[104:107], v[172:175], v[196:199], v[104:107]
	v_mfma_f32_16x16x32_bf16 v[100:103], v[160:163], v[200:203], v[100:103]
	v_mfma_f32_16x16x32_bf16 v[96:99], v[168:171], v[200:203], v[96:99]
	v_mfma_f32_16x16x32_bf16 v[132:135], v[164:167], v[188:191], v[116:119]
	v_mfma_f32_16x16x32_bf16 v[208:211], v[172:175], v[188:191], v[112:115]
	v_mfma_f32_16x16x32_bf16 v[212:215], v[164:167], v[204:207], v[100:103]
	v_mfma_f32_16x16x32_bf16 v[216:219], v[172:175], v[204:207], v[96:99]
	s_barrier
	s_nop 1
	ds_read_b128 v[96:99], v141
	ds_read_b128 v[100:103], v142
	ds_read_b128 v[112:115], v143
	ds_read_b128 v[116:119], v144
	s_barrier
	s_waitcnt lgkmcnt(0)
	s_waitcnt lgkmcnt(0)
	v_mfma_f32_16x16x32_bf16 v[92:95], v[96:99], v[176:179], v[92:95]
	v_mfma_f32_16x16x32_bf16 v[88:91], v[112:115], v[176:179], v[88:91]
	v_mfma_f32_16x16x32_bf16 v[76:79], v[96:99], v[192:195], v[76:79]
	v_mfma_f32_16x16x32_bf16 v[72:75], v[112:115], v[192:195], v[72:75]
	v_mfma_f32_16x16x32_bf16 v[68:71], v[96:99], v[200:203], v[68:71]
	v_mfma_f32_16x16x32_bf16 v[64:67], v[112:115], v[200:203], v[64:67]
	v_mfma_f32_16x16x32_bf16 v[92:95], v[100:103], v[180:183], v[92:95]
	v_mfma_f32_16x16x32_bf16 v[88:91], v[116:119], v[180:183], v[88:91]
	v_mfma_f32_16x16x32_bf16 v[84:87], v[96:99], v[184:187], v[84:87]
	v_mfma_f32_16x16x32_bf16 v[80:83], v[112:115], v[184:187], v[80:83]
	v_mfma_f32_16x16x32_bf16 v[76:79], v[100:103], v[196:199], v[76:79]
	v_mfma_f32_16x16x32_bf16 v[72:75], v[116:119], v[196:199], v[72:75]
	v_mfma_f32_16x16x32_bf16 v[68:71], v[100:103], v[204:207], v[68:71]
	v_mfma_f32_16x16x32_bf16 v[64:67], v[116:119], v[204:207], v[64:67]
	v_mfma_f32_16x16x32_bf16 v[176:179], v[100:103], v[188:191], v[84:87]
	v_mfma_f32_16x16x32_bf16 v[180:183], v[116:119], v[188:191], v[80:83]
	s_barrier
; #define LDA(dst, b, h) for (int m = 0; m < 4; ++m) for (int k = 0; k < 2; ++k) \
;     dst[m][k] = *reinterpret_cast<const bf16x8*>(aRd + (((b) * 2 + (h)) * G_HT * 2 + m * 2048 + k * 1024))
; #define LDB(dst, b, h) for (int n = 0; n < 2; ++n) for (int k = 0; k < 2; ++k) \
;     dst[n][k] = *reinterpret_cast<const bf16x8*>(bRd + (((b) * 2 + (h)) * G_HT * 2 + n * 2048 + k * 1024))
; #define MMA(ai, bj, At, Bx) do { __builtin_amdgcn_s_setprio(1); \
;     for (int m = 0; m < 4; ++m) for (int n = 0; n < 2; ++n) for (int k = 0; k < 2; ++k) \
;       acc[ai][bj][m][n] = __builtin_amdgcn_mfma_f32_16x16x32_bf16(Bx[n][k], At[m][k], acc[ai][bj][m][n], 0, 0, 0);     \
;     __builtin_amdgcn_s_setprio(0); } while (0)
; #define WAIT_V(n) asm volatile("s_waitcnt vmcnt(" #n ")" ::: "memory")
; #define WAIT_L(n) asm volatile("s_waitcnt lgkmcnt(" #n ")" ::: "memory")
; #define BAR __builtin_amdgcn_s_barrier()
; template <int EPI>
; __device__ __forceinline__ void gemm_tile(const bf16* __restrict__ A, int lda, const bf16* __restrict__ Bt, int K,
;                                           int brow, int bcol, const EpiArgs& ea, char* shmc, bool has_next, int nbrow, int nbcol, bool first_tile) {
;     ...
;     LDA(At, 0, 1); WAIT_V(4); BAR; WAIT_L(0); MMA(1, 0, At, B0); MMA(1, 1, At, B1); BAR; }
;   { LDB(B0, 1, 0); LDA(At, 1, 0); WAIT_V(2); BAR; WAIT_L(0); MMA(0, 0, At, B0); BAR;
;     LDB(B1, 1, 1); WAIT_V(0); BAR; WAIT_L(0); MMA(0, 1, At, B1); BAR;
	s_nop 0
	ds_read_b128 v[80:83], v158 offset:16384
	ds_read_b128 v[84:87], v158 offset:17408
	ds_read_b128 v[184:187], v158 offset:18432
	ds_read_b128 v[188:191], v158 offset:19456
	ds_read_b128 v[192:195], v158 offset:20480
	ds_read_b128 v[196:199], v158 offset:21504
	ds_read_b128 v[200:203], v158 offset:22528
	ds_read_b128 v[204:207], v158 offset:23552
	s_waitcnt vmcnt(4)
	s_barrier
	s_waitcnt lgkmcnt(0)
	s_waitcnt lgkmcnt(0)
	v_mfma_f32_16x16x32_bf16 v[44:47], v[160:163], v[192:195], v[44:47]
	v_mfma_f32_16x16x32_bf16 v[40:43], v[168:171], v[192:195], v[40:43]
	v_mfma_f32_16x16x32_bf16 v[60:63], v[160:163], v[80:83], v[60:63]
	v_mfma_f32_16x16x32_bf16 v[56:59], v[168:171], v[80:83], v[56:59]
	v_mfma_f32_16x16x32_bf16 v[52:55], v[160:163], v[184:187], v[52:55]
	v_mfma_f32_16x16x32_bf16 v[48:51], v[168:171], v[184:187], v[48:51]
	v_mfma_f32_16x16x32_bf16 v[44:47], v[164:167], v[196:199], v[44:47]
	v_mfma_f32_16x16x32_bf16 v[40:43], v[172:175], v[196:199], v[40:43]
	v_mfma_f32_16x16x32_bf16 v[36:39], v[160:163], v[200:203], v[36:39]
	v_mfma_f32_16x16x32_bf16 v[32:35], v[168:171], v[200:203], v[32:35]
	v_mfma_f32_16x16x32_bf16 v[220:223], v[164:167], v[84:87], v[60:63]
	v_mfma_f32_16x16x32_bf16 v[224:227], v[172:175], v[84:87], v[56:59]
	v_mfma_f32_16x16x32_bf16 v[228:231], v[164:167], v[188:191], v[52:55]
	v_mfma_f32_16x16x32_bf16 v[232:235], v[172:175], v[188:191], v[48:51]
	v_mfma_f32_16x16x32_bf16 v[160:163], v[164:167], v[204:207], v[36:39]
	v_mfma_f32_16x16x32_bf16 v[164:167], v[172:175], v[204:207], v[32:35]
	v_mfma_f32_16x16x32_bf16 v[28:31], v[96:99], v[80:83], v[28:31]
	v_mfma_f32_16x16x32_bf16 v[24:27], v[112:115], v[80:83], v[24:27]
	v_mfma_f32_16x16x32_bf16 v[12:15], v[96:99], v[192:195], v[12:15]
	v_mfma_f32_16x16x32_bf16 v[8:11], v[112:115], v[192:195], v[8:11]
	v_mfma_f32_16x16x32_bf16 v[28:31], v[100:103], v[84:87], v[28:31]
	v_mfma_f32_16x16x32_bf16 v[24:27], v[116:119], v[84:87], v[24:27]
	v_mfma_f32_16x16x32_bf16 v[20:23], v[96:99], v[184:187], v[20:23]
	v_mfma_f32_16x16x32_bf16 v[16:19], v[112:115], v[184:187], v[16:19]
	v_mfma_f32_16x16x32_bf16 v[12:15], v[100:103], v[196:199], v[12:15]
	v_mfma_f32_16x16x32_bf16 v[8:11], v[116:119], v[196:199], v[8:11]
	v_mfma_f32_16x16x32_bf16 v[4:7], v[96:99], v[200:203], v[4:7]
	v_mfma_f32_16x16x32_bf16 v[0:3], v[112:115], v[200:203], v[0:3]
	v_mfma_f32_16x16x32_bf16 v[168:171], v[100:103], v[188:191], v[20:23]
	v_mfma_f32_16x16x32_bf16 v[172:175], v[116:119], v[188:191], v[16:19]
	v_mfma_f32_16x16x32_bf16 v[184:187], v[100:103], v[204:207], v[4:7]
	v_mfma_f32_16x16x32_bf16 v[188:191], v[116:119], v[204:207], v[0:3]
	s_barrier
	s_nop 1
	ds_read_b128 v[0:3], v145
	ds_read_b128 v[4:7], v146
	ds_read_b128 v[192:195], v147
	ds_read_b128 v[196:199], v148
	ds_read_b128 v[16:19], v158 offset:32768
	ds_read_b128 v[20:23], v158 offset:33792
	ds_read_b128 v[32:35], v158 offset:34816
	ds_read_b128 v[36:39], v158 offset:35840
	ds_read_b128 v[56:59], v158 offset:36864
	ds_read_b128 v[60:63], v158 offset:37888
	ds_read_b128 v[200:203], v158 offset:38912
	ds_read_b128 v[204:207], v158 offset:39936
	s_waitcnt vmcnt(2)
	s_barrier
	s_waitcnt lgkmcnt(0)
	s_waitcnt lgkmcnt(0)
	v_mfma_f32_16x16x32_bf16 v[48:51], v[0:3], v[16:19], v[124:127]
	v_mfma_f32_16x16x32_bf16 v[112:115], v[4:7], v[20:23], v[48:51]
	v_mfma_f32_16x16x32_bf16 v[48:51], v[192:195], v[16:19], v[120:123]
	v_mfma_f32_16x16x32_bf16 v[116:119], v[196:199], v[20:23], v[48:51]
	v_mfma_f32_16x16x32_bf16 v[48:51], v[0:3], v[32:35], v[132:135]
	v_mfma_f32_16x16x32_bf16 v[96:99], v[4:7], v[36:39], v[48:51]
	v_mfma_f32_16x16x32_bf16 v[48:51], v[192:195], v[32:35], v[208:211]
	v_mfma_f32_16x16x32_bf16 v[100:103], v[196:199], v[36:39], v[48:51]
	v_mfma_f32_16x16x32_bf16 v[48:51], v[0:3], v[56:59], v[108:111]
	v_mfma_f32_16x16x32_bf16 v[80:83], v[4:7], v[60:63], v[48:51]
	v_mfma_f32_16x16x32_bf16 v[48:51], v[192:195], v[56:59], v[104:107]
	v_mfma_f32_16x16x32_bf16 v[84:87], v[196:199], v[60:63], v[48:51]
	v_mfma_f32_16x16x32_bf16 v[48:51], v[0:3], v[200:203], v[212:215]
	v_mfma_f32_16x16x32_bf16 v[52:55], v[192:195], v[200:203], v[216:219]
	v_mfma_f32_16x16x32_bf16 v[48:51], v[4:7], v[204:207], v[48:51]
	v_mfma_f32_16x16x32_bf16 v[52:55], v[196:199], v[204:207], v[52:55]
	s_barrier
; #define LDA(dst, b, h) for (int m = 0; m < 4; ++m) for (int k = 0; k < 2; ++k) \
;     dst[m][k] = *reinterpret_cast<const bf16x8*>(aRd + (((b) * 2 + (h)) * G_HT * 2 + m * 2048 + k * 1024))
; #define LDB(dst, b, h) for (int n = 0; n < 2; ++n) for (int k = 0; k < 2; ++k) \
;     dst[n][k] = *reinterpret_cast<const bf16x8*>(bRd + (((b) * 2 + (h)) * G_HT * 2 + n * 2048 + k * 1024))
; #define MMA(ai, bj, At, Bx) do { __builtin_amdgcn_s_setprio(1); \
;     for (int m = 0; m < 4; ++m) for (int n = 0; n < 2; ++n) for (int k = 0; k < 2; ++k) \
;       acc[ai][bj][m][n] = __builtin_amdgcn_mfma_f32_16x16x32_bf16(Bx[n][k], At[m][k], acc[ai][bj][m][n], 0, 0, 0);     \
;     __builtin_amdgcn_s_setprio(0); } while (0)
; #define WAIT_V(n) asm volatile("s_waitcnt vmcnt(" #n ")" ::: "memory")
; #define WAIT_L(n) asm volatile("s_waitcnt lgkmcnt(" #n ")" ::: "memory")
; #define BAR __builtin_amdgcn_s_barrier()
; template <int EPI>
; __device__ __forceinline__ void gemm_tile(const bf16* __restrict__ A, int lda, const bf16* __restrict__ Bt, int K,
;                                           int brow, int bcol, const EpiArgs& ea, char* shmc, bool has_next, int nbrow, int nbcol, bool first_tile) {
;     ...
;     LDB(B1, 1, 1); WAIT_V(0); BAR; WAIT_L(0); MMA(0, 1, At, B1); BAR;
;     LDA(At, 1, 1); BAR; WAIT_L(0); MMA(1, 0, At, B0); MMA(1, 1, At, B1); BAR; }
;   if (wr == 0) BAR;
	ds_read_b128 v[132:135], v149
	ds_read_b128 v[208:211], v150
	ds_read_b128 v[212:215], v151
	ds_read_b128 v[216:219], v152
	s_waitcnt vmcnt(0)
	s_barrier
	s_waitcnt lgkmcnt(0)
	s_waitcnt lgkmcnt(0)
	v_mfma_f32_16x16x32_bf16 v[92:95], v[132:135], v[16:19], v[92:95]
	v_mfma_f32_16x16x32_bf16 v[16:19], v[212:215], v[16:19], v[88:91]
	v_mfma_f32_16x16x32_bf16 v[124:127], v[216:219], v[20:23], v[16:19]
	v_mfma_f32_16x16x32_bf16 v[16:19], v[132:135], v[32:35], v[176:179]
	v_mfma_f32_16x16x32_bf16 v[104:107], v[208:211], v[36:39], v[16:19]
	v_mfma_f32_16x16x32_bf16 v[16:19], v[212:215], v[32:35], v[180:183]
	v_mfma_f32_16x16x32_bf16 v[108:111], v[216:219], v[36:39], v[16:19]
	v_mfma_f32_16x16x32_bf16 v[16:19], v[132:135], v[56:59], v[76:79]
	v_mfma_f32_16x16x32_bf16 v[88:91], v[208:211], v[60:63], v[16:19]
	v_mfma_f32_16x16x32_bf16 v[16:19], v[212:215], v[56:59], v[72:75]
	v_mfma_f32_16x16x32_bf16 v[120:123], v[208:211], v[20:23], v[92:95]
	v_mfma_f32_16x16x32_bf16 v[92:95], v[216:219], v[60:63], v[16:19]
	v_mfma_f32_16x16x32_bf16 v[16:19], v[132:135], v[200:203], v[68:71]
	v_mfma_f32_16x16x32_bf16 v[56:59], v[208:211], v[204:207], v[16:19]
	v_mfma_f32_16x16x32_bf16 v[16:19], v[212:215], v[200:203], v[64:67]
	v_mfma_f32_16x16x32_bf16 v[60:63], v[216:219], v[204:207], v[16:19]
	s_barrier
	ds_read_b128 v[76:79], v158 offset:49152
	ds_read_b128 v[176:179], v158 offset:50176
	ds_read_b128 v[180:183], v158 offset:51200
	ds_read_b128 v[200:203], v158 offset:52224
	ds_read_b128 v[204:207], v158 offset:53248
	ds_read_b128 v[236:239], v158 offset:54272
	ds_read_b128 v[240:243], v158 offset:55296
	ds_read_b128 v[244:247], v158 offset:56320
	s_barrier
	s_waitcnt lgkmcnt(0)
	s_waitcnt lgkmcnt(0)
	v_mfma_f32_16x16x32_bf16 v[16:19], v[0:3], v[76:79], v[220:223]
	v_mfma_f32_16x16x32_bf16 v[64:67], v[4:7], v[176:179], v[16:19]
	v_mfma_f32_16x16x32_bf16 v[16:19], v[192:195], v[76:79], v[224:227]
	v_mfma_f32_16x16x32_bf16 v[68:71], v[196:199], v[176:179], v[16:19]
	v_mfma_f32_16x16x32_bf16 v[16:19], v[0:3], v[180:183], v[228:231]
	v_mfma_f32_16x16x32_bf16 v[32:35], v[4:7], v[200:203], v[16:19]
	v_mfma_f32_16x16x32_bf16 v[16:19], v[192:195], v[180:183], v[232:235]
	v_mfma_f32_16x16x32_bf16 v[36:39], v[196:199], v[200:203], v[16:19]
	v_mfma_f32_16x16x32_bf16 v[16:19], v[0:3], v[204:207], v[44:47]
	v_mfma_f32_16x16x32_bf16 v[0:3], v[0:3], v[240:243], v[160:163]
	v_mfma_f32_16x16x32_bf16 v[16:19], v[4:7], v[236:239], v[16:19]
	v_mfma_f32_16x16x32_bf16 v[20:23], v[192:195], v[204:207], v[40:43]
	v_mfma_f32_16x16x32_bf16 v[0:3], v[4:7], v[244:247], v[0:3]
	v_mfma_f32_16x16x32_bf16 v[4:7], v[192:195], v[240:243], v[164:167]
	v_mfma_f32_16x16x32_bf16 v[20:23], v[196:199], v[236:239], v[20:23]
	v_mfma_f32_16x16x32_bf16 v[4:7], v[196:199], v[244:247], v[4:7]
	v_mfma_f32_16x16x32_bf16 v[24:27], v[212:215], v[76:79], v[24:27]
	v_mfma_f32_16x16x32_bf16 v[28:31], v[132:135], v[76:79], v[28:31]
	v_mfma_f32_16x16x32_bf16 v[76:79], v[216:219], v[176:179], v[24:27]
	v_mfma_f32_16x16x32_bf16 v[24:27], v[132:135], v[180:183], v[168:171]
	v_mfma_f32_16x16x32_bf16 v[40:43], v[208:211], v[200:203], v[24:27]
	v_mfma_f32_16x16x32_bf16 v[24:27], v[212:215], v[180:183], v[172:175]
	v_mfma_f32_16x16x32_bf16 v[12:15], v[132:135], v[204:207], v[12:15]
	v_mfma_f32_16x16x32_bf16 v[8:11], v[212:215], v[204:207], v[8:11]
	v_mfma_f32_16x16x32_bf16 v[72:75], v[208:211], v[176:179], v[28:31]
	v_mfma_f32_16x16x32_bf16 v[44:47], v[216:219], v[200:203], v[24:27]
	v_mfma_f32_16x16x32_bf16 v[24:27], v[208:211], v[236:239], v[12:15]
	v_mfma_f32_16x16x32_bf16 v[28:31], v[216:219], v[236:239], v[8:11]
	v_mfma_f32_16x16x32_bf16 v[8:11], v[132:135], v[240:243], v[184:187]
	v_mfma_f32_16x16x32_bf16 v[12:15], v[212:215], v[240:243], v[188:191]
	v_mfma_f32_16x16x32_bf16 v[8:11], v[208:211], v[244:247], v[8:11]
	v_mfma_f32_16x16x32_bf16 v[12:15], v[216:219], v[244:247], v[12:15]
	s_barrier
	s_and_saveexec_b64 s[18:19], s[4:5]
	s_cbranch_execz .LBB0_294
	s_barrier

; #define STA(b, h, half, kt) STAGE(((b) * 2 + (h)) * G_HT * 2, pA, ((size_t)(half) * G_HALF * lda + (size_t)(kt) * G_BK) * 2, lda)
; #define STB(b, h, half, kt) STAGE((4 + (b) * 2 + (h)) * G_HT * 2, pB, ((size_t)(half) * G_HALF * K + (size_t)(kt) * G_BK) * 2, K)
; #define LDA(dst, b, h) for (int m = 0; m < 4; ++m) for (int k = 0; k < 2; ++k) \
;     dst[m][k] = *reinterpret_cast<const bf16x8*>(aRd + (((b) * 2 + (h)) * G_HT * 2 + m * 2048 + k * 1024))
; #define LDB(dst, b, h) for (int n = 0; n < 2; ++n) for (int k = 0; k < 2; ++k) \
;     dst[n][k] = *reinterpret_cast<const bf16x8*>(bRd + (((b) * 2 + (h)) * G_HT * 2 + n * 2048 + k * 1024))
; #define MMA(ai, bj, At, Bx) do { __builtin_amdgcn_s_setprio(1); \
;     for (int m = 0; m < 4; ++m) for (int n = 0; n < 2; ++n) for (int k = 0; k < 2; ++k) \
;       acc[ai][bj][m][n] = __builtin_amdgcn_mfma_f32_16x16x32_bf16(Bx[n][k], At[m][k], acc[ai][bj][m][n], 0, 0, 0);     \
;     __builtin_amdgcn_s_setprio(0); } while (0)
; #define WAIT_V(n) asm volatile("s_waitcnt vmcnt(" #n ")" ::: "memory")
; #define WAIT_L(n) asm volatile("s_waitcnt lgkmcnt(" #n ")" ::: "memory")
; #define BAR __builtin_amdgcn_s_barrier()
; #define SCHED __builtin_amdgcn_sched_barrier(0)
; template <int EPI>
; __device__ __forceinline__ void gemm_tile(const bf16* __restrict__ A, int lda, const bf16* __restrict__ Bt, int K,
;                                           int brow, int bcol, const EpiArgs& ea, char* shmc, bool has_next, int nbrow, int nbcol, bool first_tile) {
;     ...
;     LDB(B0, 0, 0); SCHED; LDA(At, 0, 0); STA(1, 1, 1, t + 1);
;     WAIT_L(8); BAR; WAIT_L(0); MMA(0, 0, At, B0); BAR; SCHED;
;     LDB(B1, 0, 1); STB(0, 0, 0, t + 2);
;     BAR; WAIT_L(0); MMA(0, 1, At, B1); BAR;
;     LDA(At, 0, 1); STA(0, 0, 0, t + 2);
;     BAR; WAIT_L(0); MMA(1, 0, At, B0); BAR; SCHED;
;     STB(0, 1, 1, t + 2);
;     WAIT_V(6); BAR; MMA(1, 1, At, B1); BAR;
.LBB0_310:
	ds_read_b128 v[160:163], v138
	ds_read_b128 v[164:167], v139
	ds_read_b128 v[168:171], v140
	ds_read_b128 v[172:175], v141
	s_add_u32 s84, s30, 0xffffff80
	s_addc_u32 s85, s31, -1
	s_mov_b32 m0, s81
	ds_read_b128 v[176:179], v158
	ds_read_b128 v[180:183], v158 offset:1024
	ds_read_b128 v[184:187], v158 offset:2048
	ds_read_b128 v[188:191], v158 offset:3072
	ds_read_b128 v[192:195], v158 offset:4096
	ds_read_b128 v[196:199], v158 offset:5120
	ds_read_b128 v[200:203], v158 offset:6144
	ds_read_b128 v[204:207], v158 offset:7168
	s_nop 0
	v_lshl_add_u64 v[208:209], v[134:135], 0, s[84:85]
	global_load_lds_dwordx4 v[208:209], off
	s_mov_b32 m0, s71
	v_lshl_add_u64 v[208:209], v[208:209], 0, s[8:9]
	global_load_lds_dwordx4 v[208:209], off
	s_waitcnt lgkmcnt(8)
	s_barrier
	s_waitcnt lgkmcnt(0)
	s_waitcnt lgkmcnt(0)
	v_mfma_f32_16x16x32_bf16 v[124:127], v[160:163], v[176:179], v[124:127]
	v_mfma_f32_16x16x32_bf16 v[120:123], v[168:171], v[176:179], v[120:123]
	v_mfma_f32_16x16x32_bf16 v[116:119], v[160:163], v[184:187], v[116:119]
	v_mfma_f32_16x16x32_bf16 v[112:115], v[168:171], v[184:187], v[112:115]
	v_mfma_f32_16x16x32_bf16 v[108:111], v[160:163], v[192:195], v[108:111]
	v_mfma_f32_16x16x32_bf16 v[104:107], v[168:171], v[192:195], v[104:107]
	v_mfma_f32_16x16x32_bf16 v[100:103], v[160:163], v[200:203], v[100:103]
	v_mfma_f32_16x16x32_bf16 v[96:99], v[168:171], v[200:203], v[96:99]
	v_mfma_f32_16x16x32_bf16 v[124:127], v[164:167], v[180:183], v[124:127]
	v_mfma_f32_16x16x32_bf16 v[120:123], v[172:175], v[180:183], v[120:123]
	v_mfma_f32_16x16x32_bf16 v[116:119], v[164:167], v[188:191], v[116:119]
	v_mfma_f32_16x16x32_bf16 v[112:115], v[172:175], v[188:191], v[112:115]
	v_mfma_f32_16x16x32_bf16 v[108:111], v[164:167], v[196:199], v[108:111]
	v_mfma_f32_16x16x32_bf16 v[104:107], v[172:175], v[196:199], v[104:107]
	v_mfma_f32_16x16x32_bf16 v[100:103], v[164:167], v[204:207], v[100:103]
	v_mfma_f32_16x16x32_bf16 v[96:99], v[172:175], v[204:207], v[96:99]
	s_barrier
	s_add_u32 s84, s30, 0xfffa0000
	s_addc_u32 s85, s31, -1
	s_mov_b64 s[86:87], s[84:85]
	s_mov_b32 m0, s74
	ds_read_b128 v[208:211], v142
	ds_read_b128 v[212:215], v143
	ds_read_b128 v[216:219], v144
	ds_read_b128 v[220:223], v145
	s_nop 0
	v_lshl_add_u64 v[224:225], v[136:137], 0, s[86:87]
	global_load_lds_dwordx4 v[224:225], off
	s_mov_b32 m0, s75
	v_lshl_add_u64 v[224:225], v[224:225], 0, s[6:7]
	global_load_lds_dwordx4 v[224:225], off
	s_barrier
	s_waitcnt lgkmcnt(0)
	s_waitcnt lgkmcnt(0)
	v_mfma_f32_16x16x32_bf16 v[92:95], v[208:211], v[176:179], v[92:95]
	v_mfma_f32_16x16x32_bf16 v[88:91], v[216:219], v[176:179], v[88:91]
	v_mfma_f32_16x16x32_bf16 v[84:87], v[208:211], v[184:187], v[84:87]
	v_mfma_f32_16x16x32_bf16 v[80:83], v[216:219], v[184:187], v[80:83]
	v_mfma_f32_16x16x32_bf16 v[76:79], v[208:211], v[192:195], v[76:79]
	v_mfma_f32_16x16x32_bf16 v[72:75], v[216:219], v[192:195], v[72:75]
	v_mfma_f32_16x16x32_bf16 v[68:71], v[208:211], v[200:203], v[68:71]
	v_mfma_f32_16x16x32_bf16 v[64:67], v[216:219], v[200:203], v[64:67]
	v_mfma_f32_16x16x32_bf16 v[92:95], v[212:215], v[180:183], v[92:95]
	v_mfma_f32_16x16x32_bf16 v[88:91], v[220:223], v[180:183], v[88:91]
	v_mfma_f32_16x16x32_bf16 v[84:87], v[212:215], v[188:191], v[84:87]
	v_mfma_f32_16x16x32_bf16 v[80:83], v[220:223], v[188:191], v[80:83]
	v_mfma_f32_16x16x32_bf16 v[76:79], v[212:215], v[196:199], v[76:79]
	v_mfma_f32_16x16x32_bf16 v[72:75], v[220:223], v[196:199], v[72:75]
	v_mfma_f32_16x16x32_bf16 v[68:71], v[212:215], v[204:207], v[68:71]
	v_mfma_f32_16x16x32_bf16 v[64:67], v[220:223], v[204:207], v[64:67]
	s_mov_b32 m0, s29
	s_barrier
	ds_read_b128 v[176:179], v158 offset:16384
	ds_read_b128 v[180:183], v158 offset:17408
	ds_read_b128 v[184:187], v158 offset:18432
	ds_read_b128 v[188:191], v158 offset:19456
	ds_read_b128 v[192:195], v158 offset:20480
	ds_read_b128 v[196:199], v158 offset:21504
	ds_read_b128 v[200:203], v158 offset:22528
	ds_read_b128 v[204:207], v158 offset:23552
	s_nop 0
	v_lshl_add_u64 v[224:225], v[134:135], 0, s[84:85]
	global_load_lds_dwordx4 v[224:225], off
	s_mov_b32 m0, s82
	v_lshl_add_u64 v[224:225], v[224:225], 0, s[8:9]
	global_load_lds_dwordx4 v[224:225], off
	s_barrier
	s_waitcnt lgkmcnt(0)
	s_waitcnt lgkmcnt(0)
	v_mfma_f32_16x16x32_bf16 v[60:63], v[160:163], v[176:179], v[60:63]
	v_mfma_f32_16x16x32_bf16 v[56:59], v[168:171], v[176:179], v[56:59]
	v_mfma_f32_16x16x32_bf16 v[52:55], v[160:163], v[184:187], v[52:55]
	v_mfma_f32_16x16x32_bf16 v[48:51], v[168:171], v[184:187], v[48:51]
	v_mfma_f32_16x16x32_bf16 v[44:47], v[160:163], v[192:195], v[44:47]
	v_mfma_f32_16x16x32_bf16 v[40:43], v[168:171], v[192:195], v[40:43]
	v_mfma_f32_16x16x32_bf16 v[36:39], v[160:163], v[200:203], v[36:39]
	v_mfma_f32_16x16x32_bf16 v[32:35], v[168:171], v[200:203], v[32:35]
	v_mfma_f32_16x16x32_bf16 v[60:63], v[164:167], v[180:183], v[60:63]
	v_mfma_f32_16x16x32_bf16 v[56:59], v[172:175], v[180:183], v[56:59]
	v_mfma_f32_16x16x32_bf16 v[52:55], v[164:167], v[188:191], v[52:55]
	v_mfma_f32_16x16x32_bf16 v[48:51], v[172:175], v[188:191], v[48:51]
	v_mfma_f32_16x16x32_bf16 v[44:47], v[164:167], v[196:199], v[44:47]
	v_mfma_f32_16x16x32_bf16 v[40:43], v[172:175], v[196:199], v[40:43]
	v_mfma_f32_16x16x32_bf16 v[36:39], v[164:167], v[204:207], v[36:39]
	v_mfma_f32_16x16x32_bf16 v[32:35], v[172:175], v[204:207], v[32:35]
	s_barrier
	s_add_u32 s84, s30, 0xfffc0000
	s_addc_u32 s85, s31, -1
	s_mov_b32 m0, s77
	s_nop 0
	v_lshl_add_u64 v[160:161], v[136:137], 0, s[84:85]
	global_load_lds_dwordx4 v[160:161], off
	s_mov_b32 m0, s79
	v_lshl_add_u64 v[160:161], v[160:161], 0, s[6:7]
	global_load_lds_dwordx4 v[160:161], off
	s_waitcnt vmcnt(6)
	s_barrier
; #define STA(b, h, half, kt) STAGE(((b) * 2 + (h)) * G_HT * 2, pA, ((size_t)(half) * G_HALF * lda + (size_t)(kt) * G_BK) * 2, lda)
; #define STB(b, h, half, kt) STAGE((4 + (b) * 2 + (h)) * G_HT * 2, pB, ((size_t)(half) * G_HALF * K + (size_t)(kt) * G_BK) * 2, K)
; #define LDA(dst, b, h) for (int m = 0; m < 4; ++m) for (int k = 0; k < 2; ++k) \
;     dst[m][k] = *reinterpret_cast<const bf16x8*>(aRd + (((b) * 2 + (h)) * G_HT * 2 + m * 2048 + k * 1024))
; #define LDB(dst, b, h) for (int n = 0; n < 2; ++n) for (int k = 0; k < 2; ++k) \
;     dst[n][k] = *reinterpret_cast<const bf16x8*>(bRd + (((b) * 2 + (h)) * G_HT * 2 + n * 2048 + k * 1024))
; #define MMA(ai, bj, At, Bx) do { __builtin_amdgcn_s_setprio(1); \
;     for (int m = 0; m < 4; ++m) for (int n = 0; n < 2; ++n) for (int k = 0; k < 2; ++k) \
;       acc[ai][bj][m][n] = __builtin_amdgcn_mfma_f32_16x16x32_bf16(Bx[n][k], At[m][k], acc[ai][bj][m][n], 0, 0, 0);     \
;     __builtin_amdgcn_s_setprio(0); } while (0)
; #define WAIT_V(n) asm volatile("s_waitcnt vmcnt(" #n ")" ::: "memory")
; #define WAIT_L(n) asm volatile("s_waitcnt lgkmcnt(" #n ")" ::: "memory")
; #define BAR __builtin_amdgcn_s_barrier()
; #define SCHED __builtin_amdgcn_sched_barrier(0)
; template <int EPI>
; __device__ __forceinline__ void gemm_tile(const bf16* __restrict__ A, int lda, const bf16* __restrict__ Bt, int K,
;                                           int brow, int bcol, const EpiArgs& ea, char* shmc, bool has_next, int nbrow, int nbcol, bool first_tile) {
;     ...
;     WAIT_V(6); BAR; MMA(1, 1, At, B1); BAR;
;     LDB(B0, 1, 0); SCHED; LDA(At, 1, 0); STA(0, 1, 1, t + 2);
;     WAIT_L(8); BAR; WAIT_L(0); MMA(0, 0, At, B0); BAR; SCHED;
;     LDB(B1, 1, 1); STB(1, 0, 0, t + 3);
;     BAR; WAIT_L(0); MMA(0, 1, At, B1); BAR;
;     LDA(At, 1, 1); STA(1, 0, 0, t + 3);
;     BAR; WAIT_L(0); MMA(1, 0, At, B0); BAR; SCHED;
	v_mfma_f32_16x16x32_bf16 v[28:31], v[208:211], v[176:179], v[28:31]
	v_mfma_f32_16x16x32_bf16 v[24:27], v[216:219], v[176:179], v[24:27]
	v_mfma_f32_16x16x32_bf16 v[20:23], v[208:211], v[184:187], v[20:23]
	v_mfma_f32_16x16x32_bf16 v[16:19], v[216:219], v[184:187], v[16:19]
	v_mfma_f32_16x16x32_bf16 v[12:15], v[208:211], v[192:195], v[12:15]
	v_mfma_f32_16x16x32_bf16 v[8:11], v[216:219], v[192:195], v[8:11]
	v_mfma_f32_16x16x32_bf16 v[4:7], v[208:211], v[200:203], v[4:7]
	v_mfma_f32_16x16x32_bf16 v[0:3], v[216:219], v[200:203], v[0:3]
	v_mfma_f32_16x16x32_bf16 v[28:31], v[212:215], v[180:183], v[28:31]
	v_mfma_f32_16x16x32_bf16 v[24:27], v[220:223], v[180:183], v[24:27]
	v_mfma_f32_16x16x32_bf16 v[20:23], v[212:215], v[188:191], v[20:23]
	v_mfma_f32_16x16x32_bf16 v[16:19], v[220:223], v[188:191], v[16:19]
	v_mfma_f32_16x16x32_bf16 v[12:15], v[212:215], v[196:199], v[12:15]
	v_mfma_f32_16x16x32_bf16 v[8:11], v[220:223], v[196:199], v[8:11]
	v_mfma_f32_16x16x32_bf16 v[4:7], v[212:215], v[204:207], v[4:7]
	v_mfma_f32_16x16x32_bf16 v[0:3], v[220:223], v[204:207], v[0:3]
	s_barrier
	ds_read_b128 v[160:163], v146
	ds_read_b128 v[164:167], v147
	ds_read_b128 v[168:171], v148
	ds_read_b128 v[172:175], v149
	s_mov_b64 s[84:85], s[30:31]
	s_mov_b32 m0, s83
	ds_read_b128 v[176:179], v158 offset:32768
	ds_read_b128 v[180:183], v158 offset:33792
	ds_read_b128 v[184:187], v158 offset:34816
	ds_read_b128 v[188:191], v158 offset:35840
	ds_read_b128 v[192:195], v158 offset:36864
	ds_read_b128 v[196:199], v158 offset:37888
	ds_read_b128 v[200:203], v158 offset:38912
	ds_read_b128 v[204:207], v158 offset:39936
	s_nop 0
	v_lshl_add_u64 v[208:209], v[134:135], 0, s[84:85]
	global_load_lds_dwordx4 v[208:209], off
	s_add_i32 m0, s29, 0x6000
	v_lshl_add_u64 v[208:209], v[208:209], 0, s[8:9]
	global_load_lds_dwordx4 v[208:209], off
	s_waitcnt lgkmcnt(8)
	s_barrier
	s_waitcnt lgkmcnt(0)
	s_waitcnt lgkmcnt(0)
	v_mfma_f32_16x16x32_bf16 v[124:127], v[160:163], v[176:179], v[124:127]
	v_mfma_f32_16x16x32_bf16 v[120:123], v[168:171], v[176:179], v[120:123]
	v_mfma_f32_16x16x32_bf16 v[116:119], v[160:163], v[184:187], v[116:119]
	v_mfma_f32_16x16x32_bf16 v[112:115], v[168:171], v[184:187], v[112:115]
	v_mfma_f32_16x16x32_bf16 v[108:111], v[160:163], v[192:195], v[108:111]
	v_mfma_f32_16x16x32_bf16 v[104:107], v[168:171], v[192:195], v[104:107]
	v_mfma_f32_16x16x32_bf16 v[100:103], v[160:163], v[200:203], v[100:103]
	v_mfma_f32_16x16x32_bf16 v[96:99], v[168:171], v[200:203], v[96:99]
	v_mfma_f32_16x16x32_bf16 v[124:127], v[164:167], v[180:183], v[124:127]
	v_mfma_f32_16x16x32_bf16 v[120:123], v[172:175], v[180:183], v[120:123]
	v_mfma_f32_16x16x32_bf16 v[116:119], v[164:167], v[188:191], v[116:119]
	v_mfma_f32_16x16x32_bf16 v[112:115], v[172:175], v[188:191], v[112:115]
	v_mfma_f32_16x16x32_bf16 v[108:111], v[164:167], v[196:199], v[108:111]
	v_mfma_f32_16x16x32_bf16 v[104:107], v[172:175], v[196:199], v[104:107]
	v_mfma_f32_16x16x32_bf16 v[100:103], v[164:167], v[204:207], v[100:103]
	v_mfma_f32_16x16x32_bf16 v[96:99], v[172:175], v[204:207], v[96:99]
	s_barrier
	s_add_u32 s84, s30, 0xfffa0080
	s_addc_u32 s85, s31, -1
	s_mov_b64 s[86:87], s[84:85]
	s_mov_b32 m0, s67
	ds_read_b128 v[208:211], v150
	ds_read_b128 v[212:215], v151
	ds_read_b128 v[216:219], v152
	ds_read_b128 v[220:223], v153
	s_nop 0
	v_lshl_add_u64 v[224:225], v[136:137], 0, s[86:87]
	global_load_lds_dwordx4 v[224:225], off
	s_mov_b32 m0, s68
	v_lshl_add_u64 v[224:225], v[224:225], 0, s[6:7]
	global_load_lds_dwordx4 v[224:225], off
	s_barrier
	s_waitcnt lgkmcnt(0)
	s_waitcnt lgkmcnt(0)
	v_mfma_f32_16x16x32_bf16 v[92:95], v[208:211], v[176:179], v[92:95]
	v_mfma_f32_16x16x32_bf16 v[88:91], v[216:219], v[176:179], v[88:91]
	v_mfma_f32_16x16x32_bf16 v[84:87], v[208:211], v[184:187], v[84:87]
	v_mfma_f32_16x16x32_bf16 v[80:83], v[216:219], v[184:187], v[80:83]
	v_mfma_f32_16x16x32_bf16 v[76:79], v[208:211], v[192:195], v[76:79]
	v_mfma_f32_16x16x32_bf16 v[72:75], v[216:219], v[192:195], v[72:75]
	v_mfma_f32_16x16x32_bf16 v[68:71], v[208:211], v[200:203], v[68:71]
	v_mfma_f32_16x16x32_bf16 v[64:67], v[216:219], v[200:203], v[64:67]
	v_mfma_f32_16x16x32_bf16 v[92:95], v[212:215], v[180:183], v[92:95]
	v_mfma_f32_16x16x32_bf16 v[88:91], v[220:223], v[180:183], v[88:91]
	v_mfma_f32_16x16x32_bf16 v[84:87], v[212:215], v[188:191], v[84:87]
	v_mfma_f32_16x16x32_bf16 v[80:83], v[220:223], v[188:191], v[80:83]
	v_mfma_f32_16x16x32_bf16 v[76:79], v[212:215], v[196:199], v[76:79]
	v_mfma_f32_16x16x32_bf16 v[72:75], v[220:223], v[196:199], v[72:75]
	v_mfma_f32_16x16x32_bf16 v[68:71], v[212:215], v[204:207], v[68:71]
	v_mfma_f32_16x16x32_bf16 v[64:67], v[220:223], v[204:207], v[64:67]
	s_mov_b32 m0, s69
	s_barrier
	ds_read_b128 v[176:179], v158 offset:49152
	ds_read_b128 v[180:183], v158 offset:50176
	ds_read_b128 v[184:187], v158 offset:51200
	ds_read_b128 v[188:191], v158 offset:52224
	ds_read_b128 v[192:195], v158 offset:53248
	ds_read_b128 v[196:199], v158 offset:54272
	ds_read_b128 v[200:203], v158 offset:55296
	ds_read_b128 v[204:207], v158 offset:56320
	s_nop 0
	v_lshl_add_u64 v[224:225], v[134:135], 0, s[84:85]
	global_load_lds_dwordx4 v[224:225], off
	s_mov_b32 m0, s70
	v_lshl_add_u64 v[224:225], v[224:225], 0, s[8:9]
	global_load_lds_dwordx4 v[224:225], off
	s_barrier
; #define STA(b, h, half, kt) STAGE(((b) * 2 + (h)) * G_HT * 2, pA, ((size_t)(half) * G_HALF * lda + (size_t)(kt) * G_BK) * 2, lda)
; #define STB(b, h, half, kt) STAGE((4 + (b) * 2 + (h)) * G_HT * 2, pB, ((size_t)(half) * G_HALF * K + (size_t)(kt) * G_BK) * 2, K)
; #define LDA(dst, b, h) for (int m = 0; m < 4; ++m) for (int k = 0; k < 2; ++k) \
;     dst[m][k] = *reinterpret_cast<const bf16x8*>(aRd + (((b) * 2 + (h)) * G_HT * 2 + m * 2048 + k * 1024))
; #define LDB(dst, b, h) for (int n = 0; n < 2; ++n) for (int k = 0; k < 2; ++k) \
;     dst[n][k] = *reinterpret_cast<const bf16x8*>(bRd + (((b) * 2 + (h)) * G_HT * 2 + n * 2048 + k * 1024))
; #define MMA(ai, bj, At, Bx) do { __builtin_amdgcn_s_setprio(1); \
;     for (int m = 0; m < 4; ++m) for (int n = 0; n < 2; ++n) for (int k = 0; k < 2; ++k) \
;       acc[ai][bj][m][n] = __builtin_amdgcn_mfma_f32_16x16x32_bf16(Bx[n][k], At[m][k], acc[ai][bj][m][n], 0, 0, 0);     \
;     __builtin_amdgcn_s_setprio(0); } while (0)
; #define WAIT_V(n) asm volatile("s_waitcnt vmcnt(" #n ")" ::: "memory")
; #define WAIT_L(n) asm volatile("s_waitcnt lgkmcnt(" #n ")" ::: "memory")
; #define BAR __builtin_amdgcn_s_barrier()
; #define SCHED __builtin_amdgcn_sched_barrier(0)
; template <int EPI>
; __device__ __forceinline__ void gemm_tile(const bf16* __restrict__ A, int lda, const bf16* __restrict__ Bt, int K,
;                                           int brow, int bcol, const EpiArgs& ea, char* shmc, bool has_next, int nbrow, int nbcol, bool first_tile) {
;     ...
;     STB(0, 1, 1, t + 2);
;     WAIT_V(6); BAR; MMA(1, 1, At, B1); BAR;
;     LDB(B0, 1, 0); SCHED; LDA(At, 1, 0); STA(0, 1, 1, t + 2);
;     WAIT_L(8); BAR; WAIT_L(0); MMA(0, 0, At, B0); BAR; SCHED;
;     LDB(B1, 1, 1); STB(1, 0, 0, t + 3);
;     BAR; WAIT_L(0); MMA(0, 1, At, B1); BAR;
;     LDA(At, 1, 1); STA(1, 0, 0, t + 3);
;     BAR; WAIT_L(0); MMA(1, 0, At, B0); BAR; SCHED;
;     STB(1, 1, 1, t + 3);
;     WAIT_V(6); BAR; MMA(1, 1, At, B1); BAR;
;   }
;   { LDB(B0, 0, 0); LDA(At, 0, 0); STA(1, 1, 1, nt - 1);
;     BAR; WAIT_L(0); MMA(0, 0, At, B0); BAR;
;     LDB(B1, 0, 1); BAR; WAIT_L(0); MMA(0, 1, At, B1); BAR;
;     LDA(At, 0, 1); WAIT_V(4); BAR; WAIT_L(0); MMA(1, 0, At, B0); MMA(1, 1, At, B1); BAR; }
	s_waitcnt lgkmcnt(0)
	s_waitcnt lgkmcnt(0)
	v_mfma_f32_16x16x32_bf16 v[60:63], v[160:163], v[176:179], v[60:63]
	v_mfma_f32_16x16x32_bf16 v[56:59], v[168:171], v[176:179], v[56:59]
	v_mfma_f32_16x16x32_bf16 v[52:55], v[160:163], v[184:187], v[52:55]
	v_mfma_f32_16x16x32_bf16 v[48:51], v[168:171], v[184:187], v[48:51]
	v_mfma_f32_16x16x32_bf16 v[44:47], v[160:163], v[192:195], v[44:47]
	v_mfma_f32_16x16x32_bf16 v[40:43], v[168:171], v[192:195], v[40:43]
	v_mfma_f32_16x16x32_bf16 v[36:39], v[160:163], v[200:203], v[36:39]
	v_mfma_f32_16x16x32_bf16 v[32:35], v[168:171], v[200:203], v[32:35]
	v_mfma_f32_16x16x32_bf16 v[60:63], v[164:167], v[180:183], v[60:63]
	v_mfma_f32_16x16x32_bf16 v[56:59], v[172:175], v[180:183], v[56:59]
	v_mfma_f32_16x16x32_bf16 v[52:55], v[164:167], v[188:191], v[52:55]
	v_mfma_f32_16x16x32_bf16 v[48:51], v[172:175], v[188:191], v[48:51]
	v_mfma_f32_16x16x32_bf16 v[44:47], v[164:167], v[196:199], v[44:47]
	v_mfma_f32_16x16x32_bf16 v[40:43], v[172:175], v[196:199], v[40:43]
	v_mfma_f32_16x16x32_bf16 v[36:39], v[164:167], v[204:207], v[36:39]
	v_mfma_f32_16x16x32_bf16 v[32:35], v[172:175], v[204:207], v[32:35]
	s_barrier
	s_add_u32 s84, s30, 0xfffc0080
	s_addc_u32 s85, s31, -1
	s_mov_b32 m0, s72
	s_nop 0
	v_lshl_add_u64 v[160:161], v[136:137], 0, s[84:85]
	global_load_lds_dwordx4 v[160:161], off
	s_mov_b32 m0, s73
	v_lshl_add_u64 v[160:161], v[160:161], 0, s[6:7]
	global_load_lds_dwordx4 v[160:161], off
	s_waitcnt vmcnt(6)
	s_barrier
	v_mfma_f32_16x16x32_bf16 v[28:31], v[208:211], v[176:179], v[28:31]
	v_mfma_f32_16x16x32_bf16 v[24:27], v[216:219], v[176:179], v[24:27]
	v_mfma_f32_16x16x32_bf16 v[20:23], v[208:211], v[184:187], v[20:23]
	v_mfma_f32_16x16x32_bf16 v[16:19], v[216:219], v[184:187], v[16:19]
	v_mfma_f32_16x16x32_bf16 v[12:15], v[208:211], v[192:195], v[12:15]
	v_mfma_f32_16x16x32_bf16 v[8:11], v[216:219], v[192:195], v[8:11]
	v_mfma_f32_16x16x32_bf16 v[4:7], v[208:211], v[200:203], v[4:7]
	v_mfma_f32_16x16x32_bf16 v[0:3], v[216:219], v[200:203], v[0:3]
	v_mfma_f32_16x16x32_bf16 v[28:31], v[212:215], v[180:183], v[28:31]
	v_mfma_f32_16x16x32_bf16 v[24:27], v[220:223], v[180:183], v[24:27]
	v_mfma_f32_16x16x32_bf16 v[20:23], v[212:215], v[188:191], v[20:23]
	v_mfma_f32_16x16x32_bf16 v[16:19], v[220:223], v[188:191], v[16:19]
	v_mfma_f32_16x16x32_bf16 v[12:15], v[212:215], v[196:199], v[12:15]
	v_mfma_f32_16x16x32_bf16 v[8:11], v[220:223], v[196:199], v[8:11]
	v_mfma_f32_16x16x32_bf16 v[4:7], v[212:215], v[204:207], v[4:7]
	v_mfma_f32_16x16x32_bf16 v[0:3], v[220:223], v[204:207], v[0:3]
	s_add_i32 s80, s80, 2
	s_add_u32 s30, s30, 0x100
	s_addc_u32 s31, s31, 0
	s_cmp_lt_u32 s80, 4
	s_barrier
	s_cbranch_scc1 .LBB0_310
	s_mov_b64 s[30:31], 0x60380
	s_mov_b32 m0, s81
	ds_read_b128 v[160:163], v138
	ds_read_b128 v[164:167], v139
	ds_read_b128 v[168:171], v140
	ds_read_b128 v[172:175], v141
	ds_read_b128 v[176:179], v158
	ds_read_b128 v[180:183], v158 offset:1024
	ds_read_b128 v[184:187], v158 offset:2048
	ds_read_b128 v[188:191], v158 offset:3072
	ds_read_b128 v[192:195], v158 offset:4096
	ds_read_b128 v[196:199], v158 offset:5120
	ds_read_b128 v[200:203], v158 offset:6144
	ds_read_b128 v[204:207], v158 offset:7168
	s_nop 0
	v_lshl_add_u64 v[134:135], v[134:135], 0, s[30:31]
	global_load_lds_dwordx4 v[134:135], off
	v_lshl_add_u64 v[134:135], v[134:135], 0, s[8:9]
	s_mov_b32 m0, s71
	s_nop 0
	global_load_lds_dwordx4 v[134:135], off
	s_barrier
	s_waitcnt lgkmcnt(0)
	s_waitcnt lgkmcnt(0)
	v_mfma_f32_16x16x32_bf16 v[124:127], v[160:163], v[176:179], v[124:127]
	v_mfma_f32_16x16x32_bf16 v[120:123], v[168:171], v[176:179], v[120:123]
	v_mfma_f32_16x16x32_bf16 v[108:111], v[160:163], v[192:195], v[108:111]
	v_mfma_f32_16x16x32_bf16 v[104:107], v[168:171], v[192:195], v[104:107]
	v_mfma_f32_16x16x32_bf16 v[124:127], v[164:167], v[180:183], v[124:127]
	v_mfma_f32_16x16x32_bf16 v[120:123], v[172:175], v[180:183], v[120:123]
	v_mfma_f32_16x16x32_bf16 v[116:119], v[160:163], v[184:187], v[116:119]
	v_mfma_f32_16x16x32_bf16 v[112:115], v[168:171], v[184:187], v[112:115]
	v_mfma_f32_16x16x32_bf16 v[108:111], v[164:167], v[196:199], v[108:111]
	v_mfma_f32_16x16x32_bf16 v[104:107], v[172:175], v[196:199], v[104:107]
	v_mfma_f32_16x16x32_bf16 v[100:103], v[160:163], v[200:203], v[100:103]
	v_mfma_f32_16x16x32_bf16 v[96:99], v[168:171], v[200:203], v[96:99]
	v_mfma_f32_16x16x32_bf16 v[134:137], v[164:167], v[188:191], v[116:119]
	v_mfma_f32_16x16x32_bf16 v[208:211], v[172:175], v[188:191], v[112:115]
	v_mfma_f32_16x16x32_bf16 v[212:215], v[164:167], v[204:207], v[100:103]
	v_mfma_f32_16x16x32_bf16 v[216:219], v[172:175], v[204:207], v[96:99]
	s_barrier
	s_nop 1
	ds_read_b128 v[96:99], v142
	ds_read_b128 v[100:103], v143
	ds_read_b128 v[112:115], v144
	ds_read_b128 v[116:119], v145
	s_barrier
	s_waitcnt lgkmcnt(0)
	s_waitcnt lgkmcnt(0)
	v_mfma_f32_16x16x32_bf16 v[92:95], v[96:99], v[176:179], v[92:95]
	v_mfma_f32_16x16x32_bf16 v[88:91], v[112:115], v[176:179], v[88:91]
	v_mfma_f32_16x16x32_bf16 v[76:79], v[96:99], v[192:195], v[76:79]
	v_mfma_f32_16x16x32_bf16 v[72:75], v[112:115], v[192:195], v[72:75]
	v_mfma_f32_16x16x32_bf16 v[68:71], v[96:99], v[200:203], v[68:71]
	v_mfma_f32_16x16x32_bf16 v[64:67], v[112:115], v[200:203], v[64:67]
	v_mfma_f32_16x16x32_bf16 v[92:95], v[100:103], v[180:183], v[92:95]
	v_mfma_f32_16x16x32_bf16 v[88:91], v[116:119], v[180:183], v[88:91]
	v_mfma_f32_16x16x32_bf16 v[84:87], v[96:99], v[184:187], v[84:87]
	v_mfma_f32_16x16x32_bf16 v[80:83], v[112:115], v[184:187], v[80:83]
	v_mfma_f32_16x16x32_bf16 v[76:79], v[100:103], v[196:199], v[76:79]
	v_mfma_f32_16x16x32_bf16 v[72:75], v[116:119], v[196:199], v[72:75]
	v_mfma_f32_16x16x32_bf16 v[68:71], v[100:103], v[204:207], v[68:71]
	v_mfma_f32_16x16x32_bf16 v[64:67], v[116:119], v[204:207], v[64:67]
	v_mfma_f32_16x16x32_bf16 v[176:179], v[100:103], v[188:191], v[84:87]
	v_mfma_f32_16x16x32_bf16 v[180:183], v[116:119], v[188:191], v[80:83]
	s_barrier
; #define LDA(dst, b, h) for (int m = 0; m < 4; ++m) for (int k = 0; k < 2; ++k) \
;     dst[m][k] = *reinterpret_cast<const bf16x8*>(aRd + (((b) * 2 + (h)) * G_HT * 2 + m * 2048 + k * 1024))
; #define LDB(dst, b, h) for (int n = 0; n < 2; ++n) for (int k = 0; k < 2; ++k) \
;     dst[n][k] = *reinterpret_cast<const bf16x8*>(bRd + (((b) * 2 + (h)) * G_HT * 2 + n * 2048 + k * 1024))
; #define MMA(ai, bj, At, Bx) do { __builtin_amdgcn_s_setprio(1); \
;     for (int m = 0; m < 4; ++m) for (int n = 0; n < 2; ++n) for (int k = 0; k < 2; ++k) \
;       acc[ai][bj][m][n] = __builtin_amdgcn_mfma_f32_16x16x32_bf16(Bx[n][k], At[m][k], acc[ai][bj][m][n], 0, 0, 0);     \
;     __builtin_amdgcn_s_setprio(0); } while (0)
; #define WAIT_V(n) asm volatile("s_waitcnt vmcnt(" #n ")" ::: "memory")
; #define WAIT_L(n) asm volatile("s_waitcnt lgkmcnt(" #n ")" ::: "memory")
; #define BAR __builtin_amdgcn_s_barrier()
; template <int EPI>
; __device__ __forceinline__ void gemm_tile(const bf16* __restrict__ A, int lda, const bf16* __restrict__ Bt, int K,
;                                           int brow, int bcol, const EpiArgs& ea, char* shmc, bool has_next, int nbrow, int nbcol, bool first_tile) {
;     ...
;     LDA(At, 0, 1); WAIT_V(4); BAR; WAIT_L(0); MMA(1, 0, At, B0); MMA(1, 1, At, B1); BAR; }
;   { LDB(B0, 1, 0); LDA(At, 1, 0); WAIT_V(2); BAR; WAIT_L(0); MMA(0, 0, At, B0); BAR;
;     LDB(B1, 1, 1); WAIT_V(0); BAR; WAIT_L(0); MMA(0, 1, At, B1); BAR;
	s_nop 0
	ds_read_b128 v[80:83], v158 offset:16384
	ds_read_b128 v[84:87], v158 offset:17408
	ds_read_b128 v[184:187], v158 offset:18432
	ds_read_b128 v[188:191], v158 offset:19456
	ds_read_b128 v[192:195], v158 offset:20480
	ds_read_b128 v[196:199], v158 offset:21504
	ds_read_b128 v[200:203], v158 offset:22528
	ds_read_b128 v[204:207], v158 offset:23552
	s_waitcnt vmcnt(4)
	s_barrier
	s_waitcnt lgkmcnt(0)
	s_waitcnt lgkmcnt(0)
	v_mfma_f32_16x16x32_bf16 v[36:39], v[160:163], v[200:203], v[36:39]
	v_mfma_f32_16x16x32_bf16 v[32:35], v[168:171], v[200:203], v[32:35]
	v_mfma_f32_16x16x32_bf16 v[60:63], v[160:163], v[80:83], v[60:63]
	v_mfma_f32_16x16x32_bf16 v[56:59], v[168:171], v[80:83], v[56:59]
	v_mfma_f32_16x16x32_bf16 v[52:55], v[160:163], v[184:187], v[52:55]
	v_mfma_f32_16x16x32_bf16 v[48:51], v[168:171], v[184:187], v[48:51]
	v_mfma_f32_16x16x32_bf16 v[44:47], v[160:163], v[192:195], v[44:47]
	v_mfma_f32_16x16x32_bf16 v[40:43], v[168:171], v[192:195], v[40:43]
	v_mfma_f32_16x16x32_bf16 v[36:39], v[164:167], v[204:207], v[36:39]
	v_mfma_f32_16x16x32_bf16 v[32:35], v[172:175], v[204:207], v[32:35]
	v_mfma_f32_16x16x32_bf16 v[220:223], v[164:167], v[84:87], v[60:63]
	v_mfma_f32_16x16x32_bf16 v[224:227], v[172:175], v[84:87], v[56:59]
	v_mfma_f32_16x16x32_bf16 v[228:231], v[164:167], v[188:191], v[52:55]
	v_mfma_f32_16x16x32_bf16 v[232:235], v[172:175], v[188:191], v[48:51]
	v_mfma_f32_16x16x32_bf16 v[236:239], v[164:167], v[196:199], v[44:47]
	v_mfma_f32_16x16x32_bf16 v[240:243], v[172:175], v[196:199], v[40:43]
	v_mfma_f32_16x16x32_bf16 v[20:23], v[96:99], v[184:187], v[20:23]
	v_mfma_f32_16x16x32_bf16 v[16:19], v[112:115], v[184:187], v[16:19]
	v_mfma_f32_16x16x32_bf16 v[4:7], v[96:99], v[200:203], v[4:7]
	v_mfma_f32_16x16x32_bf16 v[28:31], v[96:99], v[80:83], v[28:31]
	v_mfma_f32_16x16x32_bf16 v[24:27], v[112:115], v[80:83], v[24:27]
	v_mfma_f32_16x16x32_bf16 v[20:23], v[100:103], v[188:191], v[20:23]
	v_mfma_f32_16x16x32_bf16 v[16:19], v[116:119], v[188:191], v[16:19]
	v_mfma_f32_16x16x32_bf16 v[12:15], v[96:99], v[192:195], v[12:15]
	v_mfma_f32_16x16x32_bf16 v[8:11], v[112:115], v[192:195], v[8:11]
	v_mfma_f32_16x16x32_bf16 v[4:7], v[100:103], v[204:207], v[4:7]
	v_mfma_f32_16x16x32_bf16 v[0:3], v[112:115], v[200:203], v[0:3]
	v_mfma_f32_16x16x32_bf16 v[160:163], v[100:103], v[84:87], v[28:31]
	v_mfma_f32_16x16x32_bf16 v[164:167], v[116:119], v[84:87], v[24:27]
	v_mfma_f32_16x16x32_bf16 v[168:171], v[100:103], v[196:199], v[12:15]
	v_mfma_f32_16x16x32_bf16 v[172:175], v[116:119], v[196:199], v[8:11]
	v_mfma_f32_16x16x32_bf16 v[184:187], v[116:119], v[204:207], v[0:3]
	s_barrier
	s_nop 0
	ds_read_b128 v[0:3], v146
	ds_read_b128 v[8:11], v147
	ds_read_b128 v[12:15], v148
	ds_read_b128 v[188:191], v149
	ds_read_b128 v[24:27], v158 offset:32768
	ds_read_b128 v[28:31], v158 offset:33792
	ds_read_b128 v[40:43], v158 offset:34816
	ds_read_b128 v[44:47], v158 offset:35840
	ds_read_b128 v[56:59], v158 offset:36864
	ds_read_b128 v[60:63], v158 offset:37888
	ds_read_b128 v[192:195], v158 offset:38912
	ds_read_b128 v[196:199], v158 offset:39936
	s_waitcnt vmcnt(2)
	s_barrier
	s_waitcnt lgkmcnt(0)
	s_waitcnt lgkmcnt(0)
	v_mfma_f32_16x16x32_bf16 v[48:51], v[0:3], v[24:27], v[124:127]
	v_mfma_f32_16x16x32_bf16 v[112:115], v[8:11], v[28:31], v[48:51]
	v_mfma_f32_16x16x32_bf16 v[48:51], v[12:15], v[24:27], v[120:123]
	v_mfma_f32_16x16x32_bf16 v[116:119], v[188:191], v[28:31], v[48:51]
	v_mfma_f32_16x16x32_bf16 v[48:51], v[0:3], v[40:43], v[134:137]
	v_mfma_f32_16x16x32_bf16 v[96:99], v[8:11], v[44:47], v[48:51]
	v_mfma_f32_16x16x32_bf16 v[48:51], v[12:15], v[40:43], v[208:211]
	v_mfma_f32_16x16x32_bf16 v[100:103], v[188:191], v[44:47], v[48:51]
	v_mfma_f32_16x16x32_bf16 v[48:51], v[0:3], v[56:59], v[108:111]
	v_mfma_f32_16x16x32_bf16 v[80:83], v[8:11], v[60:63], v[48:51]
	v_mfma_f32_16x16x32_bf16 v[48:51], v[12:15], v[56:59], v[104:107]
	v_mfma_f32_16x16x32_bf16 v[84:87], v[188:191], v[60:63], v[48:51]
	v_mfma_f32_16x16x32_bf16 v[48:51], v[0:3], v[192:195], v[212:215]
	v_mfma_f32_16x16x32_bf16 v[52:55], v[12:15], v[192:195], v[216:219]
	v_mfma_f32_16x16x32_bf16 v[48:51], v[8:11], v[196:199], v[48:51]
	v_mfma_f32_16x16x32_bf16 v[52:55], v[188:191], v[196:199], v[52:55]
	s_barrier
; #define LDA(dst, b, h) for (int m = 0; m < 4; ++m) for (int k = 0; k < 2; ++k) \
;     dst[m][k] = *reinterpret_cast<const bf16x8*>(aRd + (((b) * 2 + (h)) * G_HT * 2 + m * 2048 + k * 1024))
; #define LDB(dst, b, h) for (int n = 0; n < 2; ++n) for (int k = 0; k < 2; ++k) \
;     dst[n][k] = *reinterpret_cast<const bf16x8*>(bRd + (((b) * 2 + (h)) * G_HT * 2 + n * 2048 + k * 1024))
; #define MMA(ai, bj, At, Bx) do { __builtin_amdgcn_s_setprio(1); \
;     for (int m = 0; m < 4; ++m) for (int n = 0; n < 2; ++n) for (int k = 0; k < 2; ++k) \
;       acc[ai][bj][m][n] = __builtin_amdgcn_mfma_f32_16x16x32_bf16(Bx[n][k], At[m][k], acc[ai][bj][m][n], 0, 0, 0);     \
;     __builtin_amdgcn_s_setprio(0); } while (0)
; #define WAIT_V(n) asm volatile("s_waitcnt vmcnt(" #n ")" ::: "memory")
; #define WAIT_L(n) asm volatile("s_waitcnt lgkmcnt(" #n ")" ::: "memory")
; #define BAR __builtin_amdgcn_s_barrier()
; template <int EPI>
; __device__ __forceinline__ void gemm_tile(const bf16* __restrict__ A, int lda, const bf16* __restrict__ Bt, int K,
;                                           int brow, int bcol, const EpiArgs& ea, char* shmc, bool has_next, int nbrow, int nbcol, bool first_tile) {
;     ...
;     LDB(B1, 1, 1); WAIT_V(0); BAR; WAIT_L(0); MMA(0, 1, At, B1); BAR;
;     LDA(At, 1, 1); BAR; WAIT_L(0); MMA(1, 0, At, B0); MMA(1, 1, At, B1); BAR; }
;   if (wr == 0) BAR;
	ds_read_b128 v[134:137], v150
	ds_read_b128 v[200:203], v151
	ds_read_b128 v[204:207], v152
	ds_read_b128 v[208:211], v153
	s_waitcnt vmcnt(0)
	s_barrier
	s_waitcnt lgkmcnt(0)
	s_waitcnt lgkmcnt(0)
	v_mfma_f32_16x16x32_bf16 v[92:95], v[134:137], v[24:27], v[92:95]
	v_mfma_f32_16x16x32_bf16 v[24:27], v[204:207], v[24:27], v[88:91]
	v_mfma_f32_16x16x32_bf16 v[124:127], v[208:211], v[28:31], v[24:27]
	v_mfma_f32_16x16x32_bf16 v[24:27], v[134:137], v[40:43], v[176:179]
	v_mfma_f32_16x16x32_bf16 v[104:107], v[200:203], v[44:47], v[24:27]
	v_mfma_f32_16x16x32_bf16 v[24:27], v[204:207], v[40:43], v[180:183]
	v_mfma_f32_16x16x32_bf16 v[108:111], v[208:211], v[44:47], v[24:27]
	v_mfma_f32_16x16x32_bf16 v[24:27], v[134:137], v[56:59], v[76:79]
	v_mfma_f32_16x16x32_bf16 v[88:91], v[200:203], v[60:63], v[24:27]
	v_mfma_f32_16x16x32_bf16 v[24:27], v[204:207], v[56:59], v[72:75]
	v_mfma_f32_16x16x32_bf16 v[120:123], v[200:203], v[28:31], v[92:95]
	v_mfma_f32_16x16x32_bf16 v[92:95], v[208:211], v[60:63], v[24:27]
	v_mfma_f32_16x16x32_bf16 v[24:27], v[134:137], v[192:195], v[68:71]
	v_mfma_f32_16x16x32_bf16 v[56:59], v[200:203], v[196:199], v[24:27]
	v_mfma_f32_16x16x32_bf16 v[24:27], v[204:207], v[192:195], v[64:67]
	v_mfma_f32_16x16x32_bf16 v[60:63], v[208:211], v[196:199], v[24:27]
	s_barrier
	ds_read_b128 v[68:71], v158 offset:49152
	ds_read_b128 v[176:179], v158 offset:50176
	ds_read_b128 v[180:183], v158 offset:51200
	ds_read_b128 v[192:195], v158 offset:52224
	ds_read_b128 v[196:199], v158 offset:53248
	ds_read_b128 v[212:215], v158 offset:54272
	ds_read_b128 v[216:219], v158 offset:55296
	ds_read_b128 v[244:247], v158 offset:56320
	s_barrier
	s_waitcnt lgkmcnt(0)
	s_waitcnt lgkmcnt(0)
	v_mfma_f32_16x16x32_bf16 v[24:27], v[0:3], v[68:71], v[220:223]
	v_mfma_f32_16x16x32_bf16 v[72:75], v[8:11], v[176:179], v[24:27]
	v_mfma_f32_16x16x32_bf16 v[24:27], v[12:15], v[68:71], v[224:227]
	v_mfma_f32_16x16x32_bf16 v[76:79], v[188:191], v[176:179], v[24:27]
	v_mfma_f32_16x16x32_bf16 v[24:27], v[0:3], v[180:183], v[228:231]
	v_mfma_f32_16x16x32_bf16 v[40:43], v[8:11], v[192:195], v[24:27]
	v_mfma_f32_16x16x32_bf16 v[24:27], v[12:15], v[180:183], v[232:235]
	v_mfma_f32_16x16x32_bf16 v[44:47], v[188:191], v[192:195], v[24:27]
	v_mfma_f32_16x16x32_bf16 v[24:27], v[0:3], v[196:199], v[236:239]
	v_mfma_f32_16x16x32_bf16 v[0:3], v[0:3], v[216:219], v[36:39]
	v_mfma_f32_16x16x32_bf16 v[24:27], v[8:11], v[212:215], v[24:27]
	v_mfma_f32_16x16x32_bf16 v[28:31], v[12:15], v[196:199], v[240:243]
	v_mfma_f32_16x16x32_bf16 v[8:11], v[8:11], v[244:247], v[0:3]
	v_mfma_f32_16x16x32_bf16 v[0:3], v[12:15], v[216:219], v[32:35]
	v_mfma_f32_16x16x32_bf16 v[28:31], v[188:191], v[212:215], v[28:31]
	v_mfma_f32_16x16x32_bf16 v[12:15], v[188:191], v[244:247], v[0:3]
	v_mfma_f32_16x16x32_bf16 v[0:3], v[134:137], v[68:71], v[160:163]
	v_mfma_f32_16x16x32_bf16 v[64:67], v[200:203], v[176:179], v[0:3]
	v_mfma_f32_16x16x32_bf16 v[0:3], v[204:207], v[68:71], v[164:167]
	v_mfma_f32_16x16x32_bf16 v[68:71], v[208:211], v[176:179], v[0:3]
	v_mfma_f32_16x16x32_bf16 v[0:3], v[134:137], v[180:183], v[20:23]
	v_mfma_f32_16x16x32_bf16 v[32:35], v[200:203], v[192:195], v[0:3]
	v_mfma_f32_16x16x32_bf16 v[0:3], v[204:207], v[180:183], v[16:19]
	v_mfma_f32_16x16x32_bf16 v[36:39], v[208:211], v[192:195], v[0:3]
	v_mfma_f32_16x16x32_bf16 v[0:3], v[134:137], v[196:199], v[168:171]
	v_mfma_f32_16x16x32_bf16 v[16:19], v[200:203], v[212:215], v[0:3]
	v_mfma_f32_16x16x32_bf16 v[0:3], v[204:207], v[196:199], v[172:175]
	v_mfma_f32_16x16x32_bf16 v[20:23], v[208:211], v[212:215], v[0:3]
	v_mfma_f32_16x16x32_bf16 v[0:3], v[134:137], v[216:219], v[4:7]
	v_mfma_f32_16x16x32_bf16 v[4:7], v[204:207], v[216:219], v[184:187]
	v_mfma_f32_16x16x32_bf16 v[0:3], v[200:203], v[244:247], v[0:3]
	v_mfma_f32_16x16x32_bf16 v[4:7], v[208:211], v[244:247], v[4:7]
	s_barrier
	s_and_saveexec_b64 s[30:31], s[4:5]
	s_cbranch_execz .LBB0_313
	s_barrier

; #define STA(b, h, half, kt) STAGE(((b) * 2 + (h)) * G_HT * 2, pA, ((size_t)(half) * G_HALF * lda + (size_t)(kt) * G_BK) * 2, lda)
; #define STB(b, h, half, kt) STAGE((4 + (b) * 2 + (h)) * G_HT * 2, pB, ((size_t)(half) * G_HALF * K + (size_t)(kt) * G_BK) * 2, K)
; #define LDA(dst, b, h) for (int m = 0; m < 4; ++m) for (int k = 0; k < 2; ++k) \
;     dst[m][k] = *reinterpret_cast<const bf16x8*>(aRd + (((b) * 2 + (h)) * G_HT * 2 + m * 2048 + k * 1024))
; #define LDB(dst, b, h) for (int n = 0; n < 2; ++n) for (int k = 0; k < 2; ++k) \
;     dst[n][k] = *reinterpret_cast<const bf16x8*>(bRd + (((b) * 2 + (h)) * G_HT * 2 + n * 2048 + k * 1024))
; #define MMA(ai, bj, At, Bx) do { __builtin_amdgcn_s_setprio(1); \
;     for (int m = 0; m < 4; ++m) for (int n = 0; n < 2; ++n) for (int k = 0; k < 2; ++k) \
;       acc[ai][bj][m][n] = __builtin_amdgcn_mfma_f32_16x16x32_bf16(Bx[n][k], At[m][k], acc[ai][bj][m][n], 0, 0, 0);     \
;     __builtin_amdgcn_s_setprio(0); } while (0)
; #define WAIT_V(n) asm volatile("s_waitcnt vmcnt(" #n ")" ::: "memory")
; #define WAIT_L(n) asm volatile("s_waitcnt lgkmcnt(" #n ")" ::: "memory")
; #define BAR __builtin_amdgcn_s_barrier()
; #define SCHED __builtin_amdgcn_sched_barrier(0)
; template <int EPI>
; __device__ __forceinline__ void gemm_tile(const bf16* __restrict__ A, int lda, const bf16* __restrict__ Bt, int K,
;                                           int brow, int bcol, const EpiArgs& ea, char* shmc, bool has_next, int nbrow, int nbcol, bool first_tile) {
;     ...
;     LDB(B0, 0, 0); SCHED; LDA(At, 0, 0); STA(1, 1, 1, t + 1);
;     WAIT_L(8); BAR; WAIT_L(0); MMA(0, 0, At, B0); BAR; SCHED;
;     LDB(B1, 0, 1); STB(0, 0, 0, t + 2);
;     BAR; WAIT_L(0); MMA(0, 1, At, B1); BAR;
;     LDA(At, 0, 1); STA(0, 0, 0, t + 2);
;     BAR; WAIT_L(0); MMA(1, 0, At, B0); BAR; SCHED;
;     STB(0, 1, 1, t + 2);
;     WAIT_V(6); BAR; MMA(1, 1, At, B1); BAR;
.LBB0_654:
	ds_read_b128 v[140:143], v145
	ds_read_b128 v[166:169], v146
	ds_read_b128 v[170:173], v147
	ds_read_b128 v[174:177], v148
	s_add_u32 s42, s14, 0xffffff00
	s_addc_u32 s43, s15, -1
	s_mov_b32 m0, s29
	ds_read_b128 v[178:181], v164
	ds_read_b128 v[182:185], v164 offset:1024
	ds_read_b128 v[186:189], v164 offset:2048
	ds_read_b128 v[190:193], v164 offset:3072
	ds_read_b128 v[194:197], v164 offset:4096
	ds_read_b128 v[198:201], v164 offset:5120
	ds_read_b128 v[202:205], v164 offset:6144
	ds_read_b128 v[206:209], v164 offset:7168
	v_lshl_add_u64 v[210:211], v[136:137], 0, s[42:43]
	global_load_lds_dwordx4 v[210:211], off
	s_mov_b32 m0, s21
	v_lshl_add_u64 v[210:211], v[210:211], 0, s[10:11]
	global_load_lds_dwordx4 v[210:211], off
	s_waitcnt lgkmcnt(8)
	s_barrier
	s_waitcnt lgkmcnt(0)
	v_mfma_f32_16x16x32_bf16 v[124:127], v[140:143], v[178:181], v[124:127]
	v_mfma_f32_16x16x32_bf16 v[120:123], v[170:173], v[178:181], v[120:123]
	v_mfma_f32_16x16x32_bf16 v[116:119], v[140:143], v[186:189], v[116:119]
	v_mfma_f32_16x16x32_bf16 v[112:115], v[170:173], v[186:189], v[112:115]
	v_mfma_f32_16x16x32_bf16 v[108:111], v[140:143], v[194:197], v[108:111]
	v_mfma_f32_16x16x32_bf16 v[104:107], v[170:173], v[194:197], v[104:107]
	v_mfma_f32_16x16x32_bf16 v[100:103], v[140:143], v[202:205], v[100:103]
	v_mfma_f32_16x16x32_bf16 v[96:99], v[170:173], v[202:205], v[96:99]
	v_mfma_f32_16x16x32_bf16 v[124:127], v[166:169], v[182:185], v[124:127]
	v_mfma_f32_16x16x32_bf16 v[120:123], v[174:177], v[182:185], v[120:123]
	v_mfma_f32_16x16x32_bf16 v[116:119], v[166:169], v[190:193], v[116:119]
	v_mfma_f32_16x16x32_bf16 v[112:115], v[174:177], v[190:193], v[112:115]
	v_mfma_f32_16x16x32_bf16 v[108:111], v[166:169], v[198:201], v[108:111]
	v_mfma_f32_16x16x32_bf16 v[104:107], v[174:177], v[198:201], v[104:107]
	v_mfma_f32_16x16x32_bf16 v[100:103], v[166:169], v[206:209], v[100:103]
	v_mfma_f32_16x16x32_bf16 v[96:99], v[174:177], v[206:209], v[96:99]
	s_barrier
	s_add_u32 s42, s14, 0xffefff80
	s_addc_u32 s43, s15, -1
	s_mov_b64 s[48:49], s[42:43]
	s_mov_b32 m0, s24
	ds_read_b128 v[210:213], v149
	ds_read_b128 v[214:217], v150
	ds_read_b128 v[218:221], v151
	ds_read_b128 v[222:225], v152
	v_lshl_add_u64 v[226:227], v[138:139], 0, s[48:49]
	global_load_lds_dwordx4 v[226:227], off
	s_mov_b32 m0, s25
	v_lshl_add_u64 v[226:227], v[226:227], 0, s[10:11]
	global_load_lds_dwordx4 v[226:227], off
	s_barrier
	s_waitcnt lgkmcnt(0)
	v_mfma_f32_16x16x32_bf16 v[92:95], v[210:213], v[178:181], v[92:95]
	v_mfma_f32_16x16x32_bf16 v[88:91], v[218:221], v[178:181], v[88:91]
	v_mfma_f32_16x16x32_bf16 v[84:87], v[210:213], v[186:189], v[84:87]
	v_mfma_f32_16x16x32_bf16 v[80:83], v[218:221], v[186:189], v[80:83]
	v_mfma_f32_16x16x32_bf16 v[76:79], v[210:213], v[194:197], v[76:79]
	v_mfma_f32_16x16x32_bf16 v[72:75], v[218:221], v[194:197], v[72:75]
	v_mfma_f32_16x16x32_bf16 v[68:71], v[210:213], v[202:205], v[68:71]
	v_mfma_f32_16x16x32_bf16 v[64:67], v[218:221], v[202:205], v[64:67]
	v_mfma_f32_16x16x32_bf16 v[92:95], v[214:217], v[182:185], v[92:95]
	v_mfma_f32_16x16x32_bf16 v[88:91], v[222:225], v[182:185], v[88:91]
	v_mfma_f32_16x16x32_bf16 v[84:87], v[214:217], v[190:193], v[84:87]
	v_mfma_f32_16x16x32_bf16 v[80:83], v[222:225], v[190:193], v[80:83]
	v_mfma_f32_16x16x32_bf16 v[76:79], v[214:217], v[198:201], v[76:79]
	v_mfma_f32_16x16x32_bf16 v[72:75], v[222:225], v[198:201], v[72:75]
	v_mfma_f32_16x16x32_bf16 v[68:71], v[214:217], v[206:209], v[68:71]
	v_mfma_f32_16x16x32_bf16 v[64:67], v[222:225], v[206:209], v[64:67]
	s_mov_b32 m0, s1
	s_barrier
	ds_read_b128 v[178:181], v164 offset:16384
	ds_read_b128 v[182:185], v164 offset:17408
	ds_read_b128 v[186:189], v164 offset:18432
	ds_read_b128 v[190:193], v164 offset:19456
	ds_read_b128 v[194:197], v164 offset:20480
	ds_read_b128 v[198:201], v164 offset:21504
	ds_read_b128 v[202:205], v164 offset:22528
	ds_read_b128 v[206:209], v164 offset:23552
	v_lshl_add_u64 v[226:227], v[136:137], 0, s[42:43]
	global_load_lds_dwordx4 v[226:227], off
	s_mov_b32 m0, s30
	v_lshl_add_u64 v[226:227], v[226:227], 0, s[10:11]
	global_load_lds_dwordx4 v[226:227], off
	s_barrier
	s_waitcnt lgkmcnt(0)
	v_mfma_f32_16x16x32_bf16 v[60:63], v[140:143], v[178:181], v[60:63]
	v_mfma_f32_16x16x32_bf16 v[56:59], v[170:173], v[178:181], v[56:59]
	v_mfma_f32_16x16x32_bf16 v[52:55], v[140:143], v[186:189], v[52:55]
	v_mfma_f32_16x16x32_bf16 v[48:51], v[170:173], v[186:189], v[48:51]
	v_mfma_f32_16x16x32_bf16 v[44:47], v[140:143], v[194:197], v[44:47]
	v_mfma_f32_16x16x32_bf16 v[40:43], v[170:173], v[194:197], v[40:43]
	v_mfma_f32_16x16x32_bf16 v[36:39], v[140:143], v[202:205], v[36:39]
	v_mfma_f32_16x16x32_bf16 v[32:35], v[170:173], v[202:205], v[32:35]
	v_mfma_f32_16x16x32_bf16 v[60:63], v[166:169], v[182:185], v[60:63]
	v_mfma_f32_16x16x32_bf16 v[56:59], v[174:177], v[182:185], v[56:59]
	v_mfma_f32_16x16x32_bf16 v[52:55], v[166:169], v[190:193], v[52:55]
	v_mfma_f32_16x16x32_bf16 v[48:51], v[174:177], v[190:193], v[48:51]
	v_mfma_f32_16x16x32_bf16 v[44:47], v[166:169], v[198:201], v[44:47]
	v_mfma_f32_16x16x32_bf16 v[40:43], v[174:177], v[198:201], v[40:43]
	v_mfma_f32_16x16x32_bf16 v[36:39], v[166:169], v[206:209], v[36:39]
	v_mfma_f32_16x16x32_bf16 v[32:35], v[174:177], v[206:209], v[32:35]
	s_barrier
	s_add_u32 s42, s14, 0xffffff80
	s_addc_u32 s43, s15, -1
	s_mov_b64 s[48:49], s[42:43]
	s_mov_b32 m0, s26
	v_lshl_add_u64 v[140:141], v[138:139], 0, s[48:49]
	global_load_lds_dwordx4 v[140:141], off
	s_mov_b32 m0, s27
	v_lshl_add_u64 v[140:141], v[140:141], 0, s[10:11]
	global_load_lds_dwordx4 v[140:141], off
	s_waitcnt vmcnt(6)
	s_barrier
; #define STA(b, h, half, kt) STAGE(((b) * 2 + (h)) * G_HT * 2, pA, ((size_t)(half) * G_HALF * lda + (size_t)(kt) * G_BK) * 2, lda)
; #define STB(b, h, half, kt) STAGE((4 + (b) * 2 + (h)) * G_HT * 2, pB, ((size_t)(half) * G_HALF * K + (size_t)(kt) * G_BK) * 2, K)
; #define LDA(dst, b, h) for (int m = 0; m < 4; ++m) for (int k = 0; k < 2; ++k) \
;     dst[m][k] = *reinterpret_cast<const bf16x8*>(aRd + (((b) * 2 + (h)) * G_HT * 2 + m * 2048 + k * 1024))
; #define LDB(dst, b, h) for (int n = 0; n < 2; ++n) for (int k = 0; k < 2; ++k) \
;     dst[n][k] = *reinterpret_cast<const bf16x8*>(bRd + (((b) * 2 + (h)) * G_HT * 2 + n * 2048 + k * 1024))
; #define MMA(ai, bj, At, Bx) do { __builtin_amdgcn_s_setprio(1); \
;     for (int m = 0; m < 4; ++m) for (int n = 0; n < 2; ++n) for (int k = 0; k < 2; ++k) \
;       acc[ai][bj][m][n] = __builtin_amdgcn_mfma_f32_16x16x32_bf16(Bx[n][k], At[m][k], acc[ai][bj][m][n], 0, 0, 0);     \
;     __builtin_amdgcn_s_setprio(0); } while (0)
; #define WAIT_V(n) asm volatile("s_waitcnt vmcnt(" #n ")" ::: "memory")
; #define WAIT_L(n) asm volatile("s_waitcnt lgkmcnt(" #n ")" ::: "memory")
; #define BAR __builtin_amdgcn_s_barrier()
; #define SCHED __builtin_amdgcn_sched_barrier(0)
; template <int EPI>
; __device__ __forceinline__ void gemm_tile(const bf16* __restrict__ A, int lda, const bf16* __restrict__ Bt, int K,
;                                           int brow, int bcol, const EpiArgs& ea, char* shmc, bool has_next, int nbrow, int nbcol, bool first_tile) {
;     ...
;     WAIT_V(6); BAR; MMA(1, 1, At, B1); BAR;
;     LDB(B0, 1, 0); SCHED; LDA(At, 1, 0); STA(0, 1, 1, t + 2);
;     WAIT_L(8); BAR; WAIT_L(0); MMA(0, 0, At, B0); BAR; SCHED;
;     LDB(B1, 1, 1); STB(1, 0, 0, t + 3);
;     BAR; WAIT_L(0); MMA(0, 1, At, B1); BAR;
;     LDA(At, 1, 1); STA(1, 0, 0, t + 3);
;     BAR; WAIT_L(0); MMA(1, 0, At, B0); BAR; SCHED;
	v_mfma_f32_16x16x32_bf16 v[28:31], v[210:213], v[178:181], v[28:31]
	v_mfma_f32_16x16x32_bf16 v[24:27], v[218:221], v[178:181], v[24:27]
	v_mfma_f32_16x16x32_bf16 v[20:23], v[210:213], v[186:189], v[20:23]
	v_mfma_f32_16x16x32_bf16 v[16:19], v[218:221], v[186:189], v[16:19]
	v_mfma_f32_16x16x32_bf16 v[12:15], v[210:213], v[194:197], v[12:15]
	v_mfma_f32_16x16x32_bf16 v[8:11], v[218:221], v[194:197], v[8:11]
	v_mfma_f32_16x16x32_bf16 v[4:7], v[210:213], v[202:205], v[4:7]
	v_mfma_f32_16x16x32_bf16 v[0:3], v[218:221], v[202:205], v[0:3]
	v_mfma_f32_16x16x32_bf16 v[28:31], v[214:217], v[182:185], v[28:31]
	v_mfma_f32_16x16x32_bf16 v[24:27], v[222:225], v[182:185], v[24:27]
	v_mfma_f32_16x16x32_bf16 v[20:23], v[214:217], v[190:193], v[20:23]
	v_mfma_f32_16x16x32_bf16 v[16:19], v[222:225], v[190:193], v[16:19]
	v_mfma_f32_16x16x32_bf16 v[12:15], v[214:217], v[198:201], v[12:15]
	v_mfma_f32_16x16x32_bf16 v[8:11], v[222:225], v[198:201], v[8:11]
	v_mfma_f32_16x16x32_bf16 v[4:7], v[214:217], v[206:209], v[4:7]
	v_mfma_f32_16x16x32_bf16 v[0:3], v[222:225], v[206:209], v[0:3]
	s_barrier
	ds_read_b128 v[140:143], v153
	ds_read_b128 v[166:169], v154
	ds_read_b128 v[170:173], v155
	ds_read_b128 v[174:177], v156
	s_mov_b32 m0, s31
	ds_read_b128 v[178:181], v164 offset:32768
	ds_read_b128 v[182:185], v164 offset:33792
	ds_read_b128 v[186:189], v164 offset:34816
	ds_read_b128 v[190:193], v164 offset:35840
	ds_read_b128 v[194:197], v164 offset:36864
	ds_read_b128 v[198:201], v164 offset:37888
	ds_read_b128 v[202:205], v164 offset:38912
	ds_read_b128 v[206:209], v164 offset:39936
	v_lshl_add_u64 v[210:211], v[136:137], 0, s[42:43]
	global_load_lds_dwordx4 v[210:211], off
	s_mov_b32 m0, s34
	v_lshl_add_u64 v[210:211], v[210:211], 0, s[10:11]
	global_load_lds_dwordx4 v[210:211], off
	s_waitcnt lgkmcnt(8)
	s_barrier
	s_waitcnt lgkmcnt(0)
	v_mfma_f32_16x16x32_bf16 v[124:127], v[140:143], v[178:181], v[124:127]
	v_mfma_f32_16x16x32_bf16 v[120:123], v[170:173], v[178:181], v[120:123]
	v_mfma_f32_16x16x32_bf16 v[116:119], v[140:143], v[186:189], v[116:119]
	v_mfma_f32_16x16x32_bf16 v[112:115], v[170:173], v[186:189], v[112:115]
	v_mfma_f32_16x16x32_bf16 v[108:111], v[140:143], v[194:197], v[108:111]
	v_mfma_f32_16x16x32_bf16 v[104:107], v[170:173], v[194:197], v[104:107]
	v_mfma_f32_16x16x32_bf16 v[100:103], v[140:143], v[202:205], v[100:103]
	v_mfma_f32_16x16x32_bf16 v[96:99], v[170:173], v[202:205], v[96:99]
	v_mfma_f32_16x16x32_bf16 v[124:127], v[166:169], v[182:185], v[124:127]
	v_mfma_f32_16x16x32_bf16 v[120:123], v[174:177], v[182:185], v[120:123]
	v_mfma_f32_16x16x32_bf16 v[116:119], v[166:169], v[190:193], v[116:119]
	v_mfma_f32_16x16x32_bf16 v[112:115], v[174:177], v[190:193], v[112:115]
	v_mfma_f32_16x16x32_bf16 v[108:111], v[166:169], v[198:201], v[108:111]
	v_mfma_f32_16x16x32_bf16 v[104:107], v[174:177], v[198:201], v[104:107]
	v_mfma_f32_16x16x32_bf16 v[100:103], v[166:169], v[206:209], v[100:103]
	v_mfma_f32_16x16x32_bf16 v[96:99], v[174:177], v[206:209], v[96:99]
	s_barrier
	s_add_u32 s42, s14, 0xfff00000
	s_addc_u32 s43, s15, -1
	s_mov_b64 s[48:49], s[42:43]
	s_mov_b32 m0, s13
	ds_read_b128 v[210:213], v158
	ds_read_b128 v[214:217], v159
	ds_read_b128 v[218:221], v160
	ds_read_b128 v[222:225], v161
	v_lshl_add_u64 v[226:227], v[138:139], 0, s[48:49]
	global_load_lds_dwordx4 v[226:227], off
	s_mov_b32 m0, s18
	v_lshl_add_u64 v[226:227], v[226:227], 0, s[10:11]
	global_load_lds_dwordx4 v[226:227], off
	s_barrier
	s_waitcnt lgkmcnt(0)
	v_mfma_f32_16x16x32_bf16 v[92:95], v[210:213], v[178:181], v[92:95]
	v_mfma_f32_16x16x32_bf16 v[88:91], v[218:221], v[178:181], v[88:91]
	v_mfma_f32_16x16x32_bf16 v[84:87], v[210:213], v[186:189], v[84:87]
	v_mfma_f32_16x16x32_bf16 v[80:83], v[218:221], v[186:189], v[80:83]
	v_mfma_f32_16x16x32_bf16 v[76:79], v[210:213], v[194:197], v[76:79]
	v_mfma_f32_16x16x32_bf16 v[72:75], v[218:221], v[194:197], v[72:75]
	v_mfma_f32_16x16x32_bf16 v[68:71], v[210:213], v[202:205], v[68:71]
	v_mfma_f32_16x16x32_bf16 v[64:67], v[218:221], v[202:205], v[64:67]
	v_mfma_f32_16x16x32_bf16 v[92:95], v[214:217], v[182:185], v[92:95]
	v_mfma_f32_16x16x32_bf16 v[88:91], v[222:225], v[182:185], v[88:91]
	v_mfma_f32_16x16x32_bf16 v[84:87], v[214:217], v[190:193], v[84:87]
	v_mfma_f32_16x16x32_bf16 v[80:83], v[222:225], v[190:193], v[80:83]
	v_mfma_f32_16x16x32_bf16 v[76:79], v[214:217], v[198:201], v[76:79]
	v_mfma_f32_16x16x32_bf16 v[72:75], v[222:225], v[198:201], v[72:75]
	v_mfma_f32_16x16x32_bf16 v[68:71], v[214:217], v[206:209], v[68:71]
	v_mfma_f32_16x16x32_bf16 v[64:67], v[222:225], v[206:209], v[64:67]
	s_mov_b32 m0, s19
	s_barrier
	ds_read_b128 v[178:181], v164 offset:49152
	ds_read_b128 v[182:185], v164 offset:50176
	ds_read_b128 v[186:189], v164 offset:51200
	ds_read_b128 v[190:193], v164 offset:52224
	ds_read_b128 v[194:197], v164 offset:53248
	ds_read_b128 v[198:201], v164 offset:54272
	ds_read_b128 v[202:205], v164 offset:55296
	ds_read_b128 v[206:209], v164 offset:56320
	v_lshl_add_u64 v[226:227], v[136:137], 0, s[42:43]
	global_load_lds_dwordx4 v[226:227], off
	s_mov_b32 m0, s20
	v_lshl_add_u64 v[226:227], v[226:227], 0, s[10:11]
	global_load_lds_dwordx4 v[226:227], off
	s_barrier
; #define STA(b, h, half, kt) STAGE(((b) * 2 + (h)) * G_HT * 2, pA, ((size_t)(half) * G_HALF * lda + (size_t)(kt) * G_BK) * 2, lda)
; #define STB(b, h, half, kt) STAGE((4 + (b) * 2 + (h)) * G_HT * 2, pB, ((size_t)(half) * G_HALF * K + (size_t)(kt) * G_BK) * 2, K)
; #define LDA(dst, b, h) for (int m = 0; m < 4; ++m) for (int k = 0; k < 2; ++k) \
;     dst[m][k] = *reinterpret_cast<const bf16x8*>(aRd + (((b) * 2 + (h)) * G_HT * 2 + m * 2048 + k * 1024))
; #define LDB(dst, b, h) for (int n = 0; n < 2; ++n) for (int k = 0; k < 2; ++k) \
;     dst[n][k] = *reinterpret_cast<const bf16x8*>(bRd + (((b) * 2 + (h)) * G_HT * 2 + n * 2048 + k * 1024))
; #define MMA(ai, bj, At, Bx) do { __builtin_amdgcn_s_setprio(1); \
;     for (int m = 0; m < 4; ++m) for (int n = 0; n < 2; ++n) for (int k = 0; k < 2; ++k) \
;       acc[ai][bj][m][n] = __builtin_amdgcn_mfma_f32_16x16x32_bf16(Bx[n][k], At[m][k], acc[ai][bj][m][n], 0, 0, 0);     \
;     __builtin_amdgcn_s_setprio(0); } while (0)
; #define WAIT_V(n) asm volatile("s_waitcnt vmcnt(" #n ")" ::: "memory")
; #define WAIT_L(n) asm volatile("s_waitcnt lgkmcnt(" #n ")" ::: "memory")
; #define BAR __builtin_amdgcn_s_barrier()
; #define SCHED __builtin_amdgcn_sched_barrier(0)
; template <int EPI>
; __device__ __forceinline__ void gemm_tile(const bf16* __restrict__ A, int lda, const bf16* __restrict__ Bt, int K,
;                                           int brow, int bcol, const EpiArgs& ea, char* shmc, bool has_next, int nbrow, int nbcol, bool first_tile) {
;     ...
;     STB(0, 1, 1, t + 2);
;     WAIT_V(6); BAR; MMA(1, 1, At, B1); BAR;
;     LDB(B0, 1, 0); SCHED; LDA(At, 1, 0); STA(0, 1, 1, t + 2);
;     WAIT_L(8); BAR; WAIT_L(0); MMA(0, 0, At, B0); BAR; SCHED;
;     LDB(B1, 1, 1); STB(1, 0, 0, t + 3);
;     BAR; WAIT_L(0); MMA(0, 1, At, B1); BAR;
;     LDA(At, 1, 1); STA(1, 0, 0, t + 3);
;     BAR; WAIT_L(0); MMA(1, 0, At, B0); BAR; SCHED;
;     STB(1, 1, 1, t + 3);
;     WAIT_V(6); BAR; MMA(1, 1, At, B1); BAR;
;   }
;   { LDB(B0, 0, 0); LDA(At, 0, 0); STA(1, 1, 1, nt - 1);
;     BAR; WAIT_L(0); MMA(0, 0, At, B0); BAR;
;     LDB(B1, 0, 1); BAR; WAIT_L(0); MMA(0, 1, At, B1); BAR;
;     LDA(At, 0, 1); WAIT_V(4); BAR; WAIT_L(0); MMA(1, 0, At, B0); MMA(1, 1, At, B1); BAR; }
	s_waitcnt lgkmcnt(0)
	v_mfma_f32_16x16x32_bf16 v[60:63], v[140:143], v[178:181], v[60:63]
	v_mfma_f32_16x16x32_bf16 v[56:59], v[170:173], v[178:181], v[56:59]
	v_mfma_f32_16x16x32_bf16 v[52:55], v[140:143], v[186:189], v[52:55]
	v_mfma_f32_16x16x32_bf16 v[48:51], v[170:173], v[186:189], v[48:51]
	v_mfma_f32_16x16x32_bf16 v[44:47], v[140:143], v[194:197], v[44:47]
	v_mfma_f32_16x16x32_bf16 v[40:43], v[170:173], v[194:197], v[40:43]
	v_mfma_f32_16x16x32_bf16 v[36:39], v[140:143], v[202:205], v[36:39]
	v_mfma_f32_16x16x32_bf16 v[32:35], v[170:173], v[202:205], v[32:35]
	v_mfma_f32_16x16x32_bf16 v[60:63], v[166:169], v[182:185], v[60:63]
	v_mfma_f32_16x16x32_bf16 v[56:59], v[174:177], v[182:185], v[56:59]
	v_mfma_f32_16x16x32_bf16 v[52:55], v[166:169], v[190:193], v[52:55]
	v_mfma_f32_16x16x32_bf16 v[48:51], v[174:177], v[190:193], v[48:51]
	v_mfma_f32_16x16x32_bf16 v[44:47], v[166:169], v[198:201], v[44:47]
	v_mfma_f32_16x16x32_bf16 v[40:43], v[174:177], v[198:201], v[40:43]
	v_mfma_f32_16x16x32_bf16 v[36:39], v[166:169], v[206:209], v[36:39]
	v_mfma_f32_16x16x32_bf16 v[32:35], v[174:177], v[206:209], v[32:35]
	s_barrier
	s_mov_b64 s[42:43], s[14:15]
	s_mov_b32 m0, s22
	v_lshl_add_u64 v[140:141], v[138:139], 0, s[42:43]
	global_load_lds_dwordx4 v[140:141], off
	s_mov_b32 m0, s23
	v_lshl_add_u64 v[140:141], v[140:141], 0, s[10:11]
	global_load_lds_dwordx4 v[140:141], off
	s_waitcnt vmcnt(6)
	s_barrier
	v_mfma_f32_16x16x32_bf16 v[28:31], v[210:213], v[178:181], v[28:31]
	v_mfma_f32_16x16x32_bf16 v[24:27], v[218:221], v[178:181], v[24:27]
	v_mfma_f32_16x16x32_bf16 v[20:23], v[210:213], v[186:189], v[20:23]
	v_mfma_f32_16x16x32_bf16 v[16:19], v[218:221], v[186:189], v[16:19]
	v_mfma_f32_16x16x32_bf16 v[12:15], v[210:213], v[194:197], v[12:15]
	v_mfma_f32_16x16x32_bf16 v[8:11], v[218:221], v[194:197], v[8:11]
	v_mfma_f32_16x16x32_bf16 v[4:7], v[210:213], v[202:205], v[4:7]
	v_mfma_f32_16x16x32_bf16 v[0:3], v[218:221], v[202:205], v[0:3]
	v_mfma_f32_16x16x32_bf16 v[28:31], v[214:217], v[182:185], v[28:31]
	v_mfma_f32_16x16x32_bf16 v[24:27], v[222:225], v[182:185], v[24:27]
	v_mfma_f32_16x16x32_bf16 v[20:23], v[214:217], v[190:193], v[20:23]
	v_mfma_f32_16x16x32_bf16 v[16:19], v[222:225], v[190:193], v[16:19]
	v_mfma_f32_16x16x32_bf16 v[12:15], v[214:217], v[198:201], v[12:15]
	v_mfma_f32_16x16x32_bf16 v[8:11], v[222:225], v[198:201], v[8:11]
	v_mfma_f32_16x16x32_bf16 v[4:7], v[214:217], v[206:209], v[4:7]
	v_mfma_f32_16x16x32_bf16 v[0:3], v[222:225], v[206:209], v[0:3]
	s_add_i32 s28, s28, 2
	s_add_u32 s14, s14, 0x100
	s_addc_u32 s15, s15, 0
	s_cmp_lt_u32 s28, 60
	s_barrier
	s_cbranch_scc1 .LBB0_654
	s_mov_b64 s[14:15], 0x101f80
	s_mov_b32 m0, s29
	ds_read_b128 v[138:141], v145
	ds_read_b128 v[166:169], v146
	ds_read_b128 v[170:173], v147
	ds_read_b128 v[174:177], v148
	ds_read_b128 v[178:181], v164
	ds_read_b128 v[182:185], v164 offset:1024
	ds_read_b128 v[186:189], v164 offset:2048
	ds_read_b128 v[190:193], v164 offset:3072
	ds_read_b128 v[194:197], v164 offset:4096
	ds_read_b128 v[198:201], v164 offset:5120
	ds_read_b128 v[202:205], v164 offset:6144
	ds_read_b128 v[206:209], v164 offset:7168
	s_nop 0
	v_lshl_add_u64 v[136:137], v[136:137], 0, s[14:15]
	global_load_lds_dwordx4 v[136:137], off
	v_lshl_add_u64 v[136:137], v[136:137], 0, s[10:11]
	s_mov_b32 m0, s21
	s_nop 0
	global_load_lds_dwordx4 v[136:137], off
	s_barrier
	s_waitcnt lgkmcnt(0)
	s_waitcnt lgkmcnt(0)
	v_mfma_f32_16x16x32_bf16 v[124:127], v[138:141], v[178:181], v[124:127]
	v_mfma_f32_16x16x32_bf16 v[116:119], v[138:141], v[186:189], v[116:119]
	v_mfma_f32_16x16x32_bf16 v[112:115], v[170:173], v[186:189], v[112:115]
	v_mfma_f32_16x16x32_bf16 v[100:103], v[138:141], v[202:205], v[100:103]
	v_mfma_f32_16x16x32_bf16 v[96:99], v[170:173], v[202:205], v[96:99]
	v_mfma_f32_16x16x32_bf16 v[124:127], v[166:169], v[182:185], v[124:127]
	v_mfma_f32_16x16x32_bf16 v[120:123], v[170:173], v[178:181], v[120:123]
	v_mfma_f32_16x16x32_bf16 v[116:119], v[166:169], v[190:193], v[116:119]
	v_mfma_f32_16x16x32_bf16 v[112:115], v[174:177], v[190:193], v[112:115]
	v_mfma_f32_16x16x32_bf16 v[108:111], v[138:141], v[194:197], v[108:111]
	v_mfma_f32_16x16x32_bf16 v[104:107], v[170:173], v[194:197], v[104:107]
	v_mfma_f32_16x16x32_bf16 v[100:103], v[166:169], v[206:209], v[100:103]
	v_mfma_f32_16x16x32_bf16 v[96:99], v[174:177], v[206:209], v[96:99]
	v_mfma_f32_16x16x32_bf16 v[210:213], v[174:177], v[182:185], v[120:123]
	v_mfma_f32_16x16x32_bf16 v[214:217], v[166:169], v[198:201], v[108:111]
	v_mfma_f32_16x16x32_bf16 v[218:221], v[174:177], v[198:201], v[104:107]
	s_barrier
	s_nop 0
	ds_read_b128 v[104:107], v149
	ds_read_b128 v[108:111], v150
	ds_read_b128 v[120:123], v151
	ds_read_b128 v[222:225], v152
	s_barrier
	s_waitcnt lgkmcnt(0)
	s_waitcnt lgkmcnt(0)
	v_mfma_f32_16x16x32_bf16 v[84:87], v[104:107], v[186:189], v[84:87]
	v_mfma_f32_16x16x32_bf16 v[80:83], v[120:123], v[186:189], v[80:83]
	v_mfma_f32_16x16x32_bf16 v[68:71], v[104:107], v[202:205], v[68:71]
	v_mfma_f32_16x16x32_bf16 v[92:95], v[104:107], v[178:181], v[92:95]
	v_mfma_f32_16x16x32_bf16 v[88:91], v[120:123], v[178:181], v[88:91]
	v_mfma_f32_16x16x32_bf16 v[84:87], v[108:111], v[190:193], v[84:87]
	v_mfma_f32_16x16x32_bf16 v[80:83], v[222:225], v[190:193], v[80:83]
	v_mfma_f32_16x16x32_bf16 v[76:79], v[104:107], v[194:197], v[76:79]
	v_mfma_f32_16x16x32_bf16 v[72:75], v[120:123], v[194:197], v[72:75]
	v_mfma_f32_16x16x32_bf16 v[68:71], v[108:111], v[206:209], v[68:71]
	v_mfma_f32_16x16x32_bf16 v[64:67], v[120:123], v[202:205], v[64:67]
	v_mfma_f32_16x16x32_bf16 v[226:229], v[108:111], v[182:185], v[92:95]
	v_mfma_f32_16x16x32_bf16 v[178:181], v[222:225], v[182:185], v[88:91]
	v_mfma_f32_16x16x32_bf16 v[182:185], v[108:111], v[198:201], v[76:79]
	v_mfma_f32_16x16x32_bf16 v[186:189], v[222:225], v[198:201], v[72:75]
	v_mfma_f32_16x16x32_bf16 v[190:193], v[222:225], v[206:209], v[64:67]
	s_barrier
; #define LDA(dst, b, h) for (int m = 0; m < 4; ++m) for (int k = 0; k < 2; ++k) \
;     dst[m][k] = *reinterpret_cast<const bf16x8*>(aRd + (((b) * 2 + (h)) * G_HT * 2 + m * 2048 + k * 1024))
; #define LDB(dst, b, h) for (int n = 0; n < 2; ++n) for (int k = 0; k < 2; ++k) \
;     dst[n][k] = *reinterpret_cast<const bf16x8*>(bRd + (((b) * 2 + (h)) * G_HT * 2 + n * 2048 + k * 1024))
; #define MMA(ai, bj, At, Bx) do { __builtin_amdgcn_s_setprio(1); \
;     for (int m = 0; m < 4; ++m) for (int n = 0; n < 2; ++n) for (int k = 0; k < 2; ++k) \
;       acc[ai][bj][m][n] = __builtin_amdgcn_mfma_f32_16x16x32_bf16(Bx[n][k], At[m][k], acc[ai][bj][m][n], 0, 0, 0);     \
;     __builtin_amdgcn_s_setprio(0); } while (0)
; #define WAIT_V(n) asm volatile("s_waitcnt vmcnt(" #n ")" ::: "memory")
; #define WAIT_L(n) asm volatile("s_waitcnt lgkmcnt(" #n ")" ::: "memory")
; #define BAR __builtin_amdgcn_s_barrier()
; template <int EPI>
; __device__ __forceinline__ void gemm_tile(const bf16* __restrict__ A, int lda, const bf16* __restrict__ Bt, int K,
;                                           int brow, int bcol, const EpiArgs& ea, char* shmc, bool has_next, int nbrow, int nbcol, bool first_tile) {
;     ...
;     LDA(At, 0, 1); WAIT_V(4); BAR; WAIT_L(0); MMA(1, 0, At, B0); MMA(1, 1, At, B1); BAR; }
;   { LDB(B0, 1, 0); LDA(At, 1, 0); WAIT_V(2); BAR; WAIT_L(0); MMA(0, 0, At, B0); BAR;
;     LDB(B1, 1, 1); WAIT_V(0); BAR; WAIT_L(0); MMA(0, 1, At, B1); BAR;
	s_nop 0
	ds_read_b128 v[64:67], v164 offset:16384
	ds_read_b128 v[72:75], v164 offset:17408
	ds_read_b128 v[76:79], v164 offset:18432
	ds_read_b128 v[88:91], v164 offset:19456
	ds_read_b128 v[92:95], v164 offset:20480
	ds_read_b128 v[194:197], v164 offset:21504
	ds_read_b128 v[198:201], v164 offset:22528
	ds_read_b128 v[202:205], v164 offset:23552
	s_waitcnt vmcnt(4)
	s_barrier
	s_waitcnt lgkmcnt(0)
	s_waitcnt lgkmcnt(0)
	v_mfma_f32_16x16x32_bf16 v[60:63], v[138:141], v[64:67], v[60:63]
	v_mfma_f32_16x16x32_bf16 v[52:55], v[138:141], v[76:79], v[52:55]
	v_mfma_f32_16x16x32_bf16 v[48:51], v[170:173], v[76:79], v[48:51]
	v_mfma_f32_16x16x32_bf16 v[36:39], v[138:141], v[198:201], v[36:39]
	v_mfma_f32_16x16x32_bf16 v[32:35], v[170:173], v[198:201], v[32:35]
	v_mfma_f32_16x16x32_bf16 v[60:63], v[166:169], v[72:75], v[60:63]
	v_mfma_f32_16x16x32_bf16 v[56:59], v[170:173], v[64:67], v[56:59]
	v_mfma_f32_16x16x32_bf16 v[52:55], v[166:169], v[88:91], v[52:55]
	v_mfma_f32_16x16x32_bf16 v[48:51], v[174:177], v[88:91], v[48:51]
	v_mfma_f32_16x16x32_bf16 v[44:47], v[138:141], v[92:95], v[44:47]
	v_mfma_f32_16x16x32_bf16 v[40:43], v[170:173], v[92:95], v[40:43]
	v_mfma_f32_16x16x32_bf16 v[36:39], v[166:169], v[202:205], v[36:39]
	v_mfma_f32_16x16x32_bf16 v[32:35], v[174:177], v[202:205], v[32:35]
	v_mfma_f32_16x16x32_bf16 v[206:209], v[174:177], v[72:75], v[56:59]
	v_mfma_f32_16x16x32_bf16 v[230:233], v[166:169], v[194:197], v[44:47]
	v_mfma_f32_16x16x32_bf16 v[234:237], v[174:177], v[194:197], v[40:43]
	v_mfma_f32_16x16x32_bf16 v[20:23], v[104:107], v[76:79], v[20:23]
	v_mfma_f32_16x16x32_bf16 v[16:19], v[120:123], v[76:79], v[16:19]
	v_mfma_f32_16x16x32_bf16 v[4:7], v[104:107], v[198:201], v[4:7]
	v_mfma_f32_16x16x32_bf16 v[28:31], v[104:107], v[64:67], v[28:31]
	v_mfma_f32_16x16x32_bf16 v[24:27], v[120:123], v[64:67], v[24:27]
	v_mfma_f32_16x16x32_bf16 v[20:23], v[108:111], v[88:91], v[20:23]
	v_mfma_f32_16x16x32_bf16 v[16:19], v[222:225], v[88:91], v[16:19]
	v_mfma_f32_16x16x32_bf16 v[12:15], v[104:107], v[92:95], v[12:15]
	v_mfma_f32_16x16x32_bf16 v[8:11], v[120:123], v[92:95], v[8:11]
	v_mfma_f32_16x16x32_bf16 v[4:7], v[108:111], v[202:205], v[4:7]
	v_mfma_f32_16x16x32_bf16 v[0:3], v[120:123], v[198:201], v[0:3]
	v_mfma_f32_16x16x32_bf16 v[136:139], v[108:111], v[72:75], v[28:31]
	v_mfma_f32_16x16x32_bf16 v[140:143], v[222:225], v[72:75], v[24:27]
	v_mfma_f32_16x16x32_bf16 v[166:169], v[108:111], v[194:197], v[12:15]
	v_mfma_f32_16x16x32_bf16 v[170:173], v[222:225], v[194:197], v[8:11]
	v_mfma_f32_16x16x32_bf16 v[174:177], v[222:225], v[202:205], v[0:3]
	s_barrier
	s_nop 0
	ds_read_b128 v[0:3], v153
	ds_read_b128 v[8:11], v154
	ds_read_b128 v[12:15], v155
	ds_read_b128 v[194:197], v156
	ds_read_b128 v[24:27], v164 offset:32768
	ds_read_b128 v[28:31], v164 offset:33792
	ds_read_b128 v[40:43], v164 offset:34816
	ds_read_b128 v[44:47], v164 offset:35840
	ds_read_b128 v[56:59], v164 offset:36864
	ds_read_b128 v[64:67], v164 offset:37888
	ds_read_b128 v[198:201], v164 offset:38912
	ds_read_b128 v[202:205], v164 offset:39936
	s_waitcnt vmcnt(2)
	s_barrier
	s_waitcnt lgkmcnt(0)
	s_waitcnt lgkmcnt(0)
	v_mfma_f32_16x16x32_bf16 v[72:75], v[0:3], v[24:27], v[124:127]
	v_mfma_f32_16x16x32_bf16 v[120:123], v[8:11], v[28:31], v[72:75]
	v_mfma_f32_16x16x32_bf16 v[72:75], v[12:15], v[24:27], v[210:213]
	v_mfma_f32_16x16x32_bf16 v[124:127], v[194:197], v[28:31], v[72:75]
	v_mfma_f32_16x16x32_bf16 v[72:75], v[0:3], v[40:43], v[116:119]
	v_mfma_f32_16x16x32_bf16 v[104:107], v[8:11], v[44:47], v[72:75]
	v_mfma_f32_16x16x32_bf16 v[72:75], v[12:15], v[40:43], v[112:115]
	v_mfma_f32_16x16x32_bf16 v[108:111], v[194:197], v[44:47], v[72:75]
	v_mfma_f32_16x16x32_bf16 v[72:75], v[0:3], v[56:59], v[214:217]
	v_mfma_f32_16x16x32_bf16 v[88:91], v[8:11], v[64:67], v[72:75]
	v_mfma_f32_16x16x32_bf16 v[72:75], v[12:15], v[56:59], v[218:221]
	v_mfma_f32_16x16x32_bf16 v[92:95], v[194:197], v[64:67], v[72:75]
	v_mfma_f32_16x16x32_bf16 v[72:75], v[0:3], v[198:201], v[100:103]
	v_mfma_f32_16x16x32_bf16 v[76:79], v[12:15], v[198:201], v[96:99]
	v_mfma_f32_16x16x32_bf16 v[72:75], v[8:11], v[202:205], v[72:75]
	v_mfma_f32_16x16x32_bf16 v[76:79], v[194:197], v[202:205], v[76:79]
	s_barrier
; #define LDA(dst, b, h) for (int m = 0; m < 4; ++m) for (int k = 0; k < 2; ++k) \
;     dst[m][k] = *reinterpret_cast<const bf16x8*>(aRd + (((b) * 2 + (h)) * G_HT * 2 + m * 2048 + k * 1024))
; #define LDB(dst, b, h) for (int n = 0; n < 2; ++n) for (int k = 0; k < 2; ++k) \
;     dst[n][k] = *reinterpret_cast<const bf16x8*>(bRd + (((b) * 2 + (h)) * G_HT * 2 + n * 2048 + k * 1024))
; #define MMA(ai, bj, At, Bx) do { __builtin_amdgcn_s_setprio(1); \
;     for (int m = 0; m < 4; ++m) for (int n = 0; n < 2; ++n) for (int k = 0; k < 2; ++k) \
;       acc[ai][bj][m][n] = __builtin_amdgcn_mfma_f32_16x16x32_bf16(Bx[n][k], At[m][k], acc[ai][bj][m][n], 0, 0, 0);     \
;     __builtin_amdgcn_s_setprio(0); } while (0)
; #define WAIT_V(n) asm volatile("s_waitcnt vmcnt(" #n ")" ::: "memory")
; #define WAIT_L(n) asm volatile("s_waitcnt lgkmcnt(" #n ")" ::: "memory")
; #define BAR __builtin_amdgcn_s_barrier()
; template <int EPI>
; __device__ __forceinline__ void gemm_tile(const bf16* __restrict__ A, int lda, const bf16* __restrict__ Bt, int K,
;                                           int brow, int bcol, const EpiArgs& ea, char* shmc, bool has_next, int nbrow, int nbcol, bool first_tile) {
;     ...
;     LDB(B1, 1, 1); WAIT_V(0); BAR; WAIT_L(0); MMA(0, 1, At, B1); BAR;
;     LDA(At, 1, 1); BAR; WAIT_L(0); MMA(1, 0, At, B0); MMA(1, 1, At, B1); BAR; }
;   if (wr == 0) BAR;
	ds_read_b128 v[210:213], v158
	ds_read_b128 v[214:217], v159
	ds_read_b128 v[218:221], v160
	ds_read_b128 v[222:225], v161
	s_waitcnt vmcnt(0)
	s_barrier
	s_waitcnt lgkmcnt(0)
	s_waitcnt lgkmcnt(0)
	v_mfma_f32_16x16x32_bf16 v[96:99], v[210:213], v[24:27], v[226:229]
	v_mfma_f32_16x16x32_bf16 v[24:27], v[218:221], v[24:27], v[178:181]
	v_mfma_f32_16x16x32_bf16 v[116:119], v[222:225], v[28:31], v[24:27]
	v_mfma_f32_16x16x32_bf16 v[24:27], v[210:213], v[40:43], v[84:87]
	v_mfma_f32_16x16x32_bf16 v[112:115], v[214:217], v[28:31], v[96:99]
	v_mfma_f32_16x16x32_bf16 v[96:99], v[214:217], v[44:47], v[24:27]
	v_mfma_f32_16x16x32_bf16 v[24:27], v[218:221], v[40:43], v[80:83]
	v_mfma_f32_16x16x32_bf16 v[100:103], v[222:225], v[44:47], v[24:27]
	v_mfma_f32_16x16x32_bf16 v[24:27], v[210:213], v[56:59], v[182:185]
	v_mfma_f32_16x16x32_bf16 v[80:83], v[214:217], v[64:67], v[24:27]
	v_mfma_f32_16x16x32_bf16 v[24:27], v[218:221], v[56:59], v[186:189]
	v_mfma_f32_16x16x32_bf16 v[84:87], v[222:225], v[64:67], v[24:27]
	v_mfma_f32_16x16x32_bf16 v[24:27], v[210:213], v[198:201], v[68:71]
	v_mfma_f32_16x16x32_bf16 v[64:67], v[214:217], v[202:205], v[24:27]
	v_mfma_f32_16x16x32_bf16 v[24:27], v[218:221], v[198:201], v[190:193]
	v_mfma_f32_16x16x32_bf16 v[68:71], v[222:225], v[202:205], v[24:27]
	s_barrier
	ds_read_b128 v[178:181], v164 offset:49152
	ds_read_b128 v[182:185], v164 offset:50176
	ds_read_b128 v[186:189], v164 offset:51200
	ds_read_b128 v[190:193], v164 offset:52224
	ds_read_b128 v[198:201], v164 offset:53248
	ds_read_b128 v[202:205], v164 offset:54272
	ds_read_b128 v[226:229], v164 offset:55296
	ds_read_b128 v[238:241], v164 offset:56320
	s_barrier
	s_waitcnt lgkmcnt(0)
	s_waitcnt lgkmcnt(0)
	v_mfma_f32_16x16x32_bf16 v[24:27], v[0:3], v[178:181], v[60:63]
	v_mfma_f32_16x16x32_bf16 v[56:59], v[8:11], v[182:185], v[24:27]
	v_mfma_f32_16x16x32_bf16 v[24:27], v[12:15], v[178:181], v[206:209]
	v_mfma_f32_16x16x32_bf16 v[60:63], v[194:197], v[182:185], v[24:27]
	v_mfma_f32_16x16x32_bf16 v[24:27], v[0:3], v[186:189], v[52:55]
	v_mfma_f32_16x16x32_bf16 v[40:43], v[8:11], v[190:193], v[24:27]
	v_mfma_f32_16x16x32_bf16 v[24:27], v[12:15], v[186:189], v[48:51]
	v_mfma_f32_16x16x32_bf16 v[44:47], v[194:197], v[190:193], v[24:27]
	v_mfma_f32_16x16x32_bf16 v[24:27], v[0:3], v[198:201], v[230:233]
	v_mfma_f32_16x16x32_bf16 v[0:3], v[0:3], v[226:229], v[36:39]
	v_mfma_f32_16x16x32_bf16 v[24:27], v[8:11], v[202:205], v[24:27]
	v_mfma_f32_16x16x32_bf16 v[28:31], v[12:15], v[198:201], v[234:237]
	v_mfma_f32_16x16x32_bf16 v[8:11], v[8:11], v[238:241], v[0:3]
	v_mfma_f32_16x16x32_bf16 v[0:3], v[12:15], v[226:229], v[32:35]
	v_mfma_f32_16x16x32_bf16 v[28:31], v[194:197], v[202:205], v[28:31]
	v_mfma_f32_16x16x32_bf16 v[12:15], v[194:197], v[238:241], v[0:3]
	v_mfma_f32_16x16x32_bf16 v[0:3], v[210:213], v[178:181], v[136:139]
	v_mfma_f32_16x16x32_bf16 v[48:51], v[214:217], v[182:185], v[0:3]
	v_mfma_f32_16x16x32_bf16 v[0:3], v[218:221], v[178:181], v[140:143]
	v_mfma_f32_16x16x32_bf16 v[52:55], v[222:225], v[182:185], v[0:3]
	v_mfma_f32_16x16x32_bf16 v[0:3], v[210:213], v[186:189], v[20:23]
	v_mfma_f32_16x16x32_bf16 v[32:35], v[214:217], v[190:193], v[0:3]
	v_mfma_f32_16x16x32_bf16 v[0:3], v[218:221], v[186:189], v[16:19]
	v_mfma_f32_16x16x32_bf16 v[36:39], v[222:225], v[190:193], v[0:3]
	v_mfma_f32_16x16x32_bf16 v[0:3], v[210:213], v[198:201], v[166:169]
	v_mfma_f32_16x16x32_bf16 v[16:19], v[214:217], v[202:205], v[0:3]
	v_mfma_f32_16x16x32_bf16 v[0:3], v[218:221], v[198:201], v[170:173]
	v_mfma_f32_16x16x32_bf16 v[20:23], v[222:225], v[202:205], v[0:3]
	v_mfma_f32_16x16x32_bf16 v[0:3], v[210:213], v[226:229], v[4:7]
	v_mfma_f32_16x16x32_bf16 v[4:7], v[218:221], v[226:229], v[174:177]
	v_mfma_f32_16x16x32_bf16 v[0:3], v[214:217], v[238:241], v[0:3]
	v_mfma_f32_16x16x32_bf16 v[4:7], v[222:225], v[238:241], v[4:7]
	s_barrier
	s_and_saveexec_b64 s[14:15], s[4:5]
	s_cbranch_execz .LBB0_657
	s_barrier

; #define STA(b, h, half, kt) STAGE(((b) * 2 + (h)) * G_HT * 2, pA, ((size_t)(half) * G_HALF * lda + (size_t)(kt) * G_BK) * 2, lda)
; #define STB(b, h, half, kt) STAGE((4 + (b) * 2 + (h)) * G_HT * 2, pB, ((size_t)(half) * G_HALF * K + (size_t)(kt) * G_BK) * 2, K)
; #define LDA(dst, b, h) for (int m = 0; m < 4; ++m) for (int k = 0; k < 2; ++k) \
;     dst[m][k] = *reinterpret_cast<const bf16x8*>(aRd + (((b) * 2 + (h)) * G_HT * 2 + m * 2048 + k * 1024))
; #define LDB(dst, b, h) for (int n = 0; n < 2; ++n) for (int k = 0; k < 2; ++k) \
;     dst[n][k] = *reinterpret_cast<const bf16x8*>(bRd + (((b) * 2 + (h)) * G_HT * 2 + n * 2048 + k * 1024))
; #define MMA(ai, bj, At, Bx) do { __builtin_amdgcn_s_setprio(1); \
;     for (int m = 0; m < 4; ++m) for (int n = 0; n < 2; ++n) for (int k = 0; k < 2; ++k) \
;       acc[ai][bj][m][n] = __builtin_amdgcn_mfma_f32_16x16x32_bf16(Bx[n][k], At[m][k], acc[ai][bj][m][n], 0, 0, 0);     \
;     __builtin_amdgcn_s_setprio(0); } while (0)
; #define WAIT_V(n) asm volatile("s_waitcnt vmcnt(" #n ")" ::: "memory")
; #define WAIT_L(n) asm volatile("s_waitcnt lgkmcnt(" #n ")" ::: "memory")
; #define BAR __builtin_amdgcn_s_barrier()
; #define SCHED __builtin_amdgcn_sched_barrier(0)
; template <int EPI>
; __device__ __forceinline__ void gemm_tile(const bf16* __restrict__ A, int lda, const bf16* __restrict__ Bt, int K,
;                                           int brow, int bcol, const EpiArgs& ea, char* shmc, bool has_next, int nbrow, int nbcol, bool first_tile) {
;     ...
;     LDB(B0, 0, 0); SCHED; LDA(At, 0, 0); STA(1, 1, 1, t + 1);
;     WAIT_L(8); BAR; WAIT_L(0); MMA(0, 0, At, B0); BAR; SCHED;
;     LDB(B1, 0, 1); STB(0, 0, 0, t + 2);
;     BAR; WAIT_L(0); MMA(0, 1, At, B1); BAR;
;     LDA(At, 0, 1); STA(0, 0, 0, t + 2);
;     BAR; WAIT_L(0); MMA(1, 0, At, B0); BAR; SCHED;
;     STB(0, 1, 1, t + 2);
;     WAIT_V(6); BAR; MMA(1, 1, At, B1); BAR;
.LBB0_727:
	ds_read_b128 v[136:139], v141
	ds_read_b128 v[162:165], v142
	ds_read_b128 v[166:169], v143
	ds_read_b128 v[170:173], v144
	s_add_u32 s52, s20, 0xffffff00
	s_addc_u32 s53, s21, -1
	s_mov_b32 m0, s50
	ds_read_b128 v[174:177], v160
	ds_read_b128 v[178:181], v160 offset:1024
	ds_read_b128 v[182:185], v160 offset:2048
	ds_read_b128 v[186:189], v160 offset:3072
	ds_read_b128 v[190:193], v160 offset:4096
	ds_read_b128 v[194:197], v160 offset:5120
	ds_read_b128 v[198:201], v160 offset:6144
	ds_read_b128 v[202:205], v160 offset:7168
	v_lshl_add_u64 v[206:207], v[132:133], 0, s[52:53]
	global_load_lds_dwordx4 v[206:207], off
	s_mov_b32 m0, s34
	v_lshl_add_u64 v[206:207], v[206:207], 0, s[10:11]
	global_load_lds_dwordx4 v[206:207], off
	s_waitcnt lgkmcnt(8)
	s_barrier
	s_waitcnt lgkmcnt(0)
	v_mfma_f32_16x16x32_bf16 v[124:127], v[136:139], v[174:177], v[124:127]
	v_mfma_f32_16x16x32_bf16 v[120:123], v[166:169], v[174:177], v[120:123]
	v_mfma_f32_16x16x32_bf16 v[116:119], v[136:139], v[182:185], v[116:119]
	v_mfma_f32_16x16x32_bf16 v[112:115], v[166:169], v[182:185], v[112:115]
	v_mfma_f32_16x16x32_bf16 v[108:111], v[136:139], v[190:193], v[108:111]
	v_mfma_f32_16x16x32_bf16 v[104:107], v[166:169], v[190:193], v[104:107]
	v_mfma_f32_16x16x32_bf16 v[100:103], v[136:139], v[198:201], v[100:103]
	v_mfma_f32_16x16x32_bf16 v[96:99], v[166:169], v[198:201], v[96:99]
	v_mfma_f32_16x16x32_bf16 v[124:127], v[162:165], v[178:181], v[124:127]
	v_mfma_f32_16x16x32_bf16 v[120:123], v[170:173], v[178:181], v[120:123]
	v_mfma_f32_16x16x32_bf16 v[116:119], v[162:165], v[186:189], v[116:119]
	v_mfma_f32_16x16x32_bf16 v[112:115], v[170:173], v[186:189], v[112:115]
	v_mfma_f32_16x16x32_bf16 v[108:111], v[162:165], v[194:197], v[108:111]
	v_mfma_f32_16x16x32_bf16 v[104:107], v[170:173], v[194:197], v[104:107]
	v_mfma_f32_16x16x32_bf16 v[100:103], v[162:165], v[202:205], v[100:103]
	v_mfma_f32_16x16x32_bf16 v[96:99], v[170:173], v[202:205], v[96:99]
	s_barrier
	s_add_u32 s52, s20, 0xffefff80
	s_addc_u32 s53, s21, -1
	s_mov_b64 s[54:55], s[52:53]
	s_mov_b32 m0, s41
	ds_read_b128 v[206:209], v145
	ds_read_b128 v[210:213], v146
	ds_read_b128 v[214:217], v147
	ds_read_b128 v[218:221], v148
	v_lshl_add_u64 v[222:223], v[134:135], 0, s[54:55]
	global_load_lds_dwordx4 v[222:223], off
	s_mov_b32 m0, s42
	v_lshl_add_u64 v[222:223], v[222:223], 0, s[10:11]
	global_load_lds_dwordx4 v[222:223], off
	s_barrier
	s_waitcnt lgkmcnt(0)
	v_mfma_f32_16x16x32_bf16 v[92:95], v[206:209], v[174:177], v[92:95]
	v_mfma_f32_16x16x32_bf16 v[88:91], v[214:217], v[174:177], v[88:91]
	v_mfma_f32_16x16x32_bf16 v[84:87], v[206:209], v[182:185], v[84:87]
	v_mfma_f32_16x16x32_bf16 v[80:83], v[214:217], v[182:185], v[80:83]
	v_mfma_f32_16x16x32_bf16 v[76:79], v[206:209], v[190:193], v[76:79]
	v_mfma_f32_16x16x32_bf16 v[72:75], v[214:217], v[190:193], v[72:75]
	v_mfma_f32_16x16x32_bf16 v[68:71], v[206:209], v[198:201], v[68:71]
	v_mfma_f32_16x16x32_bf16 v[64:67], v[214:217], v[198:201], v[64:67]
	v_mfma_f32_16x16x32_bf16 v[92:95], v[210:213], v[178:181], v[92:95]
	v_mfma_f32_16x16x32_bf16 v[88:91], v[218:221], v[178:181], v[88:91]
	v_mfma_f32_16x16x32_bf16 v[84:87], v[210:213], v[186:189], v[84:87]
	v_mfma_f32_16x16x32_bf16 v[80:83], v[218:221], v[186:189], v[80:83]
	v_mfma_f32_16x16x32_bf16 v[76:79], v[210:213], v[194:197], v[76:79]
	v_mfma_f32_16x16x32_bf16 v[72:75], v[218:221], v[194:197], v[72:75]
	v_mfma_f32_16x16x32_bf16 v[68:71], v[210:213], v[202:205], v[68:71]
	v_mfma_f32_16x16x32_bf16 v[64:67], v[218:221], v[202:205], v[64:67]
	s_mov_b32 m0, s1
	s_barrier
	ds_read_b128 v[174:177], v160 offset:16384
	ds_read_b128 v[178:181], v160 offset:17408
	ds_read_b128 v[182:185], v160 offset:18432
	ds_read_b128 v[186:189], v160 offset:19456
	ds_read_b128 v[190:193], v160 offset:20480
	ds_read_b128 v[194:197], v160 offset:21504
	ds_read_b128 v[198:201], v160 offset:22528
	ds_read_b128 v[202:205], v160 offset:23552
	v_lshl_add_u64 v[222:223], v[132:133], 0, s[52:53]
	global_load_lds_dwordx4 v[222:223], off
	s_add_i32 m0, s1, 0x2000
	v_lshl_add_u64 v[222:223], v[222:223], 0, s[10:11]
	global_load_lds_dwordx4 v[222:223], off
	s_barrier
	s_waitcnt lgkmcnt(0)
	v_mfma_f32_16x16x32_bf16 v[60:63], v[136:139], v[174:177], v[60:63]
	v_mfma_f32_16x16x32_bf16 v[56:59], v[166:169], v[174:177], v[56:59]
	v_mfma_f32_16x16x32_bf16 v[52:55], v[136:139], v[182:185], v[52:55]
	v_mfma_f32_16x16x32_bf16 v[48:51], v[166:169], v[182:185], v[48:51]
	v_mfma_f32_16x16x32_bf16 v[44:47], v[136:139], v[190:193], v[44:47]
	v_mfma_f32_16x16x32_bf16 v[40:43], v[166:169], v[190:193], v[40:43]
	v_mfma_f32_16x16x32_bf16 v[36:39], v[136:139], v[198:201], v[36:39]
	v_mfma_f32_16x16x32_bf16 v[32:35], v[166:169], v[198:201], v[32:35]
	v_mfma_f32_16x16x32_bf16 v[60:63], v[162:165], v[178:181], v[60:63]
	v_mfma_f32_16x16x32_bf16 v[56:59], v[170:173], v[178:181], v[56:59]
	v_mfma_f32_16x16x32_bf16 v[52:55], v[162:165], v[186:189], v[52:55]
	v_mfma_f32_16x16x32_bf16 v[48:51], v[170:173], v[186:189], v[48:51]
	v_mfma_f32_16x16x32_bf16 v[44:47], v[162:165], v[194:197], v[44:47]
	v_mfma_f32_16x16x32_bf16 v[40:43], v[170:173], v[194:197], v[40:43]
	v_mfma_f32_16x16x32_bf16 v[36:39], v[162:165], v[202:205], v[36:39]
	v_mfma_f32_16x16x32_bf16 v[32:35], v[170:173], v[202:205], v[32:35]
	s_barrier
	s_add_u32 s52, s20, 0xffffff80
	s_addc_u32 s53, s21, -1
	s_mov_b64 s[54:55], s[52:53]
	s_mov_b32 m0, s43
	v_lshl_add_u64 v[136:137], v[134:135], 0, s[54:55]
	global_load_lds_dwordx4 v[136:137], off
	s_mov_b32 m0, s48
	v_lshl_add_u64 v[136:137], v[136:137], 0, s[10:11]
	global_load_lds_dwordx4 v[136:137], off
	s_waitcnt vmcnt(6)
	s_barrier
; #define STA(b, h, half, kt) STAGE(((b) * 2 + (h)) * G_HT * 2, pA, ((size_t)(half) * G_HALF * lda + (size_t)(kt) * G_BK) * 2, lda)
; #define STB(b, h, half, kt) STAGE((4 + (b) * 2 + (h)) * G_HT * 2, pB, ((size_t)(half) * G_HALF * K + (size_t)(kt) * G_BK) * 2, K)
; #define LDA(dst, b, h) for (int m = 0; m < 4; ++m) for (int k = 0; k < 2; ++k) \
;     dst[m][k] = *reinterpret_cast<const bf16x8*>(aRd + (((b) * 2 + (h)) * G_HT * 2 + m * 2048 + k * 1024))
; #define LDB(dst, b, h) for (int n = 0; n < 2; ++n) for (int k = 0; k < 2; ++k) \
;     dst[n][k] = *reinterpret_cast<const bf16x8*>(bRd + (((b) * 2 + (h)) * G_HT * 2 + n * 2048 + k * 1024))
; #define MMA(ai, bj, At, Bx) do { __builtin_amdgcn_s_setprio(1); \
;     for (int m = 0; m < 4; ++m) for (int n = 0; n < 2; ++n) for (int k = 0; k < 2; ++k) \
;       acc[ai][bj][m][n] = __builtin_amdgcn_mfma_f32_16x16x32_bf16(Bx[n][k], At[m][k], acc[ai][bj][m][n], 0, 0, 0);     \
;     __builtin_amdgcn_s_setprio(0); } while (0)
; #define WAIT_V(n) asm volatile("s_waitcnt vmcnt(" #n ")" ::: "memory")
; #define WAIT_L(n) asm volatile("s_waitcnt lgkmcnt(" #n ")" ::: "memory")
; #define BAR __builtin_amdgcn_s_barrier()
; #define SCHED __builtin_amdgcn_sched_barrier(0)
; template <int EPI>
; __device__ __forceinline__ void gemm_tile(const bf16* __restrict__ A, int lda, const bf16* __restrict__ Bt, int K,
;                                           int brow, int bcol, const EpiArgs& ea, char* shmc, bool has_next, int nbrow, int nbcol, bool first_tile) {
;     ...
;     WAIT_V(6); BAR; MMA(1, 1, At, B1); BAR;
;     LDB(B0, 1, 0); SCHED; LDA(At, 1, 0); STA(0, 1, 1, t + 2);
;     WAIT_L(8); BAR; WAIT_L(0); MMA(0, 0, At, B0); BAR; SCHED;
;     LDB(B1, 1, 1); STB(1, 0, 0, t + 3);
;     BAR; WAIT_L(0); MMA(0, 1, At, B1); BAR;
;     LDA(At, 1, 1); STA(1, 0, 0, t + 3);
;     BAR; WAIT_L(0); MMA(1, 0, At, B0); BAR; SCHED;
	v_mfma_f32_16x16x32_bf16 v[28:31], v[206:209], v[174:177], v[28:31]
	v_mfma_f32_16x16x32_bf16 v[24:27], v[214:217], v[174:177], v[24:27]
	v_mfma_f32_16x16x32_bf16 v[20:23], v[206:209], v[182:185], v[20:23]
	v_mfma_f32_16x16x32_bf16 v[16:19], v[214:217], v[182:185], v[16:19]
	v_mfma_f32_16x16x32_bf16 v[12:15], v[206:209], v[190:193], v[12:15]
	v_mfma_f32_16x16x32_bf16 v[8:11], v[214:217], v[190:193], v[8:11]
	v_mfma_f32_16x16x32_bf16 v[4:7], v[206:209], v[198:201], v[4:7]
	v_mfma_f32_16x16x32_bf16 v[0:3], v[214:217], v[198:201], v[0:3]
	v_mfma_f32_16x16x32_bf16 v[28:31], v[210:213], v[178:181], v[28:31]
	v_mfma_f32_16x16x32_bf16 v[24:27], v[218:221], v[178:181], v[24:27]
	v_mfma_f32_16x16x32_bf16 v[20:23], v[210:213], v[186:189], v[20:23]
	v_mfma_f32_16x16x32_bf16 v[16:19], v[218:221], v[186:189], v[16:19]
	v_mfma_f32_16x16x32_bf16 v[12:15], v[210:213], v[194:197], v[12:15]
	v_mfma_f32_16x16x32_bf16 v[8:11], v[218:221], v[194:197], v[8:11]
	v_mfma_f32_16x16x32_bf16 v[4:7], v[210:213], v[202:205], v[4:7]
	v_mfma_f32_16x16x32_bf16 v[0:3], v[218:221], v[202:205], v[0:3]
	s_barrier
	ds_read_b128 v[136:139], v149
	ds_read_b128 v[162:165], v150
	ds_read_b128 v[166:169], v151
	ds_read_b128 v[170:173], v152
	ds_read_b128 v[174:177], v160 offset:32768
	ds_read_b128 v[178:181], v160 offset:33792
	ds_read_b128 v[182:185], v160 offset:34816
	ds_read_b128 v[186:189], v160 offset:35840
	ds_read_b128 v[190:193], v160 offset:36864
	ds_read_b128 v[194:197], v160 offset:37888
	ds_read_b128 v[198:201], v160 offset:38912
	ds_read_b128 v[202:205], v160 offset:39936
	s_add_i32 m0, s1, 0x4000
	v_lshl_add_u64 v[206:207], v[132:133], 0, s[52:53]
	global_load_lds_dwordx4 v[206:207], off
	s_add_i32 m0, s1, 0x6000
	v_lshl_add_u64 v[206:207], v[206:207], 0, s[10:11]
	global_load_lds_dwordx4 v[206:207], off
	s_waitcnt lgkmcnt(8)
	s_barrier
	s_waitcnt lgkmcnt(0)
	v_mfma_f32_16x16x32_bf16 v[124:127], v[136:139], v[174:177], v[124:127]
	v_mfma_f32_16x16x32_bf16 v[120:123], v[166:169], v[174:177], v[120:123]
	v_mfma_f32_16x16x32_bf16 v[116:119], v[136:139], v[182:185], v[116:119]
	v_mfma_f32_16x16x32_bf16 v[112:115], v[166:169], v[182:185], v[112:115]
	v_mfma_f32_16x16x32_bf16 v[108:111], v[136:139], v[190:193], v[108:111]
	v_mfma_f32_16x16x32_bf16 v[104:107], v[166:169], v[190:193], v[104:107]
	v_mfma_f32_16x16x32_bf16 v[100:103], v[136:139], v[198:201], v[100:103]
	v_mfma_f32_16x16x32_bf16 v[96:99], v[166:169], v[198:201], v[96:99]
	v_mfma_f32_16x16x32_bf16 v[124:127], v[162:165], v[178:181], v[124:127]
	v_mfma_f32_16x16x32_bf16 v[120:123], v[170:173], v[178:181], v[120:123]
	v_mfma_f32_16x16x32_bf16 v[116:119], v[162:165], v[186:189], v[116:119]
	v_mfma_f32_16x16x32_bf16 v[112:115], v[170:173], v[186:189], v[112:115]
	v_mfma_f32_16x16x32_bf16 v[108:111], v[162:165], v[194:197], v[108:111]
	v_mfma_f32_16x16x32_bf16 v[104:107], v[170:173], v[194:197], v[104:107]
	v_mfma_f32_16x16x32_bf16 v[100:103], v[162:165], v[202:205], v[100:103]
	v_mfma_f32_16x16x32_bf16 v[96:99], v[170:173], v[202:205], v[96:99]
	s_barrier
	s_add_u32 s52, s20, 0xfff00000
	s_addc_u32 s53, s21, -1
	s_mov_b64 s[54:55], s[52:53]
	s_mov_b32 m0, s7
	ds_read_b128 v[206:209], v153
	ds_read_b128 v[210:213], v154
	ds_read_b128 v[214:217], v155
	ds_read_b128 v[218:221], v156
	v_lshl_add_u64 v[222:223], v[134:135], 0, s[54:55]
	global_load_lds_dwordx4 v[222:223], off
	s_mov_b32 m0, s29
	v_lshl_add_u64 v[222:223], v[222:223], 0, s[10:11]
	global_load_lds_dwordx4 v[222:223], off
	s_barrier
	s_waitcnt lgkmcnt(0)
	v_mfma_f32_16x16x32_bf16 v[92:95], v[206:209], v[174:177], v[92:95]
	v_mfma_f32_16x16x32_bf16 v[88:91], v[214:217], v[174:177], v[88:91]
	v_mfma_f32_16x16x32_bf16 v[84:87], v[206:209], v[182:185], v[84:87]
	v_mfma_f32_16x16x32_bf16 v[80:83], v[214:217], v[182:185], v[80:83]
	v_mfma_f32_16x16x32_bf16 v[76:79], v[206:209], v[190:193], v[76:79]
	v_mfma_f32_16x16x32_bf16 v[72:75], v[214:217], v[190:193], v[72:75]
	v_mfma_f32_16x16x32_bf16 v[68:71], v[206:209], v[198:201], v[68:71]
	v_mfma_f32_16x16x32_bf16 v[64:67], v[214:217], v[198:201], v[64:67]
	v_mfma_f32_16x16x32_bf16 v[92:95], v[210:213], v[178:181], v[92:95]
	v_mfma_f32_16x16x32_bf16 v[88:91], v[218:221], v[178:181], v[88:91]
	v_mfma_f32_16x16x32_bf16 v[84:87], v[210:213], v[186:189], v[84:87]
	v_mfma_f32_16x16x32_bf16 v[80:83], v[218:221], v[186:189], v[80:83]
	v_mfma_f32_16x16x32_bf16 v[76:79], v[210:213], v[194:197], v[76:79]
	v_mfma_f32_16x16x32_bf16 v[72:75], v[218:221], v[194:197], v[72:75]
	v_mfma_f32_16x16x32_bf16 v[68:71], v[210:213], v[202:205], v[68:71]
	v_mfma_f32_16x16x32_bf16 v[64:67], v[218:221], v[202:205], v[64:67]
	s_mov_b32 m0, s30
	s_barrier
	ds_read_b128 v[174:177], v160 offset:49152
	ds_read_b128 v[178:181], v160 offset:50176
	ds_read_b128 v[182:185], v160 offset:51200
	ds_read_b128 v[186:189], v160 offset:52224
	ds_read_b128 v[190:193], v160 offset:53248
	ds_read_b128 v[194:197], v160 offset:54272
	ds_read_b128 v[198:201], v160 offset:55296
	ds_read_b128 v[202:205], v160 offset:56320
	v_lshl_add_u64 v[222:223], v[132:133], 0, s[52:53]
	global_load_lds_dwordx4 v[222:223], off
	s_mov_b32 m0, s31
	v_lshl_add_u64 v[222:223], v[222:223], 0, s[10:11]
	global_load_lds_dwordx4 v[222:223], off
	s_barrier
; #define STA(b, h, half, kt) STAGE(((b) * 2 + (h)) * G_HT * 2, pA, ((size_t)(half) * G_HALF * lda + (size_t)(kt) * G_BK) * 2, lda)
; #define STB(b, h, half, kt) STAGE((4 + (b) * 2 + (h)) * G_HT * 2, pB, ((size_t)(half) * G_HALF * K + (size_t)(kt) * G_BK) * 2, K)
; #define LDA(dst, b, h) for (int m = 0; m < 4; ++m) for (int k = 0; k < 2; ++k) \
;     dst[m][k] = *reinterpret_cast<const bf16x8*>(aRd + (((b) * 2 + (h)) * G_HT * 2 + m * 2048 + k * 1024))
; #define LDB(dst, b, h) for (int n = 0; n < 2; ++n) for (int k = 0; k < 2; ++k) \
;     dst[n][k] = *reinterpret_cast<const bf16x8*>(bRd + (((b) * 2 + (h)) * G_HT * 2 + n * 2048 + k * 1024))
; #define MMA(ai, bj, At, Bx) do { __builtin_amdgcn_s_setprio(1); \
;     for (int m = 0; m < 4; ++m) for (int n = 0; n < 2; ++n) for (int k = 0; k < 2; ++k) \
;       acc[ai][bj][m][n] = __builtin_amdgcn_mfma_f32_16x16x32_bf16(Bx[n][k], At[m][k], acc[ai][bj][m][n], 0, 0, 0);     \
;     __builtin_amdgcn_s_setprio(0); } while (0)
; #define WAIT_V(n) asm volatile("s_waitcnt vmcnt(" #n ")" ::: "memory")
; #define WAIT_L(n) asm volatile("s_waitcnt lgkmcnt(" #n ")" ::: "memory")
; #define BAR __builtin_amdgcn_s_barrier()
; #define SCHED __builtin_amdgcn_sched_barrier(0)
; template <int EPI>
; __device__ __forceinline__ void gemm_tile(const bf16* __restrict__ A, int lda, const bf16* __restrict__ Bt, int K,
;                                           int brow, int bcol, const EpiArgs& ea, char* shmc, bool has_next, int nbrow, int nbcol, bool first_tile) {
;     ...
;     STB(0, 1, 1, t + 2);
;     WAIT_V(6); BAR; MMA(1, 1, At, B1); BAR;
;     LDB(B0, 1, 0); SCHED; LDA(At, 1, 0); STA(0, 1, 1, t + 2);
;     WAIT_L(8); BAR; WAIT_L(0); MMA(0, 0, At, B0); BAR; SCHED;
;     LDB(B1, 1, 1); STB(1, 0, 0, t + 3);
;     BAR; WAIT_L(0); MMA(0, 1, At, B1); BAR;
;     LDA(At, 1, 1); STA(1, 0, 0, t + 3);
;     BAR; WAIT_L(0); MMA(1, 0, At, B0); BAR; SCHED;
;     STB(1, 1, 1, t + 3);
;     WAIT_V(6); BAR; MMA(1, 1, At, B1); BAR;
;   }
;   { LDB(B0, 0, 0); LDA(At, 0, 0); STA(1, 1, 1, nt - 1);
;     BAR; WAIT_L(0); MMA(0, 0, At, B0); BAR;
;     LDB(B1, 0, 1); BAR; WAIT_L(0); MMA(0, 1, At, B1); BAR;
;     LDA(At, 0, 1); WAIT_V(4); BAR; WAIT_L(0); MMA(1, 0, At, B0); MMA(1, 1, At, B1); BAR; }
	s_waitcnt lgkmcnt(0)
	v_mfma_f32_16x16x32_bf16 v[60:63], v[136:139], v[174:177], v[60:63]
	v_mfma_f32_16x16x32_bf16 v[56:59], v[166:169], v[174:177], v[56:59]
	v_mfma_f32_16x16x32_bf16 v[52:55], v[136:139], v[182:185], v[52:55]
	v_mfma_f32_16x16x32_bf16 v[48:51], v[166:169], v[182:185], v[48:51]
	v_mfma_f32_16x16x32_bf16 v[44:47], v[136:139], v[190:193], v[44:47]
	v_mfma_f32_16x16x32_bf16 v[40:43], v[166:169], v[190:193], v[40:43]
	v_mfma_f32_16x16x32_bf16 v[36:39], v[136:139], v[198:201], v[36:39]
	v_mfma_f32_16x16x32_bf16 v[32:35], v[166:169], v[198:201], v[32:35]
	v_mfma_f32_16x16x32_bf16 v[60:63], v[162:165], v[178:181], v[60:63]
	v_mfma_f32_16x16x32_bf16 v[56:59], v[170:173], v[178:181], v[56:59]
	v_mfma_f32_16x16x32_bf16 v[52:55], v[162:165], v[186:189], v[52:55]
	v_mfma_f32_16x16x32_bf16 v[48:51], v[170:173], v[186:189], v[48:51]
	v_mfma_f32_16x16x32_bf16 v[44:47], v[162:165], v[194:197], v[44:47]
	v_mfma_f32_16x16x32_bf16 v[40:43], v[170:173], v[194:197], v[40:43]
	v_mfma_f32_16x16x32_bf16 v[36:39], v[162:165], v[202:205], v[36:39]
	v_mfma_f32_16x16x32_bf16 v[32:35], v[170:173], v[202:205], v[32:35]
	s_barrier
	s_mov_b64 s[52:53], s[20:21]
	s_mov_b32 m0, s35
	v_lshl_add_u64 v[136:137], v[134:135], 0, s[52:53]
	global_load_lds_dwordx4 v[136:137], off
	s_mov_b32 m0, s40
	v_lshl_add_u64 v[136:137], v[136:137], 0, s[10:11]
	global_load_lds_dwordx4 v[136:137], off
	s_waitcnt vmcnt(6)
	s_barrier
	v_mfma_f32_16x16x32_bf16 v[28:31], v[206:209], v[174:177], v[28:31]
	v_mfma_f32_16x16x32_bf16 v[24:27], v[214:217], v[174:177], v[24:27]
	v_mfma_f32_16x16x32_bf16 v[20:23], v[206:209], v[182:185], v[20:23]
	v_mfma_f32_16x16x32_bf16 v[16:19], v[214:217], v[182:185], v[16:19]
	v_mfma_f32_16x16x32_bf16 v[12:15], v[206:209], v[190:193], v[12:15]
	v_mfma_f32_16x16x32_bf16 v[8:11], v[214:217], v[190:193], v[8:11]
	v_mfma_f32_16x16x32_bf16 v[4:7], v[206:209], v[198:201], v[4:7]
	v_mfma_f32_16x16x32_bf16 v[0:3], v[214:217], v[198:201], v[0:3]
	v_mfma_f32_16x16x32_bf16 v[28:31], v[210:213], v[178:181], v[28:31]
	v_mfma_f32_16x16x32_bf16 v[24:27], v[218:221], v[178:181], v[24:27]
	v_mfma_f32_16x16x32_bf16 v[20:23], v[210:213], v[186:189], v[20:23]
	v_mfma_f32_16x16x32_bf16 v[16:19], v[218:221], v[186:189], v[16:19]
	v_mfma_f32_16x16x32_bf16 v[12:15], v[210:213], v[194:197], v[12:15]
	v_mfma_f32_16x16x32_bf16 v[8:11], v[218:221], v[194:197], v[8:11]
	v_mfma_f32_16x16x32_bf16 v[4:7], v[210:213], v[202:205], v[4:7]
	v_mfma_f32_16x16x32_bf16 v[0:3], v[218:221], v[202:205], v[0:3]
	s_add_i32 s49, s49, 2
	s_add_u32 s20, s20, 0x100
	s_addc_u32 s21, s21, 0
	s_cmp_lt_u32 s49, 60
	s_barrier
	s_cbranch_scc1 .LBB0_727
	s_mov_b64 s[20:21], 0x101f80
	s_mov_b32 m0, s50
	ds_read_b128 v[134:137], v141
	ds_read_b128 v[162:165], v142
	ds_read_b128 v[166:169], v143
	ds_read_b128 v[170:173], v144
	ds_read_b128 v[174:177], v160
	ds_read_b128 v[178:181], v160 offset:1024
	ds_read_b128 v[182:185], v160 offset:2048
	ds_read_b128 v[186:189], v160 offset:3072
	ds_read_b128 v[190:193], v160 offset:4096
	ds_read_b128 v[194:197], v160 offset:5120
	ds_read_b128 v[198:201], v160 offset:6144
	ds_read_b128 v[202:205], v160 offset:7168
	s_nop 0
	v_lshl_add_u64 v[132:133], v[132:133], 0, s[20:21]
	global_load_lds_dwordx4 v[132:133], off
	v_lshl_add_u64 v[132:133], v[132:133], 0, s[10:11]
	s_mov_b32 m0, s34
	s_nop 0
	global_load_lds_dwordx4 v[132:133], off
	s_barrier
	s_waitcnt lgkmcnt(0)
	s_waitcnt lgkmcnt(0)
	v_mfma_f32_16x16x32_bf16 v[124:127], v[134:137], v[174:177], v[124:127]
	v_mfma_f32_16x16x32_bf16 v[120:123], v[166:169], v[174:177], v[120:123]
	v_mfma_f32_16x16x32_bf16 v[108:111], v[134:137], v[190:193], v[108:111]
	v_mfma_f32_16x16x32_bf16 v[104:107], v[166:169], v[190:193], v[104:107]
	v_mfma_f32_16x16x32_bf16 v[124:127], v[162:165], v[178:181], v[124:127]
	v_mfma_f32_16x16x32_bf16 v[120:123], v[170:173], v[178:181], v[120:123]
	v_mfma_f32_16x16x32_bf16 v[116:119], v[134:137], v[182:185], v[116:119]
	v_mfma_f32_16x16x32_bf16 v[112:115], v[166:169], v[182:185], v[112:115]
	v_mfma_f32_16x16x32_bf16 v[108:111], v[162:165], v[194:197], v[108:111]
	v_mfma_f32_16x16x32_bf16 v[104:107], v[170:173], v[194:197], v[104:107]
	v_mfma_f32_16x16x32_bf16 v[100:103], v[134:137], v[198:201], v[100:103]
	v_mfma_f32_16x16x32_bf16 v[96:99], v[166:169], v[198:201], v[96:99]
	v_mfma_f32_16x16x32_bf16 v[206:209], v[162:165], v[186:189], v[116:119]
	v_mfma_f32_16x16x32_bf16 v[210:213], v[170:173], v[186:189], v[112:115]
	v_mfma_f32_16x16x32_bf16 v[214:217], v[162:165], v[202:205], v[100:103]
	v_mfma_f32_16x16x32_bf16 v[218:221], v[170:173], v[202:205], v[96:99]
	s_barrier
	s_nop 1
	ds_read_b128 v[96:99], v145
	ds_read_b128 v[100:103], v146
	ds_read_b128 v[112:115], v147
	ds_read_b128 v[116:119], v148
	s_barrier
	s_waitcnt lgkmcnt(0)
	s_waitcnt lgkmcnt(0)
	v_mfma_f32_16x16x32_bf16 v[92:95], v[96:99], v[174:177], v[92:95]
	v_mfma_f32_16x16x32_bf16 v[88:91], v[112:115], v[174:177], v[88:91]
	v_mfma_f32_16x16x32_bf16 v[76:79], v[96:99], v[190:193], v[76:79]
	v_mfma_f32_16x16x32_bf16 v[72:75], v[112:115], v[190:193], v[72:75]
	v_mfma_f32_16x16x32_bf16 v[92:95], v[100:103], v[178:181], v[92:95]
	v_mfma_f32_16x16x32_bf16 v[88:91], v[116:119], v[178:181], v[88:91]
	v_mfma_f32_16x16x32_bf16 v[84:87], v[96:99], v[182:185], v[84:87]
	v_mfma_f32_16x16x32_bf16 v[80:83], v[112:115], v[182:185], v[80:83]
	v_mfma_f32_16x16x32_bf16 v[76:79], v[100:103], v[194:197], v[76:79]
	v_mfma_f32_16x16x32_bf16 v[72:75], v[116:119], v[194:197], v[72:75]
	v_mfma_f32_16x16x32_bf16 v[68:71], v[96:99], v[198:201], v[68:71]
	v_mfma_f32_16x16x32_bf16 v[64:67], v[112:115], v[198:201], v[64:67]
	v_mfma_f32_16x16x32_bf16 v[174:177], v[100:103], v[186:189], v[84:87]
	v_mfma_f32_16x16x32_bf16 v[178:181], v[116:119], v[186:189], v[80:83]
	v_mfma_f32_16x16x32_bf16 v[182:185], v[100:103], v[202:205], v[68:71]
	v_mfma_f32_16x16x32_bf16 v[186:189], v[116:119], v[202:205], v[64:67]
	s_barrier
; #define LDA(dst, b, h) for (int m = 0; m < 4; ++m) for (int k = 0; k < 2; ++k) \
;     dst[m][k] = *reinterpret_cast<const bf16x8*>(aRd + (((b) * 2 + (h)) * G_HT * 2 + m * 2048 + k * 1024))
; #define LDB(dst, b, h) for (int n = 0; n < 2; ++n) for (int k = 0; k < 2; ++k) \
;     dst[n][k] = *reinterpret_cast<const bf16x8*>(bRd + (((b) * 2 + (h)) * G_HT * 2 + n * 2048 + k * 1024))
; #define MMA(ai, bj, At, Bx) do { __builtin_amdgcn_s_setprio(1); \
;     for (int m = 0; m < 4; ++m) for (int n = 0; n < 2; ++n) for (int k = 0; k < 2; ++k) \
;       acc[ai][bj][m][n] = __builtin_amdgcn_mfma_f32_16x16x32_bf16(Bx[n][k], At[m][k], acc[ai][bj][m][n], 0, 0, 0);     \
;     __builtin_amdgcn_s_setprio(0); } while (0)
; #define WAIT_V(n) asm volatile("s_waitcnt vmcnt(" #n ")" ::: "memory")
; #define WAIT_L(n) asm volatile("s_waitcnt lgkmcnt(" #n ")" ::: "memory")
; #define BAR __builtin_amdgcn_s_barrier()
; template <int EPI>
; __device__ __forceinline__ void gemm_tile(const bf16* __restrict__ A, int lda, const bf16* __restrict__ Bt, int K,
;                                           int brow, int bcol, const EpiArgs& ea, char* shmc, bool has_next, int nbrow, int nbcol, bool first_tile) {
;     ...
;     LDA(At, 0, 1); WAIT_V(4); BAR; WAIT_L(0); MMA(1, 0, At, B0); MMA(1, 1, At, B1); BAR; }
;   { LDB(B0, 1, 0); LDA(At, 1, 0); WAIT_V(2); BAR; WAIT_L(0); MMA(0, 0, At, B0); BAR;
;     LDB(B1, 1, 1); WAIT_V(0); BAR; WAIT_L(0); MMA(0, 1, At, B1); BAR;
	s_nop 1
	ds_read_b128 v[64:67], v160 offset:16384
	ds_read_b128 v[68:71], v160 offset:17408
	ds_read_b128 v[80:83], v160 offset:18432
	ds_read_b128 v[84:87], v160 offset:19456
	ds_read_b128 v[190:193], v160 offset:20480
	ds_read_b128 v[194:197], v160 offset:21504
	ds_read_b128 v[198:201], v160 offset:22528
	ds_read_b128 v[202:205], v160 offset:23552
	s_waitcnt vmcnt(4)
	s_barrier
	s_waitcnt lgkmcnt(0)
	s_waitcnt lgkmcnt(0)
	v_mfma_f32_16x16x32_bf16 v[60:63], v[134:137], v[64:67], v[60:63]
	v_mfma_f32_16x16x32_bf16 v[52:55], v[134:137], v[80:83], v[52:55]
	v_mfma_f32_16x16x32_bf16 v[48:51], v[166:169], v[80:83], v[48:51]
	v_mfma_f32_16x16x32_bf16 v[36:39], v[134:137], v[198:201], v[36:39]
	v_mfma_f32_16x16x32_bf16 v[32:35], v[166:169], v[198:201], v[32:35]
	v_mfma_f32_16x16x32_bf16 v[60:63], v[162:165], v[68:71], v[60:63]
	v_mfma_f32_16x16x32_bf16 v[56:59], v[166:169], v[64:67], v[56:59]
	v_mfma_f32_16x16x32_bf16 v[52:55], v[162:165], v[84:87], v[52:55]
	v_mfma_f32_16x16x32_bf16 v[48:51], v[170:173], v[84:87], v[48:51]
	v_mfma_f32_16x16x32_bf16 v[44:47], v[134:137], v[190:193], v[44:47]
	v_mfma_f32_16x16x32_bf16 v[40:43], v[166:169], v[190:193], v[40:43]
	v_mfma_f32_16x16x32_bf16 v[36:39], v[162:165], v[202:205], v[36:39]
	v_mfma_f32_16x16x32_bf16 v[32:35], v[170:173], v[202:205], v[32:35]
	v_mfma_f32_16x16x32_bf16 v[222:225], v[170:173], v[68:71], v[56:59]
	v_mfma_f32_16x16x32_bf16 v[226:229], v[162:165], v[194:197], v[44:47]
	v_mfma_f32_16x16x32_bf16 v[230:233], v[170:173], v[194:197], v[40:43]
	v_mfma_f32_16x16x32_bf16 v[20:23], v[96:99], v[80:83], v[20:23]
	v_mfma_f32_16x16x32_bf16 v[16:19], v[112:115], v[80:83], v[16:19]
	v_mfma_f32_16x16x32_bf16 v[12:15], v[96:99], v[190:193], v[12:15]
	v_mfma_f32_16x16x32_bf16 v[8:11], v[112:115], v[190:193], v[8:11]
	v_mfma_f32_16x16x32_bf16 v[28:31], v[96:99], v[64:67], v[28:31]
	v_mfma_f32_16x16x32_bf16 v[24:27], v[112:115], v[64:67], v[24:27]
	v_mfma_f32_16x16x32_bf16 v[20:23], v[100:103], v[84:87], v[20:23]
	v_mfma_f32_16x16x32_bf16 v[16:19], v[116:119], v[84:87], v[16:19]
	v_mfma_f32_16x16x32_bf16 v[12:15], v[100:103], v[194:197], v[12:15]
	v_mfma_f32_16x16x32_bf16 v[8:11], v[116:119], v[194:197], v[8:11]
	v_mfma_f32_16x16x32_bf16 v[4:7], v[96:99], v[198:201], v[4:7]
	v_mfma_f32_16x16x32_bf16 v[0:3], v[112:115], v[198:201], v[0:3]
	v_mfma_f32_16x16x32_bf16 v[132:135], v[100:103], v[68:71], v[28:31]
	v_mfma_f32_16x16x32_bf16 v[136:139], v[116:119], v[68:71], v[24:27]
	v_mfma_f32_16x16x32_bf16 v[162:165], v[100:103], v[202:205], v[4:7]
	v_mfma_f32_16x16x32_bf16 v[166:169], v[116:119], v[202:205], v[0:3]
	s_barrier
	s_nop 1
	ds_read_b128 v[0:3], v149
	ds_read_b128 v[4:7], v150
	ds_read_b128 v[170:173], v151
	ds_read_b128 v[190:193], v152
	ds_read_b128 v[24:27], v160 offset:32768
	ds_read_b128 v[28:31], v160 offset:33792
	ds_read_b128 v[40:43], v160 offset:34816
	ds_read_b128 v[44:47], v160 offset:35840
	ds_read_b128 v[56:59], v160 offset:36864
	ds_read_b128 v[194:197], v160 offset:37888
	ds_read_b128 v[198:201], v160 offset:38912
	ds_read_b128 v[202:205], v160 offset:39936
	s_waitcnt vmcnt(2)
	s_barrier
	s_waitcnt lgkmcnt(0)
	s_waitcnt lgkmcnt(0)
	v_mfma_f32_16x16x32_bf16 v[64:67], v[0:3], v[24:27], v[124:127]
	v_mfma_f32_16x16x32_bf16 v[112:115], v[4:7], v[28:31], v[64:67]
	v_mfma_f32_16x16x32_bf16 v[64:67], v[170:173], v[24:27], v[120:123]
	v_mfma_f32_16x16x32_bf16 v[116:119], v[190:193], v[28:31], v[64:67]
	v_mfma_f32_16x16x32_bf16 v[64:67], v[0:3], v[40:43], v[206:209]
	v_mfma_f32_16x16x32_bf16 v[96:99], v[4:7], v[44:47], v[64:67]
	v_mfma_f32_16x16x32_bf16 v[64:67], v[170:173], v[40:43], v[210:213]
	v_mfma_f32_16x16x32_bf16 v[100:103], v[190:193], v[44:47], v[64:67]
	v_mfma_f32_16x16x32_bf16 v[64:67], v[0:3], v[56:59], v[108:111]
	v_mfma_f32_16x16x32_bf16 v[80:83], v[4:7], v[194:197], v[64:67]
	v_mfma_f32_16x16x32_bf16 v[64:67], v[170:173], v[56:59], v[104:107]
	v_mfma_f32_16x16x32_bf16 v[84:87], v[190:193], v[194:197], v[64:67]
	v_mfma_f32_16x16x32_bf16 v[64:67], v[0:3], v[198:201], v[214:217]
	v_mfma_f32_16x16x32_bf16 v[68:71], v[170:173], v[198:201], v[218:221]
	v_mfma_f32_16x16x32_bf16 v[64:67], v[4:7], v[202:205], v[64:67]
	v_mfma_f32_16x16x32_bf16 v[68:71], v[190:193], v[202:205], v[68:71]
	s_barrier
; #define LDA(dst, b, h) for (int m = 0; m < 4; ++m) for (int k = 0; k < 2; ++k) \
;     dst[m][k] = *reinterpret_cast<const bf16x8*>(aRd + (((b) * 2 + (h)) * G_HT * 2 + m * 2048 + k * 1024))
; #define LDB(dst, b, h) for (int n = 0; n < 2; ++n) for (int k = 0; k < 2; ++k) \
;     dst[n][k] = *reinterpret_cast<const bf16x8*>(bRd + (((b) * 2 + (h)) * G_HT * 2 + n * 2048 + k * 1024))
; #define MMA(ai, bj, At, Bx) do { __builtin_amdgcn_s_setprio(1); \
;     for (int m = 0; m < 4; ++m) for (int n = 0; n < 2; ++n) for (int k = 0; k < 2; ++k) \
;       acc[ai][bj][m][n] = __builtin_amdgcn_mfma_f32_16x16x32_bf16(Bx[n][k], At[m][k], acc[ai][bj][m][n], 0, 0, 0);     \
;     __builtin_amdgcn_s_setprio(0); } while (0)
; #define WAIT_V(n) asm volatile("s_waitcnt vmcnt(" #n ")" ::: "memory")
; #define WAIT_L(n) asm volatile("s_waitcnt lgkmcnt(" #n ")" ::: "memory")
; #define BAR __builtin_amdgcn_s_barrier()
; template <int EPI>
; __device__ __forceinline__ void gemm_tile(const bf16* __restrict__ A, int lda, const bf16* __restrict__ Bt, int K,
;                                           int brow, int bcol, const EpiArgs& ea, char* shmc, bool has_next, int nbrow, int nbcol, bool first_tile) {
;     ...
;     LDB(B1, 1, 1); WAIT_V(0); BAR; WAIT_L(0); MMA(0, 1, At, B1); BAR;
;     LDA(At, 1, 1); BAR; WAIT_L(0); MMA(1, 0, At, B0); MMA(1, 1, At, B1); BAR; }
;   if (wr == 0) BAR;
	ds_read_b128 v[206:209], v153
	ds_read_b128 v[210:213], v154
	ds_read_b128 v[214:217], v155
	ds_read_b128 v[218:221], v156
	s_waitcnt vmcnt(0)
	s_barrier
	s_waitcnt lgkmcnt(0)
	s_waitcnt lgkmcnt(0)
	v_mfma_f32_16x16x32_bf16 v[92:95], v[206:209], v[24:27], v[92:95]
	v_mfma_f32_16x16x32_bf16 v[24:27], v[214:217], v[24:27], v[88:91]
	v_mfma_f32_16x16x32_bf16 v[124:127], v[218:221], v[28:31], v[24:27]
	v_mfma_f32_16x16x32_bf16 v[24:27], v[206:209], v[40:43], v[174:177]
	v_mfma_f32_16x16x32_bf16 v[104:107], v[210:213], v[44:47], v[24:27]
	v_mfma_f32_16x16x32_bf16 v[24:27], v[214:217], v[40:43], v[178:181]
	v_mfma_f32_16x16x32_bf16 v[108:111], v[218:221], v[44:47], v[24:27]
	v_mfma_f32_16x16x32_bf16 v[24:27], v[206:209], v[56:59], v[76:79]
	v_mfma_f32_16x16x32_bf16 v[88:91], v[210:213], v[194:197], v[24:27]
	v_mfma_f32_16x16x32_bf16 v[24:27], v[214:217], v[56:59], v[72:75]
	v_mfma_f32_16x16x32_bf16 v[120:123], v[210:213], v[28:31], v[92:95]
	v_mfma_f32_16x16x32_bf16 v[92:95], v[218:221], v[194:197], v[24:27]
	v_mfma_f32_16x16x32_bf16 v[24:27], v[206:209], v[198:201], v[182:185]
	v_mfma_f32_16x16x32_bf16 v[72:75], v[210:213], v[202:205], v[24:27]
	v_mfma_f32_16x16x32_bf16 v[24:27], v[214:217], v[198:201], v[186:189]
	v_mfma_f32_16x16x32_bf16 v[76:79], v[218:221], v[202:205], v[24:27]
	s_barrier
	ds_read_b128 v[174:177], v160 offset:49152
	ds_read_b128 v[178:181], v160 offset:50176
	ds_read_b128 v[182:185], v160 offset:51200
	ds_read_b128 v[186:189], v160 offset:52224
	ds_read_b128 v[194:197], v160 offset:53248
	ds_read_b128 v[198:201], v160 offset:54272
	ds_read_b128 v[202:205], v160 offset:55296
	ds_read_b128 v[234:237], v160 offset:56320
	s_barrier
	s_waitcnt lgkmcnt(0)
	s_waitcnt lgkmcnt(0)
	v_mfma_f32_16x16x32_bf16 v[24:27], v[0:3], v[174:177], v[60:63]
	v_mfma_f32_16x16x32_bf16 v[56:59], v[4:7], v[178:181], v[24:27]
	v_mfma_f32_16x16x32_bf16 v[24:27], v[170:173], v[174:177], v[222:225]
	v_mfma_f32_16x16x32_bf16 v[60:63], v[190:193], v[178:181], v[24:27]
	v_mfma_f32_16x16x32_bf16 v[24:27], v[0:3], v[182:185], v[52:55]
	v_mfma_f32_16x16x32_bf16 v[40:43], v[4:7], v[186:189], v[24:27]
	v_mfma_f32_16x16x32_bf16 v[24:27], v[170:173], v[182:185], v[48:51]
	v_mfma_f32_16x16x32_bf16 v[44:47], v[190:193], v[186:189], v[24:27]
	v_mfma_f32_16x16x32_bf16 v[24:27], v[0:3], v[194:197], v[226:229]
	v_mfma_f32_16x16x32_bf16 v[0:3], v[0:3], v[202:205], v[36:39]
	v_mfma_f32_16x16x32_bf16 v[24:27], v[4:7], v[198:201], v[24:27]
	v_mfma_f32_16x16x32_bf16 v[28:31], v[170:173], v[194:197], v[230:233]
	v_mfma_f32_16x16x32_bf16 v[0:3], v[4:7], v[234:237], v[0:3]
	v_mfma_f32_16x16x32_bf16 v[4:7], v[170:173], v[202:205], v[32:35]
	v_mfma_f32_16x16x32_bf16 v[28:31], v[190:193], v[198:201], v[28:31]
	v_mfma_f32_16x16x32_bf16 v[4:7], v[190:193], v[234:237], v[4:7]
	v_mfma_f32_16x16x32_bf16 v[32:35], v[206:209], v[174:177], v[132:135]
	v_mfma_f32_16x16x32_bf16 v[48:51], v[210:213], v[178:181], v[32:35]
	v_mfma_f32_16x16x32_bf16 v[32:35], v[214:217], v[174:177], v[136:139]
	v_mfma_f32_16x16x32_bf16 v[20:23], v[206:209], v[182:185], v[20:23]
	v_mfma_f32_16x16x32_bf16 v[16:19], v[214:217], v[182:185], v[16:19]
	v_mfma_f32_16x16x32_bf16 v[12:15], v[206:209], v[194:197], v[12:15]
	v_mfma_f32_16x16x32_bf16 v[8:11], v[214:217], v[194:197], v[8:11]
	v_mfma_f32_16x16x32_bf16 v[52:55], v[218:221], v[178:181], v[32:35]
	v_mfma_f32_16x16x32_bf16 v[32:35], v[210:213], v[186:189], v[20:23]
	v_mfma_f32_16x16x32_bf16 v[36:39], v[218:221], v[186:189], v[16:19]
	v_mfma_f32_16x16x32_bf16 v[16:19], v[210:213], v[198:201], v[12:15]
	v_mfma_f32_16x16x32_bf16 v[20:23], v[218:221], v[198:201], v[8:11]
	v_mfma_f32_16x16x32_bf16 v[8:11], v[206:209], v[202:205], v[162:165]
	v_mfma_f32_16x16x32_bf16 v[12:15], v[214:217], v[202:205], v[166:169]
	v_mfma_f32_16x16x32_bf16 v[8:11], v[210:213], v[234:237], v[8:11]
	v_mfma_f32_16x16x32_bf16 v[12:15], v[218:221], v[234:237], v[12:15]
	s_barrier
	s_and_saveexec_b64 s[20:21], s[4:5]
	s_cbranch_execz .LBB0_730
	s_barrier

; #define STA(b, h, half, kt) STAGE(((b) * 2 + (h)) * G_HT * 2, pA, ((size_t)(half) * G_HALF * lda + (size_t)(kt) * G_BK) * 2, lda)
; #define STB(b, h, half, kt) STAGE((4 + (b) * 2 + (h)) * G_HT * 2, pB, ((size_t)(half) * G_HALF * K + (size_t)(kt) * G_BK) * 2, K)
; #define LDA(dst, b, h) for (int m = 0; m < 4; ++m) for (int k = 0; k < 2; ++k) \
;     dst[m][k] = *reinterpret_cast<const bf16x8*>(aRd + (((b) * 2 + (h)) * G_HT * 2 + m * 2048 + k * 1024))
; #define LDB(dst, b, h) for (int n = 0; n < 2; ++n) for (int k = 0; k < 2; ++k) \
;     dst[n][k] = *reinterpret_cast<const bf16x8*>(bRd + (((b) * 2 + (h)) * G_HT * 2 + n * 2048 + k * 1024))
; #define MMA(ai, bj, At, Bx) do { __builtin_amdgcn_s_setprio(1); \
;     for (int m = 0; m < 4; ++m) for (int n = 0; n < 2; ++n) for (int k = 0; k < 2; ++k) \
;       acc[ai][bj][m][n] = __builtin_amdgcn_mfma_f32_16x16x32_bf16(Bx[n][k], At[m][k], acc[ai][bj][m][n], 0, 0, 0);     \
;     __builtin_amdgcn_s_setprio(0); } while (0)
; #define WAIT_V(n) asm volatile("s_waitcnt vmcnt(" #n ")" ::: "memory")
; #define WAIT_L(n) asm volatile("s_waitcnt lgkmcnt(" #n ")" ::: "memory")
; #define BAR __builtin_amdgcn_s_barrier()
; #define SCHED __builtin_amdgcn_sched_barrier(0)
; template <int EPI>
; __device__ __forceinline__ void gemm_tile(const bf16* __restrict__ A, int lda, const bf16* __restrict__ Bt, int K,
;                                           int brow, int bcol, const EpiArgs& ea, char* shmc, bool has_next, int nbrow, int nbcol, bool first_tile) {
;     ...
;     LDB(B0, 0, 0); SCHED; LDA(At, 0, 0); STA(1, 1, 1, t + 1);
;     WAIT_L(8); BAR; WAIT_L(0); MMA(0, 0, At, B0); BAR; SCHED;
;     LDB(B1, 0, 1); STB(0, 0, 0, t + 2);
;     BAR; WAIT_L(0); MMA(0, 1, At, B1); BAR;
;     LDA(At, 0, 1); STA(0, 0, 0, t + 2);
;     BAR; WAIT_L(0); MMA(1, 0, At, B0); BAR; SCHED;
;     STB(0, 1, 1, t + 2);
;     WAIT_V(6); BAR; MMA(1, 1, At, B1); BAR;
.LBB0_784:
	ds_read_b128 v[136:139], v141
	ds_read_b128 v[162:165], v142
	ds_read_b128 v[166:169], v143
	ds_read_b128 v[170:173], v144
	s_add_u32 s40, s18, 0xffffff00
	s_addc_u32 s41, s19, -1
	s_mov_b32 m0, s34
	ds_read_b128 v[174:177], v160
	ds_read_b128 v[178:181], v160 offset:1024
	ds_read_b128 v[182:185], v160 offset:2048
	ds_read_b128 v[186:189], v160 offset:3072
	ds_read_b128 v[190:193], v160 offset:4096
	ds_read_b128 v[194:197], v160 offset:5120
	ds_read_b128 v[198:201], v160 offset:6144
	ds_read_b128 v[202:205], v160 offset:7168
	v_lshl_add_u64 v[206:207], v[132:133], 0, s[40:41]
	global_load_lds_dwordx4 v[206:207], off
	s_mov_b32 m0, s24
	v_lshl_add_u64 v[206:207], v[206:207], 0, s[4:5]
	global_load_lds_dwordx4 v[206:207], off
	s_waitcnt lgkmcnt(8)
	s_barrier
	s_waitcnt lgkmcnt(0)
	v_mfma_f32_16x16x32_bf16 v[124:127], v[136:139], v[174:177], v[124:127]
	v_mfma_f32_16x16x32_bf16 v[120:123], v[166:169], v[174:177], v[120:123]
	v_mfma_f32_16x16x32_bf16 v[116:119], v[136:139], v[182:185], v[116:119]
	v_mfma_f32_16x16x32_bf16 v[112:115], v[166:169], v[182:185], v[112:115]
	v_mfma_f32_16x16x32_bf16 v[108:111], v[136:139], v[190:193], v[108:111]
	v_mfma_f32_16x16x32_bf16 v[104:107], v[166:169], v[190:193], v[104:107]
	v_mfma_f32_16x16x32_bf16 v[100:103], v[136:139], v[198:201], v[100:103]
	v_mfma_f32_16x16x32_bf16 v[96:99], v[166:169], v[198:201], v[96:99]
	v_mfma_f32_16x16x32_bf16 v[124:127], v[162:165], v[178:181], v[124:127]
	v_mfma_f32_16x16x32_bf16 v[120:123], v[170:173], v[178:181], v[120:123]
	v_mfma_f32_16x16x32_bf16 v[116:119], v[162:165], v[186:189], v[116:119]
	v_mfma_f32_16x16x32_bf16 v[112:115], v[170:173], v[186:189], v[112:115]
	v_mfma_f32_16x16x32_bf16 v[108:111], v[162:165], v[194:197], v[108:111]
	v_mfma_f32_16x16x32_bf16 v[104:107], v[170:173], v[194:197], v[104:107]
	v_mfma_f32_16x16x32_bf16 v[100:103], v[162:165], v[202:205], v[100:103]
	v_mfma_f32_16x16x32_bf16 v[96:99], v[170:173], v[202:205], v[96:99]
	s_barrier
	s_add_u32 s40, s18, 0xffbfff80
	s_addc_u32 s41, s19, -1
	s_mov_b64 s[42:43], s[40:41]
	s_mov_b32 m0, s27
	ds_read_b128 v[206:209], v145
	ds_read_b128 v[210:213], v146
	ds_read_b128 v[214:217], v147
	ds_read_b128 v[218:221], v148
	v_lshl_add_u64 v[222:223], v[134:135], 0, s[42:43]
	global_load_lds_dwordx4 v[222:223], off
	s_mov_b32 m0, s28
	v_lshl_add_u64 v[222:223], v[222:223], 0, s[4:5]
	global_load_lds_dwordx4 v[222:223], off
	s_barrier
	s_waitcnt lgkmcnt(0)
	v_mfma_f32_16x16x32_bf16 v[92:95], v[206:209], v[174:177], v[92:95]
	v_mfma_f32_16x16x32_bf16 v[88:91], v[214:217], v[174:177], v[88:91]
	v_mfma_f32_16x16x32_bf16 v[84:87], v[206:209], v[182:185], v[84:87]
	v_mfma_f32_16x16x32_bf16 v[80:83], v[214:217], v[182:185], v[80:83]
	v_mfma_f32_16x16x32_bf16 v[76:79], v[206:209], v[190:193], v[76:79]
	v_mfma_f32_16x16x32_bf16 v[72:75], v[214:217], v[190:193], v[72:75]
	v_mfma_f32_16x16x32_bf16 v[68:71], v[206:209], v[198:201], v[68:71]
	v_mfma_f32_16x16x32_bf16 v[64:67], v[214:217], v[198:201], v[64:67]
	v_mfma_f32_16x16x32_bf16 v[92:95], v[210:213], v[178:181], v[92:95]
	v_mfma_f32_16x16x32_bf16 v[88:91], v[218:221], v[178:181], v[88:91]
	v_mfma_f32_16x16x32_bf16 v[84:87], v[210:213], v[186:189], v[84:87]
	v_mfma_f32_16x16x32_bf16 v[80:83], v[218:221], v[186:189], v[80:83]
	v_mfma_f32_16x16x32_bf16 v[76:79], v[210:213], v[194:197], v[76:79]
	v_mfma_f32_16x16x32_bf16 v[72:75], v[218:221], v[194:197], v[72:75]
	v_mfma_f32_16x16x32_bf16 v[68:71], v[210:213], v[202:205], v[68:71]
	v_mfma_f32_16x16x32_bf16 v[64:67], v[218:221], v[202:205], v[64:67]
	s_mov_b32 m0, s15
	s_barrier
	ds_read_b128 v[174:177], v160 offset:16384
	ds_read_b128 v[178:181], v160 offset:17408
	ds_read_b128 v[182:185], v160 offset:18432
	ds_read_b128 v[186:189], v160 offset:19456
	ds_read_b128 v[190:193], v160 offset:20480
	ds_read_b128 v[194:197], v160 offset:21504
	ds_read_b128 v[198:201], v160 offset:22528
	ds_read_b128 v[202:205], v160 offset:23552
	v_lshl_add_u64 v[222:223], v[132:133], 0, s[40:41]
	global_load_lds_dwordx4 v[222:223], off
	s_mov_b32 m0, s35
	v_lshl_add_u64 v[222:223], v[222:223], 0, s[4:5]
	global_load_lds_dwordx4 v[222:223], off
	s_barrier
	s_waitcnt lgkmcnt(0)
	v_mfma_f32_16x16x32_bf16 v[60:63], v[136:139], v[174:177], v[60:63]
	v_mfma_f32_16x16x32_bf16 v[56:59], v[166:169], v[174:177], v[56:59]
	v_mfma_f32_16x16x32_bf16 v[52:55], v[136:139], v[182:185], v[52:55]
	v_mfma_f32_16x16x32_bf16 v[48:51], v[166:169], v[182:185], v[48:51]
	v_mfma_f32_16x16x32_bf16 v[44:47], v[136:139], v[190:193], v[44:47]
	v_mfma_f32_16x16x32_bf16 v[40:43], v[166:169], v[190:193], v[40:43]
	v_mfma_f32_16x16x32_bf16 v[36:39], v[136:139], v[198:201], v[36:39]
	v_mfma_f32_16x16x32_bf16 v[32:35], v[166:169], v[198:201], v[32:35]
	v_mfma_f32_16x16x32_bf16 v[60:63], v[162:165], v[178:181], v[60:63]
	v_mfma_f32_16x16x32_bf16 v[56:59], v[170:173], v[178:181], v[56:59]
	v_mfma_f32_16x16x32_bf16 v[52:55], v[162:165], v[186:189], v[52:55]
	v_mfma_f32_16x16x32_bf16 v[48:51], v[170:173], v[186:189], v[48:51]
	v_mfma_f32_16x16x32_bf16 v[44:47], v[162:165], v[194:197], v[44:47]
	v_mfma_f32_16x16x32_bf16 v[40:43], v[170:173], v[194:197], v[40:43]
	v_mfma_f32_16x16x32_bf16 v[36:39], v[162:165], v[202:205], v[36:39]
	v_mfma_f32_16x16x32_bf16 v[32:35], v[170:173], v[202:205], v[32:35]
	s_barrier
	s_add_u32 s40, s18, 0xffffff80
	s_addc_u32 s41, s19, -1
	s_mov_b64 s[42:43], s[40:41]
	s_mov_b32 m0, s29
	v_lshl_add_u64 v[136:137], v[134:135], 0, s[42:43]
	global_load_lds_dwordx4 v[136:137], off
	s_mov_b32 m0, s30
	v_lshl_add_u64 v[136:137], v[136:137], 0, s[4:5]
	global_load_lds_dwordx4 v[136:137], off
	s_waitcnt vmcnt(6)
	s_barrier
; #define STA(b, h, half, kt) STAGE(((b) * 2 + (h)) * G_HT * 2, pA, ((size_t)(half) * G_HALF * lda + (size_t)(kt) * G_BK) * 2, lda)
; #define STB(b, h, half, kt) STAGE((4 + (b) * 2 + (h)) * G_HT * 2, pB, ((size_t)(half) * G_HALF * K + (size_t)(kt) * G_BK) * 2, K)
; #define LDA(dst, b, h) for (int m = 0; m < 4; ++m) for (int k = 0; k < 2; ++k) \
;     dst[m][k] = *reinterpret_cast<const bf16x8*>(aRd + (((b) * 2 + (h)) * G_HT * 2 + m * 2048 + k * 1024))
; #define LDB(dst, b, h) for (int n = 0; n < 2; ++n) for (int k = 0; k < 2; ++k) \
;     dst[n][k] = *reinterpret_cast<const bf16x8*>(bRd + (((b) * 2 + (h)) * G_HT * 2 + n * 2048 + k * 1024))
; #define MMA(ai, bj, At, Bx) do { __builtin_amdgcn_s_setprio(1); \
;     for (int m = 0; m < 4; ++m) for (int n = 0; n < 2; ++n) for (int k = 0; k < 2; ++k) \
;       acc[ai][bj][m][n] = __builtin_amdgcn_mfma_f32_16x16x32_bf16(Bx[n][k], At[m][k], acc[ai][bj][m][n], 0, 0, 0);     \
;     __builtin_amdgcn_s_setprio(0); } while (0)
; #define WAIT_V(n) asm volatile("s_waitcnt vmcnt(" #n ")" ::: "memory")
; #define WAIT_L(n) asm volatile("s_waitcnt lgkmcnt(" #n ")" ::: "memory")
; #define BAR __builtin_amdgcn_s_barrier()
; #define SCHED __builtin_amdgcn_sched_barrier(0)
; template <int EPI>
; __device__ __forceinline__ void gemm_tile(const bf16* __restrict__ A, int lda, const bf16* __restrict__ Bt, int K,
;                                           int brow, int bcol, const EpiArgs& ea, char* shmc, bool has_next, int nbrow, int nbcol, bool first_tile) {
;     ...
;     WAIT_V(6); BAR; MMA(1, 1, At, B1); BAR;
;     LDB(B0, 1, 0); SCHED; LDA(At, 1, 0); STA(0, 1, 1, t + 2);
;     WAIT_L(8); BAR; WAIT_L(0); MMA(0, 0, At, B0); BAR; SCHED;
;     LDB(B1, 1, 1); STB(1, 0, 0, t + 3);
;     BAR; WAIT_L(0); MMA(0, 1, At, B1); BAR;
;     LDA(At, 1, 1); STA(1, 0, 0, t + 3);
;     BAR; WAIT_L(0); MMA(1, 0, At, B0); BAR; SCHED;
	v_mfma_f32_16x16x32_bf16 v[28:31], v[206:209], v[174:177], v[28:31]
	v_mfma_f32_16x16x32_bf16 v[24:27], v[214:217], v[174:177], v[24:27]
	v_mfma_f32_16x16x32_bf16 v[20:23], v[206:209], v[182:185], v[20:23]
	v_mfma_f32_16x16x32_bf16 v[16:19], v[214:217], v[182:185], v[16:19]
	v_mfma_f32_16x16x32_bf16 v[12:15], v[206:209], v[190:193], v[12:15]
	v_mfma_f32_16x16x32_bf16 v[8:11], v[214:217], v[190:193], v[8:11]
	v_mfma_f32_16x16x32_bf16 v[4:7], v[206:209], v[198:201], v[4:7]
	v_mfma_f32_16x16x32_bf16 v[0:3], v[214:217], v[198:201], v[0:3]
	v_mfma_f32_16x16x32_bf16 v[28:31], v[210:213], v[178:181], v[28:31]
	v_mfma_f32_16x16x32_bf16 v[24:27], v[218:221], v[178:181], v[24:27]
	v_mfma_f32_16x16x32_bf16 v[20:23], v[210:213], v[186:189], v[20:23]
	v_mfma_f32_16x16x32_bf16 v[16:19], v[218:221], v[186:189], v[16:19]
	v_mfma_f32_16x16x32_bf16 v[12:15], v[210:213], v[194:197], v[12:15]
	v_mfma_f32_16x16x32_bf16 v[8:11], v[218:221], v[194:197], v[8:11]
	v_mfma_f32_16x16x32_bf16 v[4:7], v[210:213], v[202:205], v[4:7]
	v_mfma_f32_16x16x32_bf16 v[0:3], v[218:221], v[202:205], v[0:3]
	s_barrier
	ds_read_b128 v[136:139], v149
	ds_read_b128 v[162:165], v150
	ds_read_b128 v[166:169], v151
	ds_read_b128 v[170:173], v152
	s_mov_b32 m0, s36
	ds_read_b128 v[174:177], v160 offset:32768
	ds_read_b128 v[178:181], v160 offset:33792
	ds_read_b128 v[182:185], v160 offset:34816
	ds_read_b128 v[186:189], v160 offset:35840
	ds_read_b128 v[190:193], v160 offset:36864
	ds_read_b128 v[194:197], v160 offset:37888
	ds_read_b128 v[198:201], v160 offset:38912
	ds_read_b128 v[202:205], v160 offset:39936
	v_lshl_add_u64 v[206:207], v[132:133], 0, s[40:41]
	global_load_lds_dwordx4 v[206:207], off
	s_mov_b32 m0, s37
	v_lshl_add_u64 v[206:207], v[206:207], 0, s[4:5]
	global_load_lds_dwordx4 v[206:207], off
	s_waitcnt lgkmcnt(8)
	s_barrier
	s_waitcnt lgkmcnt(0)
	v_mfma_f32_16x16x32_bf16 v[124:127], v[136:139], v[174:177], v[124:127]
	v_mfma_f32_16x16x32_bf16 v[120:123], v[166:169], v[174:177], v[120:123]
	v_mfma_f32_16x16x32_bf16 v[116:119], v[136:139], v[182:185], v[116:119]
	v_mfma_f32_16x16x32_bf16 v[112:115], v[166:169], v[182:185], v[112:115]
	v_mfma_f32_16x16x32_bf16 v[108:111], v[136:139], v[190:193], v[108:111]
	v_mfma_f32_16x16x32_bf16 v[104:107], v[166:169], v[190:193], v[104:107]
	v_mfma_f32_16x16x32_bf16 v[100:103], v[136:139], v[198:201], v[100:103]
	v_mfma_f32_16x16x32_bf16 v[96:99], v[166:169], v[198:201], v[96:99]
	v_mfma_f32_16x16x32_bf16 v[124:127], v[162:165], v[178:181], v[124:127]
	v_mfma_f32_16x16x32_bf16 v[120:123], v[170:173], v[178:181], v[120:123]
	v_mfma_f32_16x16x32_bf16 v[116:119], v[162:165], v[186:189], v[116:119]
	v_mfma_f32_16x16x32_bf16 v[112:115], v[170:173], v[186:189], v[112:115]
	v_mfma_f32_16x16x32_bf16 v[108:111], v[162:165], v[194:197], v[108:111]
	v_mfma_f32_16x16x32_bf16 v[104:107], v[170:173], v[194:197], v[104:107]
	v_mfma_f32_16x16x32_bf16 v[100:103], v[162:165], v[202:205], v[100:103]
	v_mfma_f32_16x16x32_bf16 v[96:99], v[170:173], v[202:205], v[96:99]
	s_barrier
	s_add_u32 s40, s18, 0xffc00000
	s_addc_u32 s41, s19, -1
	s_mov_b64 s[42:43], s[40:41]
	s_mov_b32 m0, s17
	ds_read_b128 v[206:209], v153
	ds_read_b128 v[210:213], v154
	ds_read_b128 v[214:217], v155
	ds_read_b128 v[218:221], v156
	v_lshl_add_u64 v[222:223], v[134:135], 0, s[42:43]
	global_load_lds_dwordx4 v[222:223], off
	s_mov_b32 m0, s21
	v_lshl_add_u64 v[222:223], v[222:223], 0, s[4:5]
	global_load_lds_dwordx4 v[222:223], off
	s_barrier
	s_waitcnt lgkmcnt(0)
	v_mfma_f32_16x16x32_bf16 v[92:95], v[206:209], v[174:177], v[92:95]
	v_mfma_f32_16x16x32_bf16 v[88:91], v[214:217], v[174:177], v[88:91]
	v_mfma_f32_16x16x32_bf16 v[84:87], v[206:209], v[182:185], v[84:87]
	v_mfma_f32_16x16x32_bf16 v[80:83], v[214:217], v[182:185], v[80:83]
	v_mfma_f32_16x16x32_bf16 v[76:79], v[206:209], v[190:193], v[76:79]
	v_mfma_f32_16x16x32_bf16 v[72:75], v[214:217], v[190:193], v[72:75]
	v_mfma_f32_16x16x32_bf16 v[68:71], v[206:209], v[198:201], v[68:71]
	v_mfma_f32_16x16x32_bf16 v[64:67], v[214:217], v[198:201], v[64:67]
	v_mfma_f32_16x16x32_bf16 v[92:95], v[210:213], v[178:181], v[92:95]
	v_mfma_f32_16x16x32_bf16 v[88:91], v[218:221], v[178:181], v[88:91]
	v_mfma_f32_16x16x32_bf16 v[84:87], v[210:213], v[186:189], v[84:87]
	v_mfma_f32_16x16x32_bf16 v[80:83], v[218:221], v[186:189], v[80:83]
	v_mfma_f32_16x16x32_bf16 v[76:79], v[210:213], v[194:197], v[76:79]
	v_mfma_f32_16x16x32_bf16 v[72:75], v[218:221], v[194:197], v[72:75]
	v_mfma_f32_16x16x32_bf16 v[68:71], v[210:213], v[202:205], v[68:71]
	v_mfma_f32_16x16x32_bf16 v[64:67], v[218:221], v[202:205], v[64:67]
	s_mov_b32 m0, s22
	s_barrier
	ds_read_b128 v[174:177], v160 offset:49152
	ds_read_b128 v[178:181], v160 offset:50176
	ds_read_b128 v[182:185], v160 offset:51200
	ds_read_b128 v[186:189], v160 offset:52224
	ds_read_b128 v[190:193], v160 offset:53248
	ds_read_b128 v[194:197], v160 offset:54272
	ds_read_b128 v[198:201], v160 offset:55296
	ds_read_b128 v[202:205], v160 offset:56320
	v_lshl_add_u64 v[222:223], v[132:133], 0, s[40:41]
	global_load_lds_dwordx4 v[222:223], off
	s_mov_b32 m0, s23
	v_lshl_add_u64 v[222:223], v[222:223], 0, s[4:5]
	global_load_lds_dwordx4 v[222:223], off
	s_barrier
; #define STA(b, h, half, kt) STAGE(((b) * 2 + (h)) * G_HT * 2, pA, ((size_t)(half) * G_HALF * lda + (size_t)(kt) * G_BK) * 2, lda)
; #define STB(b, h, half, kt) STAGE((4 + (b) * 2 + (h)) * G_HT * 2, pB, ((size_t)(half) * G_HALF * K + (size_t)(kt) * G_BK) * 2, K)
; #define LDA(dst, b, h) for (int m = 0; m < 4; ++m) for (int k = 0; k < 2; ++k) \
;     dst[m][k] = *reinterpret_cast<const bf16x8*>(aRd + (((b) * 2 + (h)) * G_HT * 2 + m * 2048 + k * 1024))
; #define LDB(dst, b, h) for (int n = 0; n < 2; ++n) for (int k = 0; k < 2; ++k) \
;     dst[n][k] = *reinterpret_cast<const bf16x8*>(bRd + (((b) * 2 + (h)) * G_HT * 2 + n * 2048 + k * 1024))
; #define MMA(ai, bj, At, Bx) do { __builtin_amdgcn_s_setprio(1); \
;     for (int m = 0; m < 4; ++m) for (int n = 0; n < 2; ++n) for (int k = 0; k < 2; ++k) \
;       acc[ai][bj][m][n] = __builtin_amdgcn_mfma_f32_16x16x32_bf16(Bx[n][k], At[m][k], acc[ai][bj][m][n], 0, 0, 0);     \
;     __builtin_amdgcn_s_setprio(0); } while (0)
; #define WAIT_V(n) asm volatile("s_waitcnt vmcnt(" #n ")" ::: "memory")
; #define WAIT_L(n) asm volatile("s_waitcnt lgkmcnt(" #n ")" ::: "memory")
; #define BAR __builtin_amdgcn_s_barrier()
; #define SCHED __builtin_amdgcn_sched_barrier(0)
; template <int EPI>
; __device__ __forceinline__ void gemm_tile(const bf16* __restrict__ A, int lda, const bf16* __restrict__ Bt, int K,
;                                           int brow, int bcol, const EpiArgs& ea, char* shmc, bool has_next, int nbrow, int nbcol, bool first_tile) {
;     ...
;     STB(0, 1, 1, t + 2);
;     WAIT_V(6); BAR; MMA(1, 1, At, B1); BAR;
;     LDB(B0, 1, 0); SCHED; LDA(At, 1, 0); STA(0, 1, 1, t + 2);
;     WAIT_L(8); BAR; WAIT_L(0); MMA(0, 0, At, B0); BAR; SCHED;
;     LDB(B1, 1, 1); STB(1, 0, 0, t + 3);
;     BAR; WAIT_L(0); MMA(0, 1, At, B1); BAR;
;     LDA(At, 1, 1); STA(1, 0, 0, t + 3);
;     BAR; WAIT_L(0); MMA(1, 0, At, B0); BAR; SCHED;
;     STB(1, 1, 1, t + 3);
;     WAIT_V(6); BAR; MMA(1, 1, At, B1); BAR;
;   }
;   { LDB(B0, 0, 0); LDA(At, 0, 0); STA(1, 1, 1, nt - 1);
;     BAR; WAIT_L(0); MMA(0, 0, At, B0); BAR;
;     LDB(B1, 0, 1); BAR; WAIT_L(0); MMA(0, 1, At, B1); BAR;
;     LDA(At, 0, 1); WAIT_V(4); BAR; WAIT_L(0); MMA(1, 0, At, B0); MMA(1, 1, At, B1); BAR; }
	s_waitcnt lgkmcnt(0)
	v_mfma_f32_16x16x32_bf16 v[60:63], v[136:139], v[174:177], v[60:63]
	v_mfma_f32_16x16x32_bf16 v[56:59], v[166:169], v[174:177], v[56:59]
	v_mfma_f32_16x16x32_bf16 v[52:55], v[136:139], v[182:185], v[52:55]
	v_mfma_f32_16x16x32_bf16 v[48:51], v[166:169], v[182:185], v[48:51]
	v_mfma_f32_16x16x32_bf16 v[44:47], v[136:139], v[190:193], v[44:47]
	v_mfma_f32_16x16x32_bf16 v[40:43], v[166:169], v[190:193], v[40:43]
	v_mfma_f32_16x16x32_bf16 v[36:39], v[136:139], v[198:201], v[36:39]
	v_mfma_f32_16x16x32_bf16 v[32:35], v[166:169], v[198:201], v[32:35]
	v_mfma_f32_16x16x32_bf16 v[60:63], v[162:165], v[178:181], v[60:63]
	v_mfma_f32_16x16x32_bf16 v[56:59], v[170:173], v[178:181], v[56:59]
	v_mfma_f32_16x16x32_bf16 v[52:55], v[162:165], v[186:189], v[52:55]
	v_mfma_f32_16x16x32_bf16 v[48:51], v[170:173], v[186:189], v[48:51]
	v_mfma_f32_16x16x32_bf16 v[44:47], v[162:165], v[194:197], v[44:47]
	v_mfma_f32_16x16x32_bf16 v[40:43], v[170:173], v[194:197], v[40:43]
	v_mfma_f32_16x16x32_bf16 v[36:39], v[162:165], v[202:205], v[36:39]
	v_mfma_f32_16x16x32_bf16 v[32:35], v[170:173], v[202:205], v[32:35]
	s_barrier
	s_mov_b64 s[40:41], s[18:19]
	s_mov_b32 m0, s25
	v_lshl_add_u64 v[136:137], v[134:135], 0, s[40:41]
	global_load_lds_dwordx4 v[136:137], off
	s_mov_b32 m0, s26
	v_lshl_add_u64 v[136:137], v[136:137], 0, s[4:5]
	global_load_lds_dwordx4 v[136:137], off
	s_waitcnt vmcnt(6)
	s_barrier
	v_mfma_f32_16x16x32_bf16 v[28:31], v[206:209], v[174:177], v[28:31]
	v_mfma_f32_16x16x32_bf16 v[24:27], v[214:217], v[174:177], v[24:27]
	v_mfma_f32_16x16x32_bf16 v[20:23], v[206:209], v[182:185], v[20:23]
	v_mfma_f32_16x16x32_bf16 v[16:19], v[214:217], v[182:185], v[16:19]
	v_mfma_f32_16x16x32_bf16 v[12:15], v[206:209], v[190:193], v[12:15]
	v_mfma_f32_16x16x32_bf16 v[8:11], v[214:217], v[190:193], v[8:11]
	v_mfma_f32_16x16x32_bf16 v[4:7], v[206:209], v[198:201], v[4:7]
	v_mfma_f32_16x16x32_bf16 v[0:3], v[214:217], v[198:201], v[0:3]
	v_mfma_f32_16x16x32_bf16 v[28:31], v[210:213], v[178:181], v[28:31]
	v_mfma_f32_16x16x32_bf16 v[24:27], v[218:221], v[178:181], v[24:27]
	v_mfma_f32_16x16x32_bf16 v[20:23], v[210:213], v[186:189], v[20:23]
	v_mfma_f32_16x16x32_bf16 v[16:19], v[218:221], v[186:189], v[16:19]
	v_mfma_f32_16x16x32_bf16 v[12:15], v[210:213], v[194:197], v[12:15]
	v_mfma_f32_16x16x32_bf16 v[8:11], v[218:221], v[194:197], v[8:11]
	v_mfma_f32_16x16x32_bf16 v[4:7], v[210:213], v[202:205], v[4:7]
	v_mfma_f32_16x16x32_bf16 v[0:3], v[218:221], v[202:205], v[0:3]
	s_add_i32 s31, s31, 2
	s_add_u32 s18, s18, 0x100
	s_addc_u32 s19, s19, 0
	s_cmpk_lt_u32 s31, 0xfc
	s_barrier
	s_cbranch_scc1 .LBB0_784
	s_mov_b64 s[18:19], 0x407f80
	s_mov_b32 m0, s34
	ds_read_b128 v[134:137], v141
	ds_read_b128 v[162:165], v142
	ds_read_b128 v[166:169], v143
	ds_read_b128 v[170:173], v144
	ds_read_b128 v[174:177], v160
	ds_read_b128 v[178:181], v160 offset:1024
	ds_read_b128 v[182:185], v160 offset:2048
	ds_read_b128 v[186:189], v160 offset:3072
	ds_read_b128 v[190:193], v160 offset:4096
	ds_read_b128 v[194:197], v160 offset:5120
	ds_read_b128 v[198:201], v160 offset:6144
	ds_read_b128 v[202:205], v160 offset:7168
	s_nop 0
	v_lshl_add_u64 v[132:133], v[132:133], 0, s[18:19]
	global_load_lds_dwordx4 v[132:133], off
	v_lshl_add_u64 v[132:133], v[132:133], 0, s[4:5]
	s_mov_b32 m0, s24
	s_nop 0
	global_load_lds_dwordx4 v[132:133], off
	s_barrier
	s_waitcnt lgkmcnt(0)
	s_waitcnt lgkmcnt(0)
	v_mfma_f32_16x16x32_bf16 v[124:127], v[134:137], v[174:177], v[124:127]
	v_mfma_f32_16x16x32_bf16 v[120:123], v[166:169], v[174:177], v[120:123]
	v_mfma_f32_16x16x32_bf16 v[116:119], v[134:137], v[182:185], v[116:119]
	v_mfma_f32_16x16x32_bf16 v[112:115], v[166:169], v[182:185], v[112:115]
	v_mfma_f32_16x16x32_bf16 v[100:103], v[134:137], v[198:201], v[100:103]
	v_mfma_f32_16x16x32_bf16 v[96:99], v[166:169], v[198:201], v[96:99]
	v_mfma_f32_16x16x32_bf16 v[124:127], v[162:165], v[178:181], v[124:127]
	v_mfma_f32_16x16x32_bf16 v[120:123], v[170:173], v[178:181], v[120:123]
	v_mfma_f32_16x16x32_bf16 v[116:119], v[162:165], v[186:189], v[116:119]
	v_mfma_f32_16x16x32_bf16 v[112:115], v[170:173], v[186:189], v[112:115]
	v_mfma_f32_16x16x32_bf16 v[108:111], v[134:137], v[190:193], v[108:111]
	v_mfma_f32_16x16x32_bf16 v[104:107], v[166:169], v[190:193], v[104:107]
	v_mfma_f32_16x16x32_bf16 v[100:103], v[162:165], v[202:205], v[100:103]
	v_mfma_f32_16x16x32_bf16 v[96:99], v[170:173], v[202:205], v[96:99]
	v_mfma_f32_16x16x32_bf16 v[206:209], v[162:165], v[194:197], v[108:111]
	v_mfma_f32_16x16x32_bf16 v[210:213], v[170:173], v[194:197], v[104:107]
	s_barrier
	s_nop 1
	ds_read_b128 v[104:107], v145
	ds_read_b128 v[108:111], v146
	ds_read_b128 v[214:217], v147
	ds_read_b128 v[218:221], v148
	s_barrier
	s_waitcnt lgkmcnt(0)
	s_waitcnt lgkmcnt(0)
	v_mfma_f32_16x16x32_bf16 v[84:87], v[104:107], v[182:185], v[84:87]
	v_mfma_f32_16x16x32_bf16 v[80:83], v[214:217], v[182:185], v[80:83]
	v_mfma_f32_16x16x32_bf16 v[68:71], v[104:107], v[198:201], v[68:71]
	v_mfma_f32_16x16x32_bf16 v[64:67], v[214:217], v[198:201], v[64:67]
	v_mfma_f32_16x16x32_bf16 v[92:95], v[104:107], v[174:177], v[92:95]
	v_mfma_f32_16x16x32_bf16 v[88:91], v[214:217], v[174:177], v[88:91]
	v_mfma_f32_16x16x32_bf16 v[84:87], v[108:111], v[186:189], v[84:87]
	v_mfma_f32_16x16x32_bf16 v[80:83], v[218:221], v[186:189], v[80:83]
	v_mfma_f32_16x16x32_bf16 v[76:79], v[104:107], v[190:193], v[76:79]
	v_mfma_f32_16x16x32_bf16 v[72:75], v[214:217], v[190:193], v[72:75]
	v_mfma_f32_16x16x32_bf16 v[68:71], v[108:111], v[202:205], v[68:71]
	v_mfma_f32_16x16x32_bf16 v[64:67], v[218:221], v[202:205], v[64:67]
	v_mfma_f32_16x16x32_bf16 v[222:225], v[108:111], v[178:181], v[92:95]
	v_mfma_f32_16x16x32_bf16 v[174:177], v[218:221], v[178:181], v[88:91]
	v_mfma_f32_16x16x32_bf16 v[178:181], v[108:111], v[194:197], v[76:79]
	v_mfma_f32_16x16x32_bf16 v[182:185], v[218:221], v[194:197], v[72:75]
	s_barrier
; #define LDA(dst, b, h) for (int m = 0; m < 4; ++m) for (int k = 0; k < 2; ++k) \
;     dst[m][k] = *reinterpret_cast<const bf16x8*>(aRd + (((b) * 2 + (h)) * G_HT * 2 + m * 2048 + k * 1024))
; #define LDB(dst, b, h) for (int n = 0; n < 2; ++n) for (int k = 0; k < 2; ++k) \
;     dst[n][k] = *reinterpret_cast<const bf16x8*>(bRd + (((b) * 2 + (h)) * G_HT * 2 + n * 2048 + k * 1024))
; #define MMA(ai, bj, At, Bx) do { __builtin_amdgcn_s_setprio(1); \
;     for (int m = 0; m < 4; ++m) for (int n = 0; n < 2; ++n) for (int k = 0; k < 2; ++k) \
;       acc[ai][bj][m][n] = __builtin_amdgcn_mfma_f32_16x16x32_bf16(Bx[n][k], At[m][k], acc[ai][bj][m][n], 0, 0, 0);     \
;     __builtin_amdgcn_s_setprio(0); } while (0)
; #define WAIT_V(n) asm volatile("s_waitcnt vmcnt(" #n ")" ::: "memory")
; #define WAIT_L(n) asm volatile("s_waitcnt lgkmcnt(" #n ")" ::: "memory")
; #define BAR __builtin_amdgcn_s_barrier()
; template <int EPI>
; __device__ __forceinline__ void gemm_tile(const bf16* __restrict__ A, int lda, const bf16* __restrict__ Bt, int K,
;                                           int brow, int bcol, const EpiArgs& ea, char* shmc, bool has_next, int nbrow, int nbcol, bool first_tile) {
;     ...
;     LDA(At, 0, 1); WAIT_V(4); BAR; WAIT_L(0); MMA(1, 0, At, B0); MMA(1, 1, At, B1); BAR; }
;   { LDB(B0, 1, 0); LDA(At, 1, 0); WAIT_V(2); BAR; WAIT_L(0); MMA(0, 0, At, B0); BAR;
;     LDB(B1, 1, 1); WAIT_V(0); BAR; WAIT_L(0); MMA(0, 1, At, B1); BAR;
	s_nop 0
	ds_read_b128 v[72:75], v160 offset:16384
	ds_read_b128 v[76:79], v160 offset:17408
	ds_read_b128 v[88:91], v160 offset:18432
	ds_read_b128 v[92:95], v160 offset:19456
	ds_read_b128 v[186:189], v160 offset:20480
	ds_read_b128 v[190:193], v160 offset:21504
	ds_read_b128 v[194:197], v160 offset:22528
	ds_read_b128 v[198:201], v160 offset:23552
	s_waitcnt vmcnt(4)
	s_barrier
	s_waitcnt lgkmcnt(0)
	s_waitcnt lgkmcnt(0)
	v_mfma_f32_16x16x32_bf16 v[60:63], v[134:137], v[72:75], v[60:63]
	v_mfma_f32_16x16x32_bf16 v[56:59], v[166:169], v[72:75], v[56:59]
	v_mfma_f32_16x16x32_bf16 v[52:55], v[134:137], v[88:91], v[52:55]
	v_mfma_f32_16x16x32_bf16 v[48:51], v[166:169], v[88:91], v[48:51]
	v_mfma_f32_16x16x32_bf16 v[36:39], v[134:137], v[194:197], v[36:39]
	v_mfma_f32_16x16x32_bf16 v[32:35], v[166:169], v[194:197], v[32:35]
	v_mfma_f32_16x16x32_bf16 v[60:63], v[162:165], v[76:79], v[60:63]
	v_mfma_f32_16x16x32_bf16 v[56:59], v[170:173], v[76:79], v[56:59]
	v_mfma_f32_16x16x32_bf16 v[52:55], v[162:165], v[92:95], v[52:55]
	v_mfma_f32_16x16x32_bf16 v[48:51], v[170:173], v[92:95], v[48:51]
	v_mfma_f32_16x16x32_bf16 v[44:47], v[134:137], v[186:189], v[44:47]
	v_mfma_f32_16x16x32_bf16 v[40:43], v[166:169], v[186:189], v[40:43]
	v_mfma_f32_16x16x32_bf16 v[36:39], v[162:165], v[198:201], v[36:39]
	v_mfma_f32_16x16x32_bf16 v[32:35], v[170:173], v[198:201], v[32:35]
	v_mfma_f32_16x16x32_bf16 v[202:205], v[162:165], v[190:193], v[44:47]
	v_mfma_f32_16x16x32_bf16 v[226:229], v[170:173], v[190:193], v[40:43]
	v_mfma_f32_16x16x32_bf16 v[20:23], v[104:107], v[88:91], v[20:23]
	v_mfma_f32_16x16x32_bf16 v[16:19], v[214:217], v[88:91], v[16:19]
	v_mfma_f32_16x16x32_bf16 v[4:7], v[104:107], v[194:197], v[4:7]
	v_mfma_f32_16x16x32_bf16 v[0:3], v[214:217], v[194:197], v[0:3]
	v_mfma_f32_16x16x32_bf16 v[28:31], v[104:107], v[72:75], v[28:31]
	v_mfma_f32_16x16x32_bf16 v[24:27], v[214:217], v[72:75], v[24:27]
	v_mfma_f32_16x16x32_bf16 v[20:23], v[108:111], v[92:95], v[20:23]
	v_mfma_f32_16x16x32_bf16 v[16:19], v[218:221], v[92:95], v[16:19]
	v_mfma_f32_16x16x32_bf16 v[12:15], v[104:107], v[186:189], v[12:15]
	v_mfma_f32_16x16x32_bf16 v[8:11], v[214:217], v[186:189], v[8:11]
	v_mfma_f32_16x16x32_bf16 v[4:7], v[108:111], v[198:201], v[4:7]
	v_mfma_f32_16x16x32_bf16 v[0:3], v[218:221], v[198:201], v[0:3]
	v_mfma_f32_16x16x32_bf16 v[132:135], v[108:111], v[76:79], v[28:31]
	v_mfma_f32_16x16x32_bf16 v[136:139], v[218:221], v[76:79], v[24:27]
	v_mfma_f32_16x16x32_bf16 v[162:165], v[108:111], v[190:193], v[12:15]
	v_mfma_f32_16x16x32_bf16 v[166:169], v[218:221], v[190:193], v[8:11]
	s_barrier
	s_nop 0
	ds_read_b128 v[8:11], v149
	ds_read_b128 v[12:15], v150
	ds_read_b128 v[170:173], v151
	ds_read_b128 v[186:189], v152
	ds_read_b128 v[24:27], v160 offset:32768
	ds_read_b128 v[28:31], v160 offset:33792
	ds_read_b128 v[40:43], v160 offset:34816
	ds_read_b128 v[44:47], v160 offset:35840
	ds_read_b128 v[190:193], v160 offset:36864
	ds_read_b128 v[194:197], v160 offset:37888
	ds_read_b128 v[198:201], v160 offset:38912
	ds_read_b128 v[214:217], v160 offset:39936
	s_waitcnt vmcnt(2)
	s_barrier
	s_waitcnt lgkmcnt(0)
	s_waitcnt lgkmcnt(0)
	v_mfma_f32_16x16x32_bf16 v[72:75], v[8:11], v[24:27], v[124:127]
	v_mfma_f32_16x16x32_bf16 v[124:127], v[12:15], v[28:31], v[72:75]
	v_mfma_f32_16x16x32_bf16 v[72:75], v[170:173], v[24:27], v[120:123]
	v_mfma_f32_16x16x32_bf16 v[120:123], v[186:189], v[28:31], v[72:75]
	v_mfma_f32_16x16x32_bf16 v[72:75], v[8:11], v[40:43], v[116:119]
	v_mfma_f32_16x16x32_bf16 v[108:111], v[12:15], v[44:47], v[72:75]
	v_mfma_f32_16x16x32_bf16 v[72:75], v[170:173], v[40:43], v[112:115]
	v_mfma_f32_16x16x32_bf16 v[104:107], v[186:189], v[44:47], v[72:75]
	v_mfma_f32_16x16x32_bf16 v[72:75], v[8:11], v[190:193], v[206:209]
	v_mfma_f32_16x16x32_bf16 v[92:95], v[12:15], v[194:197], v[72:75]
	v_mfma_f32_16x16x32_bf16 v[72:75], v[170:173], v[190:193], v[210:213]
	v_mfma_f32_16x16x32_bf16 v[88:91], v[186:189], v[194:197], v[72:75]
	v_mfma_f32_16x16x32_bf16 v[72:75], v[8:11], v[198:201], v[100:103]
	v_mfma_f32_16x16x32_bf16 v[76:79], v[12:15], v[214:217], v[72:75]
	v_mfma_f32_16x16x32_bf16 v[72:75], v[170:173], v[198:201], v[96:99]
	v_mfma_f32_16x16x32_bf16 v[72:75], v[186:189], v[214:217], v[72:75]
	s_barrier
; #define LDA(dst, b, h) for (int m = 0; m < 4; ++m) for (int k = 0; k < 2; ++k) \
;     dst[m][k] = *reinterpret_cast<const bf16x8*>(aRd + (((b) * 2 + (h)) * G_HT * 2 + m * 2048 + k * 1024))
; #define LDB(dst, b, h) for (int n = 0; n < 2; ++n) for (int k = 0; k < 2; ++k) \
;     dst[n][k] = *reinterpret_cast<const bf16x8*>(bRd + (((b) * 2 + (h)) * G_HT * 2 + n * 2048 + k * 1024))
; #define MMA(ai, bj, At, Bx) do { __builtin_amdgcn_s_setprio(1); \
;     for (int m = 0; m < 4; ++m) for (int n = 0; n < 2; ++n) for (int k = 0; k < 2; ++k) \
;       acc[ai][bj][m][n] = __builtin_amdgcn_mfma_f32_16x16x32_bf16(Bx[n][k], At[m][k], acc[ai][bj][m][n], 0, 0, 0);     \
;     __builtin_amdgcn_s_setprio(0); } while (0)
; #define WAIT_V(n) asm volatile("s_waitcnt vmcnt(" #n ")" ::: "memory")
; #define WAIT_L(n) asm volatile("s_waitcnt lgkmcnt(" #n ")" ::: "memory")
; #define BAR __builtin_amdgcn_s_barrier()
; template <int EPI>
; __device__ __forceinline__ void gemm_tile(const bf16* __restrict__ A, int lda, const bf16* __restrict__ Bt, int K,
;                                           int brow, int bcol, const EpiArgs& ea, char* shmc, bool has_next, int nbrow, int nbcol, bool first_tile) {
;     ...
;     LDB(B1, 1, 1); WAIT_V(0); BAR; WAIT_L(0); MMA(0, 1, At, B1); BAR;
;     LDA(At, 1, 1); BAR; WAIT_L(0); MMA(1, 0, At, B0); MMA(1, 1, At, B1); BAR; }
;   if (wr == 0) BAR;
	ds_read_b128 v[206:209], v153
	ds_read_b128 v[210:213], v154
	ds_read_b128 v[218:221], v155
	ds_read_b128 v[230:233], v156
	s_waitcnt vmcnt(0)
	s_barrier
	s_waitcnt lgkmcnt(0)
	s_waitcnt lgkmcnt(0)
	v_mfma_f32_16x16x32_bf16 v[96:99], v[206:209], v[24:27], v[222:225]
	v_mfma_f32_16x16x32_bf16 v[24:27], v[218:221], v[24:27], v[174:177]
	v_mfma_f32_16x16x32_bf16 v[112:115], v[230:233], v[28:31], v[24:27]
	v_mfma_f32_16x16x32_bf16 v[24:27], v[206:209], v[40:43], v[84:87]
	v_mfma_f32_16x16x32_bf16 v[100:103], v[210:213], v[44:47], v[24:27]
	v_mfma_f32_16x16x32_bf16 v[24:27], v[218:221], v[40:43], v[80:83]
	v_mfma_f32_16x16x32_bf16 v[116:119], v[210:213], v[28:31], v[96:99]
	v_mfma_f32_16x16x32_bf16 v[96:99], v[230:233], v[44:47], v[24:27]
	v_mfma_f32_16x16x32_bf16 v[24:27], v[206:209], v[190:193], v[178:181]
	v_mfma_f32_16x16x32_bf16 v[84:87], v[210:213], v[194:197], v[24:27]
	v_mfma_f32_16x16x32_bf16 v[24:27], v[218:221], v[190:193], v[182:185]
	v_mfma_f32_16x16x32_bf16 v[80:83], v[230:233], v[194:197], v[24:27]
	v_mfma_f32_16x16x32_bf16 v[24:27], v[206:209], v[198:201], v[68:71]
	v_mfma_f32_16x16x32_bf16 v[68:71], v[210:213], v[214:217], v[24:27]
	v_mfma_f32_16x16x32_bf16 v[24:27], v[218:221], v[198:201], v[64:67]
	v_mfma_f32_16x16x32_bf16 v[64:67], v[230:233], v[214:217], v[24:27]
	s_barrier
	ds_read_b128 v[174:177], v160 offset:49152
	ds_read_b128 v[178:181], v160 offset:50176
	ds_read_b128 v[182:185], v160 offset:51200
	ds_read_b128 v[190:193], v160 offset:52224
	ds_read_b128 v[194:197], v160 offset:53248
	ds_read_b128 v[198:201], v160 offset:54272
	ds_read_b128 v[214:217], v160 offset:55296
	ds_read_b128 v[222:225], v160 offset:56320
	s_barrier
	s_waitcnt lgkmcnt(0)
	s_waitcnt lgkmcnt(0)
	v_mfma_f32_16x16x32_bf16 v[24:27], v[8:11], v[174:177], v[60:63]
	v_mfma_f32_16x16x32_bf16 v[60:63], v[12:15], v[178:181], v[24:27]
	v_mfma_f32_16x16x32_bf16 v[24:27], v[170:173], v[174:177], v[56:59]
	v_mfma_f32_16x16x32_bf16 v[56:59], v[186:189], v[178:181], v[24:27]
	v_mfma_f32_16x16x32_bf16 v[24:27], v[8:11], v[182:185], v[52:55]
	v_mfma_f32_16x16x32_bf16 v[44:47], v[12:15], v[190:193], v[24:27]
	v_mfma_f32_16x16x32_bf16 v[24:27], v[170:173], v[182:185], v[48:51]
	v_mfma_f32_16x16x32_bf16 v[40:43], v[186:189], v[190:193], v[24:27]
	v_mfma_f32_16x16x32_bf16 v[24:27], v[8:11], v[194:197], v[202:205]
	v_mfma_f32_16x16x32_bf16 v[8:11], v[8:11], v[214:217], v[36:39]
	v_mfma_f32_16x16x32_bf16 v[28:31], v[12:15], v[198:201], v[24:27]
	v_mfma_f32_16x16x32_bf16 v[24:27], v[170:173], v[194:197], v[226:229]
	v_mfma_f32_16x16x32_bf16 v[12:15], v[12:15], v[222:225], v[8:11]
	v_mfma_f32_16x16x32_bf16 v[8:11], v[170:173], v[214:217], v[32:35]
	v_mfma_f32_16x16x32_bf16 v[24:27], v[186:189], v[198:201], v[24:27]
	v_mfma_f32_16x16x32_bf16 v[8:11], v[186:189], v[222:225], v[8:11]
	v_mfma_f32_16x16x32_bf16 v[32:35], v[206:209], v[174:177], v[132:135]
	v_mfma_f32_16x16x32_bf16 v[52:55], v[210:213], v[178:181], v[32:35]
	v_mfma_f32_16x16x32_bf16 v[32:35], v[218:221], v[174:177], v[136:139]
	v_mfma_f32_16x16x32_bf16 v[16:19], v[218:221], v[182:185], v[16:19]
	v_mfma_f32_16x16x32_bf16 v[48:51], v[230:233], v[178:181], v[32:35]
	v_mfma_f32_16x16x32_bf16 v[20:23], v[206:209], v[182:185], v[20:23]
	v_mfma_f32_16x16x32_bf16 v[32:35], v[230:233], v[190:193], v[16:19]
	v_mfma_f32_16x16x32_bf16 v[16:19], v[206:209], v[194:197], v[162:165]
	v_mfma_f32_16x16x32_bf16 v[36:39], v[210:213], v[190:193], v[20:23]
	v_mfma_f32_16x16x32_bf16 v[20:23], v[210:213], v[198:201], v[16:19]
	v_mfma_f32_16x16x32_bf16 v[16:19], v[218:221], v[194:197], v[166:169]
	v_mfma_f32_16x16x32_bf16 v[4:7], v[206:209], v[214:217], v[4:7]
	v_mfma_f32_16x16x32_bf16 v[0:3], v[218:221], v[214:217], v[0:3]
	v_mfma_f32_16x16x32_bf16 v[16:19], v[230:233], v[198:201], v[16:19]
	v_mfma_f32_16x16x32_bf16 v[4:7], v[210:213], v[222:225], v[4:7]
	v_mfma_f32_16x16x32_bf16 v[0:3], v[230:233], v[222:225], v[0:3]
	s_barrier
	s_and_saveexec_b64 s[18:19], s[2:3]
	s_cbranch_execz .LBB0_787
	s_barrier
